# GEMM loops: mid-phase s_setprio 0/1 toggle pairs removed (priority held across all 32 MFMAs of a phase)
# baseline (speedup 1.0000x reference)
; #define PG8_STAGE(bufoff, gbase, voff) do { _Pragma("unroll") for (int _i = 0; _i < 2; ++_i) \
;         __builtin_amdgcn_global_load_lds((const unsigned*)((const char*)(gbase) + (voff)[_i]), (LAS unsigned*)(lds + (bufoff) + ldsw + _i * 8192), 16, 0, 0); } while (0)
; #define PG8_LDA(dst, b, h) do { _Pragma("unroll") for (int m = 0; m < 4; ++m) _Pragma("unroll") for (int k = 0; k < 2; ++k) dst[m][k] = *(const LAS half8*)(lds + PG8_SA(b, h) + aoff + m * 2048 + k * 1024); } while (0)
; #define PG8_LDB(dst, b, h) do { _Pragma("unroll") for (int n = 0; n < 2; ++n) _Pragma("unroll") for (int k = 0; k < 2; ++k) dst[n][k] = *(const LAS half8*)(lds + PG8_SB(b, h) + boff + n * 2048 + k * 1024); } while (0)
; #define PG8_MMA(ai, bj, At, Bt) do { __builtin_amdgcn_s_setprio(1); _Pragma("unroll") for (int m = 0; m < 4; ++m) _Pragma("unroll") for (int n = 0; n < 2; ++n) _Pragma("unroll") for (int k = 0; k < 2; ++k) \
;         acc[ai][bj][m][n] = __builtin_amdgcn_mfma_f32_16x16x32_f16(Bt[n][k], At[m][k], acc[ai][bj][m][n], 0, 0, 0); __builtin_amdgcn_s_setprio(0); } while (0)
; #define PG8_WAIT_V(n) asm volatile("s_waitcnt vmcnt(" #n ")" ::: "memory")
; #define PG8_WAIT_L(n) asm volatile("s_waitcnt lgkmcnt(" #n ")" ::: "memory")
; #define PG8_BAR __builtin_amdgcn_s_barrier()
; #define PG8_SCHED __builtin_amdgcn_sched_barrier(0)
; template <class Epi>
; __device__ __forceinline__ void gemm_phase(LAS unsigned char* lds, const Gemm g, const StaticOrder& S, const Epi& E) {
;     ...
;         for (int t = 0; t < nt; t += 2) {
;             const bool last = (t == nt - 2);
;             const char* a1 = cA + (size_t)(t + 1) * kstep;
;             const char* a2 = last ? nA : cA + (size_t)(t + 2) * kstep; const char* b2 = last ? nB : cB + (size_t)(t + 2) * kstep;
;             const char* a3 = a2 + kstep; const char* b3 = b2 + kstep;
;             PG8_LDB(B0, 0, 0); PG8_LDB(B1, 0, 1); PG8_SCHED; PG8_LDA(At, 0, 0); PG8_STAGE(PG8_SA(1, 1), a1 + hA, voffA);
;             PG8_WAIT_V(8); PG8_WAIT_L(0); PG8_BAR; PG8_MMA(0, 0, At, B0); PG8_MMA(0, 1, At, B1); PG8_BAR; PG8_SCHED;
;             PG8_LDA(At, 0, 1); PG8_STAGE(PG8_SB(0, 0), b2, voffB); PG8_STAGE(PG8_SB(0, 1), b2 + hB, voffB); PG8_STAGE(PG8_SA(0, 0), a2, voffA);
;             PG8_WAIT_V(8); PG8_WAIT_L(0); PG8_BAR; PG8_MMA(1, 0, At, B0); PG8_MMA(1, 1, At, B1); PG8_BAR; PG8_SCHED;
.LBB0_83:
	s_add_i32 s15, s14, 2
	s_add_u32 s10, s0, 0x100
	s_addc_u32 s11, s1, 0
	s_add_i32 s17, 0, 0x10000
	s_cmp_eq_u32 s88, s14
	s_cselect_b32 s53, s43, s11
	s_cselect_b32 s52, s42, s10
	s_cselect_b32 s25, s19, s3
	s_cselect_b32 s24, s18, s2
	s_add_i32 s14, 0, 0x14000
	v_add_u32_e32 v152, s17, v161
	v_add_u32_e32 v170, s14, v161
	ds_read_b128 v[140:143], v152
	ds_read_b128 v[144:147], v152 offset:1024
	ds_read_b128 v[148:151], v152 offset:2048
	ds_read_b128 v[152:155], v152 offset:3072
	ds_read_b128 v[156:159], v170
	ds_read_b128 v[162:165], v170 offset:1024
	ds_read_b128 v[166:169], v170 offset:2048
	ds_read_b128 v[170:173], v170 offset:3072
	v_lshl_add_u64 v[206:207], s[0:1], 0, v[138:139]
	s_add_i32 m0, s57, 0xc000
	ds_read_b128 v[174:177], v228
	ds_read_b128 v[178:181], v228 offset:1024
	ds_read_b128 v[182:185], v228 offset:2048
	ds_read_b128 v[186:189], v228 offset:3072
	ds_read_b128 v[190:193], v228 offset:4096
	ds_read_b128 v[194:197], v228 offset:5120
	ds_read_b128 v[198:201], v228 offset:6144
	ds_read_b128 v[202:205], v228 offset:7168
	global_load_lds_dwordx4 v[206:207], off
	v_lshl_add_u64 v[206:207], s[0:1], 0, v[136:137]
	s_add_i32 m0, s57, 0xe000
	s_nop 0
	global_load_lds_dwordx4 v[206:207], off
	s_waitcnt vmcnt(8)
	s_waitcnt lgkmcnt(0)
	s_barrier
	s_setprio 1
	s_waitcnt lgkmcnt(0)
	v_mfma_f32_16x16x32_f16 v[122:125], v[140:143], v[174:177], v[122:125]
	v_mfma_f32_16x16x32_f16 v[118:121], v[148:151], v[174:177], v[118:121]
	v_mfma_f32_16x16x32_f16 v[106:109], v[140:143], v[182:185], v[106:109]
	v_mfma_f32_16x16x32_f16 v[102:105], v[148:151], v[182:185], v[102:105]
	v_mfma_f32_16x16x32_f16 v[90:93], v[140:143], v[190:193], v[90:93]
	v_mfma_f32_16x16x32_f16 v[86:89], v[148:151], v[190:193], v[86:89]
	v_mfma_f32_16x16x32_f16 v[74:77], v[140:143], v[198:201], v[74:77]
	v_mfma_f32_16x16x32_f16 v[70:73], v[148:151], v[198:201], v[70:73]
	v_mfma_f32_16x16x32_f16 v[122:125], v[144:147], v[178:181], v[122:125]
	v_mfma_f32_16x16x32_f16 v[118:121], v[152:155], v[178:181], v[118:121]
	v_mfma_f32_16x16x32_f16 v[106:109], v[144:147], v[186:189], v[106:109]
	v_mfma_f32_16x16x32_f16 v[102:105], v[152:155], v[186:189], v[102:105]
	v_mfma_f32_16x16x32_f16 v[90:93], v[144:147], v[194:197], v[90:93]
	v_mfma_f32_16x16x32_f16 v[86:89], v[152:155], v[194:197], v[86:89]
	v_mfma_f32_16x16x32_f16 v[74:77], v[144:147], v[202:205], v[74:77]
	v_mfma_f32_16x16x32_f16 v[70:73], v[152:155], v[202:205], v[70:73]
	v_mfma_f32_16x16x32_f16 v[114:117], v[156:159], v[174:177], v[114:117]
	v_mfma_f32_16x16x32_f16 v[126:129], v[166:169], v[174:177], v[126:129]
	v_mfma_f32_16x16x32_f16 v[98:101], v[156:159], v[182:185], v[98:101]
	v_mfma_f32_16x16x32_f16 v[110:113], v[166:169], v[182:185], v[110:113]
	v_mfma_f32_16x16x32_f16 v[82:85], v[156:159], v[190:193], v[82:85]
	v_mfma_f32_16x16x32_f16 v[94:97], v[166:169], v[190:193], v[94:97]
	v_mfma_f32_16x16x32_f16 v[66:69], v[156:159], v[198:201], v[66:69]
	v_mfma_f32_16x16x32_f16 v[78:81], v[166:169], v[198:201], v[78:81]
	v_mfma_f32_16x16x32_f16 v[114:117], v[162:165], v[178:181], v[114:117]
	v_mfma_f32_16x16x32_f16 v[126:129], v[170:173], v[178:181], v[126:129]
	v_mfma_f32_16x16x32_f16 v[98:101], v[162:165], v[186:189], v[98:101]
	v_mfma_f32_16x16x32_f16 v[110:113], v[170:173], v[186:189], v[110:113]
	v_mfma_f32_16x16x32_f16 v[82:85], v[162:165], v[194:197], v[82:85]
	v_mfma_f32_16x16x32_f16 v[94:97], v[170:173], v[194:197], v[94:97]
	v_mfma_f32_16x16x32_f16 v[66:69], v[162:165], v[202:205], v[66:69]
	v_mfma_f32_16x16x32_f16 v[78:81], v[170:173], v[202:205], v[78:81]
	s_setprio 0
	s_barrier
	s_add_i32 s0, s17, s56
	v_lshl_add_u64 v[206:207], s[24:25], 0, v[0:1]
	s_mov_b32 m0, s0
	ds_read_b128 v[174:177], v228 offset:16384
	ds_read_b128 v[178:181], v228 offset:17408
	ds_read_b128 v[182:185], v228 offset:18432
	ds_read_b128 v[186:189], v228 offset:19456
	ds_read_b128 v[190:193], v228 offset:20480
	ds_read_b128 v[194:197], v228 offset:21504
	ds_read_b128 v[198:201], v228 offset:22528
	ds_read_b128 v[202:205], v228 offset:23552
	global_load_lds_dwordx4 v[206:207], off
	s_add_i32 m0, s0, 0x2000
	s_add_u32 s0, s24, 0xb0000
	v_lshl_add_u64 v[208:209], s[24:25], 0, v[134:135]
	s_addc_u32 s1, s25, 0
	s_add_i32 s14, s14, s56
	global_load_lds_dwordx4 v[208:209], off
	v_lshl_add_u64 v[210:211], s[0:1], 0, v[0:1]
	s_mov_b32 m0, s14
	v_lshl_add_u64 v[212:213], s[52:53], 0, v[132:133]
	global_load_lds_dwordx4 v[210:211], off
	v_lshl_add_u64 v[210:211], s[0:1], 0, v[134:135]
	s_add_i32 m0, s14, 0x2000
	s_nop 0
	global_load_lds_dwordx4 v[210:211], off
	v_lshl_add_u64 v[210:211], s[52:53], 0, v[130:131]
	s_mov_b32 m0, s57
	s_nop 0
	global_load_lds_dwordx4 v[210:211], off
	s_mov_b32 m0, s58
	s_nop 0
	global_load_lds_dwordx4 v[212:213], off
	s_waitcnt vmcnt(8)
	s_waitcnt lgkmcnt(0)
	s_barrier
; #define PG8_STAGE(bufoff, gbase, voff) do { _Pragma("unroll") for (int _i = 0; _i < 2; ++_i) \
;         __builtin_amdgcn_global_load_lds((const unsigned*)((const char*)(gbase) + (voff)[_i]), (LAS unsigned*)(lds + (bufoff) + ldsw + _i * 8192), 16, 0, 0); } while (0)
; #define PG8_LDA(dst, b, h) do { _Pragma("unroll") for (int m = 0; m < 4; ++m) _Pragma("unroll") for (int k = 0; k < 2; ++k) dst[m][k] = *(const LAS half8*)(lds + PG8_SA(b, h) + aoff + m * 2048 + k * 1024); } while (0)
; #define PG8_LDB(dst, b, h) do { _Pragma("unroll") for (int n = 0; n < 2; ++n) _Pragma("unroll") for (int k = 0; k < 2; ++k) dst[n][k] = *(const LAS half8*)(lds + PG8_SB(b, h) + boff + n * 2048 + k * 1024); } while (0)
; #define PG8_MMA(ai, bj, At, Bt) do { __builtin_amdgcn_s_setprio(1); _Pragma("unroll") for (int m = 0; m < 4; ++m) _Pragma("unroll") for (int n = 0; n < 2; ++n) _Pragma("unroll") for (int k = 0; k < 2; ++k) \
;         acc[ai][bj][m][n] = __builtin_amdgcn_mfma_f32_16x16x32_f16(Bt[n][k], At[m][k], acc[ai][bj][m][n], 0, 0, 0); __builtin_amdgcn_s_setprio(0); } while (0)
; #define PG8_WAIT_V(n) asm volatile("s_waitcnt vmcnt(" #n ")" ::: "memory")
; #define PG8_WAIT_L(n) asm volatile("s_waitcnt lgkmcnt(" #n ")" ::: "memory")
; #define PG8_BAR __builtin_amdgcn_s_barrier()
; #define PG8_SCHED __builtin_amdgcn_sched_barrier(0)
; template <class Epi>
; __device__ __forceinline__ void gemm_phase(LAS unsigned char* lds, const Gemm g, const StaticOrder& S, const Epi& E) {
;     ...
;             PG8_WAIT_V(8); PG8_WAIT_L(0); PG8_BAR; PG8_MMA(1, 0, At, B0); PG8_MMA(1, 1, At, B1); PG8_BAR; PG8_SCHED;
;             PG8_LDB(B0, 1, 0); PG8_LDB(B1, 1, 1); PG8_SCHED; PG8_LDA(At, 1, 0); PG8_STAGE(PG8_SA(0, 1), a2 + hA, voffA);
;             PG8_WAIT_V(8); PG8_WAIT_L(0); PG8_BAR; PG8_MMA(0, 0, At, B0); PG8_MMA(0, 1, At, B1); PG8_BAR; PG8_SCHED;
	s_setprio 1
	s_waitcnt lgkmcnt(0)
	v_mfma_f32_16x16x32_f16 v[58:61], v[140:143], v[174:177], v[58:61]
	v_mfma_f32_16x16x32_f16 v[54:57], v[148:151], v[174:177], v[54:57]
	v_mfma_f32_16x16x32_f16 v[42:45], v[140:143], v[182:185], v[42:45]
	v_mfma_f32_16x16x32_f16 v[38:41], v[148:151], v[182:185], v[38:41]
	v_mfma_f32_16x16x32_f16 v[26:29], v[140:143], v[190:193], v[26:29]
	v_mfma_f32_16x16x32_f16 v[22:25], v[148:151], v[190:193], v[22:25]
	v_mfma_f32_16x16x32_f16 v[10:13], v[140:143], v[198:201], v[10:13]
	v_mfma_f32_16x16x32_f16 v[6:9], v[148:151], v[198:201], v[6:9]
	v_mfma_f32_16x16x32_f16 v[58:61], v[144:147], v[178:181], v[58:61]
	v_mfma_f32_16x16x32_f16 v[54:57], v[152:155], v[178:181], v[54:57]
	v_mfma_f32_16x16x32_f16 v[42:45], v[144:147], v[186:189], v[42:45]
	v_mfma_f32_16x16x32_f16 v[38:41], v[152:155], v[186:189], v[38:41]
	v_mfma_f32_16x16x32_f16 v[26:29], v[144:147], v[194:197], v[26:29]
	v_mfma_f32_16x16x32_f16 v[22:25], v[152:155], v[194:197], v[22:25]
	v_mfma_f32_16x16x32_f16 v[10:13], v[144:147], v[202:205], v[10:13]
	v_mfma_f32_16x16x32_f16 v[6:9], v[152:155], v[202:205], v[6:9]
	v_mfma_f32_16x16x32_f16 v[50:53], v[156:159], v[174:177], v[50:53]
	v_mfma_f32_16x16x32_f16 v[62:65], v[166:169], v[174:177], v[62:65]
	v_mfma_f32_16x16x32_f16 v[34:37], v[156:159], v[182:185], v[34:37]
	v_mfma_f32_16x16x32_f16 v[46:49], v[166:169], v[182:185], v[46:49]
	v_mfma_f32_16x16x32_f16 v[18:21], v[156:159], v[190:193], v[18:21]
	v_mfma_f32_16x16x32_f16 v[30:33], v[166:169], v[190:193], v[30:33]
	v_mfma_f32_16x16x32_f16 v[2:5], v[156:159], v[198:201], v[2:5]
	v_mfma_f32_16x16x32_f16 v[14:17], v[166:169], v[198:201], v[14:17]
	v_mfma_f32_16x16x32_f16 v[50:53], v[162:165], v[178:181], v[50:53]
	v_mfma_f32_16x16x32_f16 v[62:65], v[170:173], v[178:181], v[62:65]
	v_mfma_f32_16x16x32_f16 v[34:37], v[162:165], v[186:189], v[34:37]
	v_mfma_f32_16x16x32_f16 v[46:49], v[170:173], v[186:189], v[46:49]
	v_mfma_f32_16x16x32_f16 v[18:21], v[162:165], v[194:197], v[18:21]
	v_mfma_f32_16x16x32_f16 v[30:33], v[170:173], v[194:197], v[30:33]
	v_mfma_f32_16x16x32_f16 v[2:5], v[162:165], v[202:205], v[2:5]
	v_mfma_f32_16x16x32_f16 v[14:17], v[170:173], v[202:205], v[14:17]
	s_setprio 0
	s_barrier
	s_add_i32 s14, 0, 0x18000
	s_add_i32 s17, 0, 0x1c000
	v_add_u32_e32 v152, s14, v161
	v_add_u32_e32 v170, s17, v161
	ds_read_b128 v[140:143], v152
	ds_read_b128 v[144:147], v152 offset:1024
	ds_read_b128 v[148:151], v152 offset:2048
	ds_read_b128 v[152:155], v152 offset:3072
	ds_read_b128 v[156:159], v170
	ds_read_b128 v[162:165], v170 offset:1024
	ds_read_b128 v[166:169], v170 offset:2048
	ds_read_b128 v[170:173], v170 offset:3072
	s_add_u32 s0, s52, 0xb0000
	s_addc_u32 s1, s53, 0
	s_mov_b32 m0, s59
	v_lshl_add_u64 v[214:215], s[0:1], 0, v[130:131]
	ds_read_b128 v[174:177], v228 offset:32768
	ds_read_b128 v[178:181], v228 offset:33792
	ds_read_b128 v[182:185], v228 offset:34816
	ds_read_b128 v[186:189], v228 offset:35840
	ds_read_b128 v[190:193], v228 offset:36864
	ds_read_b128 v[194:197], v228 offset:37888
	ds_read_b128 v[198:201], v228 offset:38912
	ds_read_b128 v[202:205], v228 offset:39936
	global_load_lds_dwordx4 v[214:215], off
	v_lshl_add_u64 v[214:215], s[0:1], 0, v[132:133]
	s_mov_b32 m0, s60
	s_nop 0
	global_load_lds_dwordx4 v[214:215], off
	s_waitcnt vmcnt(8)
	s_waitcnt lgkmcnt(0)
	s_barrier
	s_setprio 1
	s_waitcnt lgkmcnt(0)
	v_mfma_f32_16x16x32_f16 v[122:125], v[140:143], v[174:177], v[122:125]
	v_mfma_f32_16x16x32_f16 v[118:121], v[148:151], v[174:177], v[118:121]
	v_mfma_f32_16x16x32_f16 v[106:109], v[140:143], v[182:185], v[106:109]
	v_mfma_f32_16x16x32_f16 v[102:105], v[148:151], v[182:185], v[102:105]
	v_mfma_f32_16x16x32_f16 v[90:93], v[140:143], v[190:193], v[90:93]
	v_mfma_f32_16x16x32_f16 v[86:89], v[148:151], v[190:193], v[86:89]
	v_mfma_f32_16x16x32_f16 v[74:77], v[140:143], v[198:201], v[74:77]
	v_mfma_f32_16x16x32_f16 v[70:73], v[148:151], v[198:201], v[70:73]
	v_mfma_f32_16x16x32_f16 v[122:125], v[144:147], v[178:181], v[122:125]
	v_mfma_f32_16x16x32_f16 v[118:121], v[152:155], v[178:181], v[118:121]
	v_mfma_f32_16x16x32_f16 v[106:109], v[144:147], v[186:189], v[106:109]
	v_mfma_f32_16x16x32_f16 v[102:105], v[152:155], v[186:189], v[102:105]
	v_mfma_f32_16x16x32_f16 v[90:93], v[144:147], v[194:197], v[90:93]
	v_mfma_f32_16x16x32_f16 v[86:89], v[152:155], v[194:197], v[86:89]
	v_mfma_f32_16x16x32_f16 v[74:77], v[144:147], v[202:205], v[74:77]
	v_mfma_f32_16x16x32_f16 v[70:73], v[152:155], v[202:205], v[70:73]
	v_mfma_f32_16x16x32_f16 v[114:117], v[156:159], v[174:177], v[114:117]
	v_mfma_f32_16x16x32_f16 v[126:129], v[166:169], v[174:177], v[126:129]
	v_mfma_f32_16x16x32_f16 v[98:101], v[156:159], v[182:185], v[98:101]
	v_mfma_f32_16x16x32_f16 v[110:113], v[166:169], v[182:185], v[110:113]
	v_mfma_f32_16x16x32_f16 v[82:85], v[156:159], v[190:193], v[82:85]
	v_mfma_f32_16x16x32_f16 v[94:97], v[166:169], v[190:193], v[94:97]
	v_mfma_f32_16x16x32_f16 v[66:69], v[156:159], v[198:201], v[66:69]
	v_mfma_f32_16x16x32_f16 v[78:81], v[166:169], v[198:201], v[78:81]
	v_mfma_f32_16x16x32_f16 v[114:117], v[162:165], v[178:181], v[114:117]
	v_mfma_f32_16x16x32_f16 v[126:129], v[170:173], v[178:181], v[126:129]
	v_mfma_f32_16x16x32_f16 v[98:101], v[162:165], v[186:189], v[98:101]
	v_mfma_f32_16x16x32_f16 v[110:113], v[170:173], v[186:189], v[110:113]
	v_mfma_f32_16x16x32_f16 v[82:85], v[162:165], v[194:197], v[82:85]
	v_mfma_f32_16x16x32_f16 v[94:97], v[170:173], v[194:197], v[94:97]
	v_mfma_f32_16x16x32_f16 v[66:69], v[162:165], v[202:205], v[66:69]
	v_mfma_f32_16x16x32_f16 v[78:81], v[170:173], v[202:205], v[78:81]
	s_setprio 0
	s_barrier
; #define PG8_STAGE(bufoff, gbase, voff) do { _Pragma("unroll") for (int _i = 0; _i < 2; ++_i) \
;         __builtin_amdgcn_global_load_lds((const unsigned*)((const char*)(gbase) + (voff)[_i]), (LAS unsigned*)(lds + (bufoff) + ldsw + _i * 8192), 16, 0, 0); } while (0)
; #define PG8_LDA(dst, b, h) do { _Pragma("unroll") for (int m = 0; m < 4; ++m) _Pragma("unroll") for (int k = 0; k < 2; ++k) dst[m][k] = *(const LAS half8*)(lds + PG8_SA(b, h) + aoff + m * 2048 + k * 1024); } while (0)
; #define PG8_MMA(ai, bj, At, Bt) do { __builtin_amdgcn_s_setprio(1); _Pragma("unroll") for (int m = 0; m < 4; ++m) _Pragma("unroll") for (int n = 0; n < 2; ++n) _Pragma("unroll") for (int k = 0; k < 2; ++k) \
;         acc[ai][bj][m][n] = __builtin_amdgcn_mfma_f32_16x16x32_f16(Bt[n][k], At[m][k], acc[ai][bj][m][n], 0, 0, 0); __builtin_amdgcn_s_setprio(0); } while (0)
; #define PG8_WAIT_V(n) asm volatile("s_waitcnt vmcnt(" #n ")" ::: "memory")
; #define PG8_WAIT_L(n) asm volatile("s_waitcnt lgkmcnt(" #n ")" ::: "memory")
; #define PG8_BAR __builtin_amdgcn_s_barrier()
; #define PG8_SCHED __builtin_amdgcn_sched_barrier(0)
; template <class Epi>
; __device__ __forceinline__ void gemm_phase(LAS unsigned char* lds, const Gemm g, const StaticOrder& S, const Epi& E) {
;     ...
;             PG8_LDA(At, 1, 1); PG8_STAGE(PG8_SB(1, 0), b3, voffB); PG8_STAGE(PG8_SB(1, 1), b3 + hB, voffB); PG8_STAGE(PG8_SA(1, 0), a3, voffA);
;             PG8_WAIT_V(8); PG8_WAIT_L(0); PG8_BAR; PG8_MMA(1, 0, At, B0); PG8_MMA(1, 1, At, B1); PG8_BAR; PG8_SCHED;
;         }
	s_add_i32 s0, s14, s56
	v_lshl_add_u64 v[206:207], v[206:207], 0, s[92:93]
	s_mov_b32 m0, s0
	ds_read_b128 v[174:177], v228 offset:49152
	ds_read_b128 v[178:181], v228 offset:50176
	ds_read_b128 v[182:185], v228 offset:51200
	ds_read_b128 v[186:189], v228 offset:52224
	ds_read_b128 v[190:193], v228 offset:53248
	ds_read_b128 v[194:197], v228 offset:54272
	ds_read_b128 v[198:201], v228 offset:55296
	ds_read_b128 v[202:205], v228 offset:56320
	global_load_lds_dwordx4 v[206:207], off
	s_add_i32 m0, s0, 0x2000
	s_add_u32 s0, s24, 0xb0080
	v_lshl_add_u64 v[206:207], v[208:209], 0, s[92:93]
	s_addc_u32 s1, s25, 0
	s_add_i32 s14, s17, s56
	global_load_lds_dwordx4 v[206:207], off
	v_lshl_add_u64 v[206:207], s[0:1], 0, v[0:1]
	s_mov_b32 m0, s14
	s_nop 0
	global_load_lds_dwordx4 v[206:207], off
	v_lshl_add_u64 v[206:207], s[0:1], 0, v[134:135]
	s_add_i32 m0, s14, 0x2000
	s_nop 0
	global_load_lds_dwordx4 v[206:207], off
	v_lshl_add_u64 v[206:207], v[210:211], 0, s[92:93]
	s_mov_b32 m0, s63
	s_nop 0
	global_load_lds_dwordx4 v[206:207], off
	v_lshl_add_u64 v[206:207], v[212:213], 0, s[92:93]
	s_mov_b32 m0, s64
	s_nop 0
	global_load_lds_dwordx4 v[206:207], off
	s_waitcnt vmcnt(8)
	s_waitcnt lgkmcnt(0)
	s_barrier
	s_setprio 1
	s_waitcnt lgkmcnt(0)
	v_mfma_f32_16x16x32_f16 v[58:61], v[140:143], v[174:177], v[58:61]
	v_mfma_f32_16x16x32_f16 v[54:57], v[148:151], v[174:177], v[54:57]
	v_mfma_f32_16x16x32_f16 v[42:45], v[140:143], v[182:185], v[42:45]
	v_mfma_f32_16x16x32_f16 v[38:41], v[148:151], v[182:185], v[38:41]
	v_mfma_f32_16x16x32_f16 v[26:29], v[140:143], v[190:193], v[26:29]
	v_mfma_f32_16x16x32_f16 v[22:25], v[148:151], v[190:193], v[22:25]
	v_mfma_f32_16x16x32_f16 v[10:13], v[140:143], v[198:201], v[10:13]
	v_mfma_f32_16x16x32_f16 v[6:9], v[148:151], v[198:201], v[6:9]
	v_mfma_f32_16x16x32_f16 v[58:61], v[144:147], v[178:181], v[58:61]
	v_mfma_f32_16x16x32_f16 v[54:57], v[152:155], v[178:181], v[54:57]
	v_mfma_f32_16x16x32_f16 v[42:45], v[144:147], v[186:189], v[42:45]
	v_mfma_f32_16x16x32_f16 v[38:41], v[152:155], v[186:189], v[38:41]
	v_mfma_f32_16x16x32_f16 v[26:29], v[144:147], v[194:197], v[26:29]
	v_mfma_f32_16x16x32_f16 v[22:25], v[152:155], v[194:197], v[22:25]
	v_mfma_f32_16x16x32_f16 v[10:13], v[144:147], v[202:205], v[10:13]
	v_mfma_f32_16x16x32_f16 v[6:9], v[152:155], v[202:205], v[6:9]
	v_mfma_f32_16x16x32_f16 v[50:53], v[156:159], v[174:177], v[50:53]
	v_mfma_f32_16x16x32_f16 v[62:65], v[166:169], v[174:177], v[62:65]
	v_mfma_f32_16x16x32_f16 v[34:37], v[156:159], v[182:185], v[34:37]
	v_mfma_f32_16x16x32_f16 v[46:49], v[166:169], v[182:185], v[46:49]
	v_mfma_f32_16x16x32_f16 v[18:21], v[156:159], v[190:193], v[18:21]
	v_mfma_f32_16x16x32_f16 v[30:33], v[166:169], v[190:193], v[30:33]
	v_mfma_f32_16x16x32_f16 v[2:5], v[156:159], v[198:201], v[2:5]
	v_mfma_f32_16x16x32_f16 v[14:17], v[166:169], v[198:201], v[14:17]
	v_mfma_f32_16x16x32_f16 v[50:53], v[162:165], v[178:181], v[50:53]
	v_mfma_f32_16x16x32_f16 v[62:65], v[170:173], v[178:181], v[62:65]
	v_mfma_f32_16x16x32_f16 v[34:37], v[162:165], v[186:189], v[34:37]
	v_mfma_f32_16x16x32_f16 v[46:49], v[170:173], v[186:189], v[46:49]
	v_mfma_f32_16x16x32_f16 v[18:21], v[162:165], v[194:197], v[18:21]
	v_mfma_f32_16x16x32_f16 v[30:33], v[170:173], v[194:197], v[30:33]
	v_mfma_f32_16x16x32_f16 v[2:5], v[162:165], v[202:205], v[2:5]
	v_mfma_f32_16x16x32_f16 v[14:17], v[170:173], v[202:205], v[14:17]
	s_setprio 0
	s_barrier
	s_add_u32 s2, s2, 0x100
	s_addc_u32 s3, s3, 0
	s_cmp_ge_i32 s15, s23
	s_mov_b64 s[0:1], s[10:11]
	s_mov_b32 s14, s15
	s_cbranch_scc0 .LBB0_83
	s_and_b64 vcc, exec, s[50:51]
	s_cbranch_vccz .LBB0_86

; #define PG8_STAGE(bufoff, gbase, voff) do { _Pragma("unroll") for (int _i = 0; _i < 2; ++_i) \
;         __builtin_amdgcn_global_load_lds((const unsigned*)((const char*)(gbase) + (voff)[_i]), (LAS unsigned*)(lds + (bufoff) + ldsw + _i * 8192), 16, 0, 0); } while (0)
; #define PG8_LDA(dst, b, h) do { _Pragma("unroll") for (int m = 0; m < 4; ++m) _Pragma("unroll") for (int k = 0; k < 2; ++k) dst[m][k] = *(const LAS half8*)(lds + PG8_SA(b, h) + aoff + m * 2048 + k * 1024); } while (0)
; #define PG8_LDB(dst, b, h) do { _Pragma("unroll") for (int n = 0; n < 2; ++n) _Pragma("unroll") for (int k = 0; k < 2; ++k) dst[n][k] = *(const LAS half8*)(lds + PG8_SB(b, h) + boff + n * 2048 + k * 1024); } while (0)
; #define PG8_MMA(ai, bj, At, Bt) do { __builtin_amdgcn_s_setprio(1); _Pragma("unroll") for (int m = 0; m < 4; ++m) _Pragma("unroll") for (int n = 0; n < 2; ++n) _Pragma("unroll") for (int k = 0; k < 2; ++k) \
;         acc[ai][bj][m][n] = __builtin_amdgcn_mfma_f32_16x16x32_f16(Bt[n][k], At[m][k], acc[ai][bj][m][n], 0, 0, 0); __builtin_amdgcn_s_setprio(0); } while (0)
; #define PG8_WAIT_V(n) asm volatile("s_waitcnt vmcnt(" #n ")" ::: "memory")
; #define PG8_WAIT_L(n) asm volatile("s_waitcnt lgkmcnt(" #n ")" ::: "memory")
; #define PG8_BAR __builtin_amdgcn_s_barrier()
; #define PG8_SCHED __builtin_amdgcn_sched_barrier(0)
; template <class Epi>
; __device__ __forceinline__ void gemm_phase(LAS unsigned char* lds, const Gemm g, const StaticOrder& S, const Epi& E) {
;     ...
;         for (int t = 0; t < nt; t += 2) {
;             const bool last = (t == nt - 2);
;             const char* a1 = cA + (size_t)(t + 1) * kstep;
;             const char* a2 = last ? nA : cA + (size_t)(t + 2) * kstep; const char* b2 = last ? nB : cB + (size_t)(t + 2) * kstep;
;             const char* a3 = a2 + kstep; const char* b3 = b2 + kstep;
;             PG8_LDB(B0, 0, 0); PG8_LDB(B1, 0, 1); PG8_SCHED; PG8_LDA(At, 0, 0); PG8_STAGE(PG8_SA(1, 1), a1 + hA, voffA);
;             PG8_WAIT_V(8); PG8_WAIT_L(0); PG8_BAR; PG8_MMA(0, 0, At, B0); PG8_MMA(0, 1, At, B1); PG8_BAR; PG8_SCHED;
;             PG8_LDA(At, 0, 1); PG8_STAGE(PG8_SB(0, 0), b2, voffB); PG8_STAGE(PG8_SB(0, 1), b2 + hB, voffB); PG8_STAGE(PG8_SA(0, 0), a2, voffA);
;             PG8_WAIT_V(8); PG8_WAIT_L(0); PG8_BAR; PG8_MMA(1, 0, At, B0); PG8_MMA(1, 1, At, B1); PG8_BAR; PG8_SCHED;
.LBB0_158:
	s_add_i32 s14, s11, 2
	s_add_u32 s16, s0, 0x100
	s_addc_u32 s17, s1, 0
	s_add_i32 s15, 0, 0x10000
	s_cmp_eq_u32 s64, s11
	s_cselect_b32 s25, s51, s17
	s_cselect_b32 s24, s50, s16
	s_cselect_b32 s19, s43, s3
	s_cselect_b32 s18, s42, s2
	s_add_i32 s11, 0, 0x14000
	v_add_u32_e32 v152, s15, v161
	v_add_u32_e32 v170, s11, v161
	ds_read_b128 v[140:143], v152
	ds_read_b128 v[144:147], v152 offset:1024
	ds_read_b128 v[148:151], v152 offset:2048
	ds_read_b128 v[152:155], v152 offset:3072
	ds_read_b128 v[156:159], v170
	ds_read_b128 v[162:165], v170 offset:1024
	ds_read_b128 v[166:169], v170 offset:2048
	ds_read_b128 v[170:173], v170 offset:3072
	v_lshl_add_u64 v[206:207], s[0:1], 0, v[138:139]
	s_add_i32 m0, s55, 0xc000
	ds_read_b128 v[174:177], v228
	ds_read_b128 v[178:181], v228 offset:1024
	ds_read_b128 v[182:185], v228 offset:2048
	ds_read_b128 v[186:189], v228 offset:3072
	ds_read_b128 v[190:193], v228 offset:4096
	ds_read_b128 v[194:197], v228 offset:5120
	ds_read_b128 v[198:201], v228 offset:6144
	ds_read_b128 v[202:205], v228 offset:7168
	global_load_lds_dwordx4 v[206:207], off
	v_lshl_add_u64 v[206:207], s[0:1], 0, v[136:137]
	s_add_i32 m0, s55, 0xe000
	s_nop 0
	global_load_lds_dwordx4 v[206:207], off
	s_waitcnt vmcnt(8)
	s_waitcnt lgkmcnt(0)
	s_barrier
	s_setprio 1
	s_waitcnt lgkmcnt(0)
	v_mfma_f32_16x16x32_f16 v[122:125], v[140:143], v[174:177], v[122:125]
	v_mfma_f32_16x16x32_f16 v[118:121], v[148:151], v[174:177], v[118:121]
	v_mfma_f32_16x16x32_f16 v[106:109], v[140:143], v[182:185], v[106:109]
	v_mfma_f32_16x16x32_f16 v[102:105], v[148:151], v[182:185], v[102:105]
	v_mfma_f32_16x16x32_f16 v[90:93], v[140:143], v[190:193], v[90:93]
	v_mfma_f32_16x16x32_f16 v[86:89], v[148:151], v[190:193], v[86:89]
	v_mfma_f32_16x16x32_f16 v[74:77], v[140:143], v[198:201], v[74:77]
	v_mfma_f32_16x16x32_f16 v[70:73], v[148:151], v[198:201], v[70:73]
	v_mfma_f32_16x16x32_f16 v[122:125], v[144:147], v[178:181], v[122:125]
	v_mfma_f32_16x16x32_f16 v[118:121], v[152:155], v[178:181], v[118:121]
	v_mfma_f32_16x16x32_f16 v[106:109], v[144:147], v[186:189], v[106:109]
	v_mfma_f32_16x16x32_f16 v[102:105], v[152:155], v[186:189], v[102:105]
	v_mfma_f32_16x16x32_f16 v[90:93], v[144:147], v[194:197], v[90:93]
	v_mfma_f32_16x16x32_f16 v[86:89], v[152:155], v[194:197], v[86:89]
	v_mfma_f32_16x16x32_f16 v[74:77], v[144:147], v[202:205], v[74:77]
	v_mfma_f32_16x16x32_f16 v[70:73], v[152:155], v[202:205], v[70:73]
	v_mfma_f32_16x16x32_f16 v[114:117], v[156:159], v[174:177], v[114:117]
	v_mfma_f32_16x16x32_f16 v[126:129], v[166:169], v[174:177], v[126:129]
	v_mfma_f32_16x16x32_f16 v[98:101], v[156:159], v[182:185], v[98:101]
	v_mfma_f32_16x16x32_f16 v[110:113], v[166:169], v[182:185], v[110:113]
	v_mfma_f32_16x16x32_f16 v[82:85], v[156:159], v[190:193], v[82:85]
	v_mfma_f32_16x16x32_f16 v[94:97], v[166:169], v[190:193], v[94:97]
	v_mfma_f32_16x16x32_f16 v[66:69], v[156:159], v[198:201], v[66:69]
	v_mfma_f32_16x16x32_f16 v[78:81], v[166:169], v[198:201], v[78:81]
	v_mfma_f32_16x16x32_f16 v[114:117], v[162:165], v[178:181], v[114:117]
	v_mfma_f32_16x16x32_f16 v[126:129], v[170:173], v[178:181], v[126:129]
	v_mfma_f32_16x16x32_f16 v[98:101], v[162:165], v[186:189], v[98:101]
	v_mfma_f32_16x16x32_f16 v[110:113], v[170:173], v[186:189], v[110:113]
	v_mfma_f32_16x16x32_f16 v[82:85], v[162:165], v[194:197], v[82:85]
	v_mfma_f32_16x16x32_f16 v[94:97], v[170:173], v[194:197], v[94:97]
	v_mfma_f32_16x16x32_f16 v[66:69], v[162:165], v[202:205], v[66:69]
	v_mfma_f32_16x16x32_f16 v[78:81], v[170:173], v[202:205], v[78:81]
	s_setprio 0
	s_barrier
	s_add_i32 s0, s15, s54
	v_lshl_add_u64 v[206:207], s[18:19], 0, v[0:1]
	s_mov_b32 m0, s0
	ds_read_b128 v[174:177], v228 offset:16384
	ds_read_b128 v[178:181], v228 offset:17408
	ds_read_b128 v[182:185], v228 offset:18432
	ds_read_b128 v[186:189], v228 offset:19456
	ds_read_b128 v[190:193], v228 offset:20480
	ds_read_b128 v[194:197], v228 offset:21504
	ds_read_b128 v[198:201], v228 offset:22528
	ds_read_b128 v[202:205], v228 offset:23552
	global_load_lds_dwordx4 v[206:207], off
	s_add_i32 m0, s0, 0x2000
	s_add_u32 s0, s18, 0xb0000
	v_lshl_add_u64 v[208:209], s[18:19], 0, v[134:135]
	s_addc_u32 s1, s19, 0
	s_add_i32 s11, s11, s54
	global_load_lds_dwordx4 v[208:209], off
	v_lshl_add_u64 v[210:211], s[0:1], 0, v[0:1]
	s_mov_b32 m0, s11
	v_lshl_add_u64 v[212:213], s[24:25], 0, v[132:133]
	global_load_lds_dwordx4 v[210:211], off
	v_lshl_add_u64 v[210:211], s[0:1], 0, v[134:135]
	s_add_i32 m0, s11, 0x2000
	s_nop 0
	global_load_lds_dwordx4 v[210:211], off
	v_lshl_add_u64 v[210:211], s[24:25], 0, v[130:131]
	s_mov_b32 m0, s55
	s_nop 0
	global_load_lds_dwordx4 v[210:211], off
	s_mov_b32 m0, s56
	s_nop 0
	global_load_lds_dwordx4 v[212:213], off
	s_waitcnt vmcnt(8)
	s_waitcnt lgkmcnt(0)
	s_barrier
; #define PG8_STAGE(bufoff, gbase, voff) do { _Pragma("unroll") for (int _i = 0; _i < 2; ++_i) \
;         __builtin_amdgcn_global_load_lds((const unsigned*)((const char*)(gbase) + (voff)[_i]), (LAS unsigned*)(lds + (bufoff) + ldsw + _i * 8192), 16, 0, 0); } while (0)
; #define PG8_LDA(dst, b, h) do { _Pragma("unroll") for (int m = 0; m < 4; ++m) _Pragma("unroll") for (int k = 0; k < 2; ++k) dst[m][k] = *(const LAS half8*)(lds + PG8_SA(b, h) + aoff + m * 2048 + k * 1024); } while (0)
; #define PG8_LDB(dst, b, h) do { _Pragma("unroll") for (int n = 0; n < 2; ++n) _Pragma("unroll") for (int k = 0; k < 2; ++k) dst[n][k] = *(const LAS half8*)(lds + PG8_SB(b, h) + boff + n * 2048 + k * 1024); } while (0)
; #define PG8_MMA(ai, bj, At, Bt) do { __builtin_amdgcn_s_setprio(1); _Pragma("unroll") for (int m = 0; m < 4; ++m) _Pragma("unroll") for (int n = 0; n < 2; ++n) _Pragma("unroll") for (int k = 0; k < 2; ++k) \
;         acc[ai][bj][m][n] = __builtin_amdgcn_mfma_f32_16x16x32_f16(Bt[n][k], At[m][k], acc[ai][bj][m][n], 0, 0, 0); __builtin_amdgcn_s_setprio(0); } while (0)
; #define PG8_WAIT_V(n) asm volatile("s_waitcnt vmcnt(" #n ")" ::: "memory")
; #define PG8_WAIT_L(n) asm volatile("s_waitcnt lgkmcnt(" #n ")" ::: "memory")
; #define PG8_BAR __builtin_amdgcn_s_barrier()
; #define PG8_SCHED __builtin_amdgcn_sched_barrier(0)
; template <class Epi>
; __device__ __forceinline__ void gemm_phase(LAS unsigned char* lds, const Gemm g, const StaticOrder& S, const Epi& E) {
;     ...
;             PG8_WAIT_V(8); PG8_WAIT_L(0); PG8_BAR; PG8_MMA(1, 0, At, B0); PG8_MMA(1, 1, At, B1); PG8_BAR; PG8_SCHED;
;             PG8_LDB(B0, 1, 0); PG8_LDB(B1, 1, 1); PG8_SCHED; PG8_LDA(At, 1, 0); PG8_STAGE(PG8_SA(0, 1), a2 + hA, voffA);
;             PG8_WAIT_V(8); PG8_WAIT_L(0); PG8_BAR; PG8_MMA(0, 0, At, B0); PG8_MMA(0, 1, At, B1); PG8_BAR; PG8_SCHED;
	s_setprio 1
	s_waitcnt lgkmcnt(0)
	v_mfma_f32_16x16x32_f16 v[58:61], v[140:143], v[174:177], v[58:61]
	v_mfma_f32_16x16x32_f16 v[54:57], v[148:151], v[174:177], v[54:57]
	v_mfma_f32_16x16x32_f16 v[42:45], v[140:143], v[182:185], v[42:45]
	v_mfma_f32_16x16x32_f16 v[38:41], v[148:151], v[182:185], v[38:41]
	v_mfma_f32_16x16x32_f16 v[26:29], v[140:143], v[190:193], v[26:29]
	v_mfma_f32_16x16x32_f16 v[22:25], v[148:151], v[190:193], v[22:25]
	v_mfma_f32_16x16x32_f16 v[10:13], v[140:143], v[198:201], v[10:13]
	v_mfma_f32_16x16x32_f16 v[6:9], v[148:151], v[198:201], v[6:9]
	v_mfma_f32_16x16x32_f16 v[58:61], v[144:147], v[178:181], v[58:61]
	v_mfma_f32_16x16x32_f16 v[54:57], v[152:155], v[178:181], v[54:57]
	v_mfma_f32_16x16x32_f16 v[42:45], v[144:147], v[186:189], v[42:45]
	v_mfma_f32_16x16x32_f16 v[38:41], v[152:155], v[186:189], v[38:41]
	v_mfma_f32_16x16x32_f16 v[26:29], v[144:147], v[194:197], v[26:29]
	v_mfma_f32_16x16x32_f16 v[22:25], v[152:155], v[194:197], v[22:25]
	v_mfma_f32_16x16x32_f16 v[10:13], v[144:147], v[202:205], v[10:13]
	v_mfma_f32_16x16x32_f16 v[6:9], v[152:155], v[202:205], v[6:9]
	v_mfma_f32_16x16x32_f16 v[50:53], v[156:159], v[174:177], v[50:53]
	v_mfma_f32_16x16x32_f16 v[62:65], v[166:169], v[174:177], v[62:65]
	v_mfma_f32_16x16x32_f16 v[34:37], v[156:159], v[182:185], v[34:37]
	v_mfma_f32_16x16x32_f16 v[46:49], v[166:169], v[182:185], v[46:49]
	v_mfma_f32_16x16x32_f16 v[18:21], v[156:159], v[190:193], v[18:21]
	v_mfma_f32_16x16x32_f16 v[30:33], v[166:169], v[190:193], v[30:33]
	v_mfma_f32_16x16x32_f16 v[2:5], v[156:159], v[198:201], v[2:5]
	v_mfma_f32_16x16x32_f16 v[14:17], v[166:169], v[198:201], v[14:17]
	v_mfma_f32_16x16x32_f16 v[50:53], v[162:165], v[178:181], v[50:53]
	v_mfma_f32_16x16x32_f16 v[62:65], v[170:173], v[178:181], v[62:65]
	v_mfma_f32_16x16x32_f16 v[34:37], v[162:165], v[186:189], v[34:37]
	v_mfma_f32_16x16x32_f16 v[46:49], v[170:173], v[186:189], v[46:49]
	v_mfma_f32_16x16x32_f16 v[18:21], v[162:165], v[194:197], v[18:21]
	v_mfma_f32_16x16x32_f16 v[30:33], v[170:173], v[194:197], v[30:33]
	v_mfma_f32_16x16x32_f16 v[2:5], v[162:165], v[202:205], v[2:5]
	v_mfma_f32_16x16x32_f16 v[14:17], v[170:173], v[202:205], v[14:17]
	s_setprio 0
	s_barrier
	s_add_i32 s11, 0, 0x18000
	s_add_i32 s15, 0, 0x1c000
	v_add_u32_e32 v152, s11, v161
	v_add_u32_e32 v170, s15, v161
	ds_read_b128 v[140:143], v152
	ds_read_b128 v[144:147], v152 offset:1024
	ds_read_b128 v[148:151], v152 offset:2048
	ds_read_b128 v[152:155], v152 offset:3072
	ds_read_b128 v[156:159], v170
	ds_read_b128 v[162:165], v170 offset:1024
	ds_read_b128 v[166:169], v170 offset:2048
	ds_read_b128 v[170:173], v170 offset:3072
	s_add_u32 s0, s24, 0xb0000
	s_addc_u32 s1, s25, 0
	s_mov_b32 m0, s57
	v_lshl_add_u64 v[214:215], s[0:1], 0, v[130:131]
	ds_read_b128 v[174:177], v228 offset:32768
	ds_read_b128 v[178:181], v228 offset:33792
	ds_read_b128 v[182:185], v228 offset:34816
	ds_read_b128 v[186:189], v228 offset:35840
	ds_read_b128 v[190:193], v228 offset:36864
	ds_read_b128 v[194:197], v228 offset:37888
	ds_read_b128 v[198:201], v228 offset:38912
	ds_read_b128 v[202:205], v228 offset:39936
	global_load_lds_dwordx4 v[214:215], off
	v_lshl_add_u64 v[214:215], s[0:1], 0, v[132:133]
	s_mov_b32 m0, s58
	s_nop 0
	global_load_lds_dwordx4 v[214:215], off
	s_waitcnt vmcnt(8)
	s_waitcnt lgkmcnt(0)
	s_barrier
	s_setprio 1
	s_waitcnt lgkmcnt(0)
	v_mfma_f32_16x16x32_f16 v[122:125], v[140:143], v[174:177], v[122:125]
	v_mfma_f32_16x16x32_f16 v[118:121], v[148:151], v[174:177], v[118:121]
	v_mfma_f32_16x16x32_f16 v[106:109], v[140:143], v[182:185], v[106:109]
	v_mfma_f32_16x16x32_f16 v[102:105], v[148:151], v[182:185], v[102:105]
	v_mfma_f32_16x16x32_f16 v[90:93], v[140:143], v[190:193], v[90:93]
	v_mfma_f32_16x16x32_f16 v[86:89], v[148:151], v[190:193], v[86:89]
	v_mfma_f32_16x16x32_f16 v[74:77], v[140:143], v[198:201], v[74:77]
	v_mfma_f32_16x16x32_f16 v[70:73], v[148:151], v[198:201], v[70:73]
	v_mfma_f32_16x16x32_f16 v[122:125], v[144:147], v[178:181], v[122:125]
	v_mfma_f32_16x16x32_f16 v[118:121], v[152:155], v[178:181], v[118:121]
	v_mfma_f32_16x16x32_f16 v[106:109], v[144:147], v[186:189], v[106:109]
	v_mfma_f32_16x16x32_f16 v[102:105], v[152:155], v[186:189], v[102:105]
	v_mfma_f32_16x16x32_f16 v[90:93], v[144:147], v[194:197], v[90:93]
	v_mfma_f32_16x16x32_f16 v[86:89], v[152:155], v[194:197], v[86:89]
	v_mfma_f32_16x16x32_f16 v[74:77], v[144:147], v[202:205], v[74:77]
	v_mfma_f32_16x16x32_f16 v[70:73], v[152:155], v[202:205], v[70:73]
	v_mfma_f32_16x16x32_f16 v[114:117], v[156:159], v[174:177], v[114:117]
	v_mfma_f32_16x16x32_f16 v[126:129], v[166:169], v[174:177], v[126:129]
	v_mfma_f32_16x16x32_f16 v[98:101], v[156:159], v[182:185], v[98:101]
	v_mfma_f32_16x16x32_f16 v[110:113], v[166:169], v[182:185], v[110:113]
	v_mfma_f32_16x16x32_f16 v[82:85], v[156:159], v[190:193], v[82:85]
	v_mfma_f32_16x16x32_f16 v[94:97], v[166:169], v[190:193], v[94:97]
	v_mfma_f32_16x16x32_f16 v[66:69], v[156:159], v[198:201], v[66:69]
	v_mfma_f32_16x16x32_f16 v[78:81], v[166:169], v[198:201], v[78:81]
	v_mfma_f32_16x16x32_f16 v[114:117], v[162:165], v[178:181], v[114:117]
	v_mfma_f32_16x16x32_f16 v[126:129], v[170:173], v[178:181], v[126:129]
	v_mfma_f32_16x16x32_f16 v[98:101], v[162:165], v[186:189], v[98:101]
	v_mfma_f32_16x16x32_f16 v[110:113], v[170:173], v[186:189], v[110:113]
	v_mfma_f32_16x16x32_f16 v[82:85], v[162:165], v[194:197], v[82:85]
	v_mfma_f32_16x16x32_f16 v[94:97], v[170:173], v[194:197], v[94:97]
	v_mfma_f32_16x16x32_f16 v[66:69], v[162:165], v[202:205], v[66:69]
	v_mfma_f32_16x16x32_f16 v[78:81], v[170:173], v[202:205], v[78:81]
	s_setprio 0
	s_barrier
; #define PG8_STAGE(bufoff, gbase, voff) do { _Pragma("unroll") for (int _i = 0; _i < 2; ++_i) \
;         __builtin_amdgcn_global_load_lds((const unsigned*)((const char*)(gbase) + (voff)[_i]), (LAS unsigned*)(lds + (bufoff) + ldsw + _i * 8192), 16, 0, 0); } while (0)
; #define PG8_LDA(dst, b, h) do { _Pragma("unroll") for (int m = 0; m < 4; ++m) _Pragma("unroll") for (int k = 0; k < 2; ++k) dst[m][k] = *(const LAS half8*)(lds + PG8_SA(b, h) + aoff + m * 2048 + k * 1024); } while (0)
; #define PG8_MMA(ai, bj, At, Bt) do { __builtin_amdgcn_s_setprio(1); _Pragma("unroll") for (int m = 0; m < 4; ++m) _Pragma("unroll") for (int n = 0; n < 2; ++n) _Pragma("unroll") for (int k = 0; k < 2; ++k) \
;         acc[ai][bj][m][n] = __builtin_amdgcn_mfma_f32_16x16x32_f16(Bt[n][k], At[m][k], acc[ai][bj][m][n], 0, 0, 0); __builtin_amdgcn_s_setprio(0); } while (0)
; #define PG8_WAIT_V(n) asm volatile("s_waitcnt vmcnt(" #n ")" ::: "memory")
; #define PG8_WAIT_L(n) asm volatile("s_waitcnt lgkmcnt(" #n ")" ::: "memory")
; #define PG8_BAR __builtin_amdgcn_s_barrier()
; #define PG8_SCHED __builtin_amdgcn_sched_barrier(0)
; template <class Epi>
; __device__ __forceinline__ void gemm_phase(LAS unsigned char* lds, const Gemm g, const StaticOrder& S, const Epi& E) {
;     ...
;             PG8_LDA(At, 1, 1); PG8_STAGE(PG8_SB(1, 0), b3, voffB); PG8_STAGE(PG8_SB(1, 1), b3 + hB, voffB); PG8_STAGE(PG8_SA(1, 0), a3, voffA);
;             PG8_WAIT_V(8); PG8_WAIT_L(0); PG8_BAR; PG8_MMA(1, 0, At, B0); PG8_MMA(1, 1, At, B1); PG8_BAR; PG8_SCHED;
;         }
	s_add_i32 s0, s11, s54
	v_lshl_add_u64 v[206:207], v[206:207], 0, s[92:93]
	s_mov_b32 m0, s0
	ds_read_b128 v[174:177], v228 offset:49152
	ds_read_b128 v[178:181], v228 offset:50176
	ds_read_b128 v[182:185], v228 offset:51200
	ds_read_b128 v[186:189], v228 offset:52224
	ds_read_b128 v[190:193], v228 offset:53248
	ds_read_b128 v[194:197], v228 offset:54272
	ds_read_b128 v[198:201], v228 offset:55296
	ds_read_b128 v[202:205], v228 offset:56320
	global_load_lds_dwordx4 v[206:207], off
	s_add_i32 m0, s0, 0x2000
	s_add_u32 s0, s18, 0xb0080
	v_lshl_add_u64 v[206:207], v[208:209], 0, s[92:93]
	s_addc_u32 s1, s19, 0
	s_add_i32 s11, s15, s54
	global_load_lds_dwordx4 v[206:207], off
	v_lshl_add_u64 v[206:207], s[0:1], 0, v[0:1]
	s_mov_b32 m0, s11
	s_nop 0
	global_load_lds_dwordx4 v[206:207], off
	v_lshl_add_u64 v[206:207], s[0:1], 0, v[134:135]
	s_add_i32 m0, s11, 0x2000
	s_nop 0
	global_load_lds_dwordx4 v[206:207], off
	v_lshl_add_u64 v[206:207], v[210:211], 0, s[92:93]
	s_mov_b32 m0, s61
	s_nop 0
	global_load_lds_dwordx4 v[206:207], off
	v_lshl_add_u64 v[206:207], v[212:213], 0, s[92:93]
	s_mov_b32 m0, s62
	s_nop 0
	global_load_lds_dwordx4 v[206:207], off
	s_waitcnt vmcnt(8)
	s_waitcnt lgkmcnt(0)
	s_barrier
	s_setprio 1
	s_waitcnt lgkmcnt(0)
	v_mfma_f32_16x16x32_f16 v[58:61], v[140:143], v[174:177], v[58:61]
	v_mfma_f32_16x16x32_f16 v[54:57], v[148:151], v[174:177], v[54:57]
	v_mfma_f32_16x16x32_f16 v[42:45], v[140:143], v[182:185], v[42:45]
	v_mfma_f32_16x16x32_f16 v[38:41], v[148:151], v[182:185], v[38:41]
	v_mfma_f32_16x16x32_f16 v[26:29], v[140:143], v[190:193], v[26:29]
	v_mfma_f32_16x16x32_f16 v[22:25], v[148:151], v[190:193], v[22:25]
	v_mfma_f32_16x16x32_f16 v[10:13], v[140:143], v[198:201], v[10:13]
	v_mfma_f32_16x16x32_f16 v[6:9], v[148:151], v[198:201], v[6:9]
	v_mfma_f32_16x16x32_f16 v[58:61], v[144:147], v[178:181], v[58:61]
	v_mfma_f32_16x16x32_f16 v[54:57], v[152:155], v[178:181], v[54:57]
	v_mfma_f32_16x16x32_f16 v[42:45], v[144:147], v[186:189], v[42:45]
	v_mfma_f32_16x16x32_f16 v[38:41], v[152:155], v[186:189], v[38:41]
	v_mfma_f32_16x16x32_f16 v[26:29], v[144:147], v[194:197], v[26:29]
	v_mfma_f32_16x16x32_f16 v[22:25], v[152:155], v[194:197], v[22:25]
	v_mfma_f32_16x16x32_f16 v[10:13], v[144:147], v[202:205], v[10:13]
	v_mfma_f32_16x16x32_f16 v[6:9], v[152:155], v[202:205], v[6:9]
	v_mfma_f32_16x16x32_f16 v[50:53], v[156:159], v[174:177], v[50:53]
	v_mfma_f32_16x16x32_f16 v[62:65], v[166:169], v[174:177], v[62:65]
	v_mfma_f32_16x16x32_f16 v[34:37], v[156:159], v[182:185], v[34:37]
	v_mfma_f32_16x16x32_f16 v[46:49], v[166:169], v[182:185], v[46:49]
	v_mfma_f32_16x16x32_f16 v[18:21], v[156:159], v[190:193], v[18:21]
	v_mfma_f32_16x16x32_f16 v[30:33], v[166:169], v[190:193], v[30:33]
	v_mfma_f32_16x16x32_f16 v[2:5], v[156:159], v[198:201], v[2:5]
	v_mfma_f32_16x16x32_f16 v[14:17], v[166:169], v[198:201], v[14:17]
	v_mfma_f32_16x16x32_f16 v[50:53], v[162:165], v[178:181], v[50:53]
	v_mfma_f32_16x16x32_f16 v[62:65], v[170:173], v[178:181], v[62:65]
	v_mfma_f32_16x16x32_f16 v[34:37], v[162:165], v[186:189], v[34:37]
	v_mfma_f32_16x16x32_f16 v[46:49], v[170:173], v[186:189], v[46:49]
	v_mfma_f32_16x16x32_f16 v[18:21], v[162:165], v[194:197], v[18:21]
	v_mfma_f32_16x16x32_f16 v[30:33], v[170:173], v[194:197], v[30:33]
	v_mfma_f32_16x16x32_f16 v[2:5], v[162:165], v[202:205], v[2:5]
	v_mfma_f32_16x16x32_f16 v[14:17], v[170:173], v[202:205], v[14:17]
	s_setprio 0
	s_barrier
	s_add_u32 s2, s2, 0x100
	s_addc_u32 s3, s3, 0
	s_cmp_ge_i32 s14, s23
	s_mov_b64 s[0:1], s[16:17]
	s_mov_b32 s11, s14
	s_cbranch_scc0 .LBB0_158
	s_and_b64 vcc, exec, s[46:47]
	s_cbranch_vccz .LBB0_161

; #define PG8_STAGE(bufoff, gbase, voff) do { _Pragma("unroll") for (int _i = 0; _i < 2; ++_i) \
;         __builtin_amdgcn_global_load_lds((const unsigned*)((const char*)(gbase) + (voff)[_i]), (LAS unsigned*)(lds + (bufoff) + ldsw + _i * 8192), 16, 0, 0); } while (0)
; #define PG8_LDA(dst, b, h) do { _Pragma("unroll") for (int m = 0; m < 4; ++m) _Pragma("unroll") for (int k = 0; k < 2; ++k) dst[m][k] = *(const LAS half8*)(lds + PG8_SA(b, h) + aoff + m * 2048 + k * 1024); } while (0)
; #define PG8_LDB(dst, b, h) do { _Pragma("unroll") for (int n = 0; n < 2; ++n) _Pragma("unroll") for (int k = 0; k < 2; ++k) dst[n][k] = *(const LAS half8*)(lds + PG8_SB(b, h) + boff + n * 2048 + k * 1024); } while (0)
; #define PG8_MMA(ai, bj, At, Bt) do { __builtin_amdgcn_s_setprio(1); _Pragma("unroll") for (int m = 0; m < 4; ++m) _Pragma("unroll") for (int n = 0; n < 2; ++n) _Pragma("unroll") for (int k = 0; k < 2; ++k) \
;         acc[ai][bj][m][n] = __builtin_amdgcn_mfma_f32_16x16x32_f16(Bt[n][k], At[m][k], acc[ai][bj][m][n], 0, 0, 0); __builtin_amdgcn_s_setprio(0); } while (0)
; #define PG8_WAIT_V(n) asm volatile("s_waitcnt vmcnt(" #n ")" ::: "memory")
; #define PG8_WAIT_L(n) asm volatile("s_waitcnt lgkmcnt(" #n ")" ::: "memory")
; #define PG8_BAR __builtin_amdgcn_s_barrier()
; #define PG8_SCHED __builtin_amdgcn_sched_barrier(0)
; template <class Epi>
; __device__ __forceinline__ void gemm_phase(LAS unsigned char* lds, const Gemm g, const StaticOrder& S, const Epi& E) {
;     ...
;         for (int t = 0; t < nt; t += 2) {
;             const bool last = (t == nt - 2);
;             const char* a1 = cA + (size_t)(t + 1) * kstep;
;             const char* a2 = last ? nA : cA + (size_t)(t + 2) * kstep; const char* b2 = last ? nB : cB + (size_t)(t + 2) * kstep;
;             const char* a3 = a2 + kstep; const char* b3 = b2 + kstep;
;             PG8_LDB(B0, 0, 0); PG8_LDB(B1, 0, 1); PG8_SCHED; PG8_LDA(At, 0, 0); PG8_STAGE(PG8_SA(1, 1), a1 + hA, voffA);
;             PG8_WAIT_V(8); PG8_WAIT_L(0); PG8_BAR; PG8_MMA(0, 0, At, B0); PG8_MMA(0, 1, At, B1); PG8_BAR; PG8_SCHED;
;             PG8_LDA(At, 0, 1); PG8_STAGE(PG8_SB(0, 0), b2, voffB); PG8_STAGE(PG8_SB(0, 1), b2 + hB, voffB); PG8_STAGE(PG8_SA(0, 0), a2, voffA);
;             PG8_WAIT_V(8); PG8_WAIT_L(0); PG8_BAR; PG8_MMA(1, 0, At, B0); PG8_MMA(1, 1, At, B1); PG8_BAR; PG8_SCHED;
.LBB0_337:
	s_add_i32 s22, s21, 2
	s_add_u32 s26, s42, 0xfffc0080
	s_addc_u32 s27, s43, -1
	s_add_i32 s28, 0, 0x10000
	s_cmp_eq_u32 s58, s21
	s_cselect_b32 s47, s3, s27
	s_cselect_b32 s46, s11, s26
	v_add_u32_e32 v0, s28, v142
	s_cselect_b32 s45, s14, s20
	s_cselect_b32 s44, s15, s17
	s_add_i32 s21, 0, 0x14000
	ds_read_b128 v[144:147], v0
	ds_read_b128 v[148:151], v0 offset:1024
	ds_read_b128 v[152:155], v0 offset:2048
	ds_read_b128 v[156:159], v0 offset:3072
	v_add_u32_e32 v0, s21, v142
	ds_read_b128 v[162:165], v0
	ds_read_b128 v[166:169], v0 offset:1024
	ds_read_b128 v[170:173], v0 offset:2048
	ds_read_b128 v[174:177], v0 offset:3072
	v_lshl_add_u64 v[210:211], s[42:43], 0, v[140:141]
	s_add_i32 m0, s51, 0xc000
	ds_read_b128 v[178:181], v143
	ds_read_b128 v[182:185], v143 offset:1024
	ds_read_b128 v[186:189], v143 offset:2048
	ds_read_b128 v[190:193], v143 offset:3072
	ds_read_b128 v[194:197], v143 offset:4096
	ds_read_b128 v[198:201], v143 offset:5120
	ds_read_b128 v[202:205], v143 offset:6144
	ds_read_b128 v[206:209], v143 offset:7168
	global_load_lds_dwordx4 v[210:211], off
	v_lshl_add_u64 v[210:211], s[42:43], 0, v[138:139]
	s_add_i32 m0, s51, 0xe000
	s_nop 0
	global_load_lds_dwordx4 v[210:211], off
	s_waitcnt vmcnt(8)
	s_waitcnt lgkmcnt(0)
	s_barrier
	s_setprio 1
	s_waitcnt lgkmcnt(0)
	v_mfma_f32_16x16x32_f16 v[126:129], v[144:147], v[178:181], v[126:129]
	v_mfma_f32_16x16x32_f16 v[118:121], v[152:155], v[178:181], v[118:121]
	v_mfma_f32_16x16x32_f16 v[110:113], v[144:147], v[186:189], v[110:113]
	v_mfma_f32_16x16x32_f16 v[102:105], v[152:155], v[186:189], v[102:105]
	v_mfma_f32_16x16x32_f16 v[94:97], v[144:147], v[194:197], v[94:97]
	v_mfma_f32_16x16x32_f16 v[86:89], v[152:155], v[194:197], v[86:89]
	v_mfma_f32_16x16x32_f16 v[78:81], v[144:147], v[202:205], v[78:81]
	v_mfma_f32_16x16x32_f16 v[70:73], v[152:155], v[202:205], v[70:73]
	v_mfma_f32_16x16x32_f16 v[126:129], v[148:151], v[182:185], v[126:129]
	v_mfma_f32_16x16x32_f16 v[118:121], v[156:159], v[182:185], v[118:121]
	v_mfma_f32_16x16x32_f16 v[110:113], v[148:151], v[190:193], v[110:113]
	v_mfma_f32_16x16x32_f16 v[102:105], v[156:159], v[190:193], v[102:105]
	v_mfma_f32_16x16x32_f16 v[94:97], v[148:151], v[198:201], v[94:97]
	v_mfma_f32_16x16x32_f16 v[86:89], v[156:159], v[198:201], v[86:89]
	v_mfma_f32_16x16x32_f16 v[78:81], v[148:151], v[206:209], v[78:81]
	v_mfma_f32_16x16x32_f16 v[70:73], v[156:159], v[206:209], v[70:73]
	v_mfma_f32_16x16x32_f16 v[122:125], v[162:165], v[178:181], v[122:125]
	v_mfma_f32_16x16x32_f16 v[114:117], v[170:173], v[178:181], v[114:117]
	v_mfma_f32_16x16x32_f16 v[106:109], v[162:165], v[186:189], v[106:109]
	v_mfma_f32_16x16x32_f16 v[98:101], v[170:173], v[186:189], v[98:101]
	v_mfma_f32_16x16x32_f16 v[90:93], v[162:165], v[194:197], v[90:93]
	v_mfma_f32_16x16x32_f16 v[82:85], v[170:173], v[194:197], v[82:85]
	v_mfma_f32_16x16x32_f16 v[74:77], v[162:165], v[202:205], v[74:77]
	v_mfma_f32_16x16x32_f16 v[66:69], v[170:173], v[202:205], v[66:69]
	v_mfma_f32_16x16x32_f16 v[122:125], v[166:169], v[182:185], v[122:125]
	v_mfma_f32_16x16x32_f16 v[114:117], v[174:177], v[182:185], v[114:117]
	v_mfma_f32_16x16x32_f16 v[106:109], v[166:169], v[190:193], v[106:109]
	v_mfma_f32_16x16x32_f16 v[98:101], v[174:177], v[190:193], v[98:101]
	v_mfma_f32_16x16x32_f16 v[90:93], v[166:169], v[198:201], v[90:93]
	v_mfma_f32_16x16x32_f16 v[82:85], v[174:177], v[198:201], v[82:85]
	v_mfma_f32_16x16x32_f16 v[74:77], v[166:169], v[206:209], v[74:77]
	v_mfma_f32_16x16x32_f16 v[66:69], v[174:177], v[206:209], v[66:69]
	s_setprio 0
	s_barrier
	s_add_i32 s26, s28, s50
	v_lshl_add_u64 v[210:211], s[44:45], 0, v[134:135]
	s_mov_b32 m0, s26
	ds_read_b128 v[178:181], v143 offset:16384
	ds_read_b128 v[182:185], v143 offset:17408
	ds_read_b128 v[186:189], v143 offset:18432
	ds_read_b128 v[190:193], v143 offset:19456
	ds_read_b128 v[194:197], v143 offset:20480
	ds_read_b128 v[198:201], v143 offset:21504
	ds_read_b128 v[202:205], v143 offset:22528
	ds_read_b128 v[206:209], v143 offset:23552
	global_load_lds_dwordx4 v[210:211], off
	s_add_i32 m0, s26, 0x2000
	s_add_u32 s26, s44, 0x40000
	v_lshl_add_u64 v[212:213], s[44:45], 0, v[130:131]
	s_addc_u32 s27, s45, 0
	s_add_i32 s21, s21, s50
	global_load_lds_dwordx4 v[212:213], off
	v_lshl_add_u64 v[214:215], s[26:27], 0, v[134:135]
	s_mov_b32 m0, s21
	v_lshl_add_u64 v[218:219], s[46:47], 0, v[132:133]
	global_load_lds_dwordx4 v[214:215], off
	v_lshl_add_u64 v[214:215], s[26:27], 0, v[130:131]
	s_add_i32 m0, s21, 0x2000
	s_nop 0
	global_load_lds_dwordx4 v[214:215], off
	v_lshl_add_u64 v[214:215], s[46:47], 0, v[136:137]
	s_mov_b32 m0, s51
	s_nop 0
	global_load_lds_dwordx4 v[214:215], off
	s_mov_b32 m0, s52
	s_nop 0
	global_load_lds_dwordx4 v[218:219], off
	s_waitcnt vmcnt(8)
	s_waitcnt lgkmcnt(0)
	s_barrier
; #define PG8_STAGE(bufoff, gbase, voff) do { _Pragma("unroll") for (int _i = 0; _i < 2; ++_i) \
;         __builtin_amdgcn_global_load_lds((const unsigned*)((const char*)(gbase) + (voff)[_i]), (LAS unsigned*)(lds + (bufoff) + ldsw + _i * 8192), 16, 0, 0); } while (0)
; #define PG8_LDA(dst, b, h) do { _Pragma("unroll") for (int m = 0; m < 4; ++m) _Pragma("unroll") for (int k = 0; k < 2; ++k) dst[m][k] = *(const LAS half8*)(lds + PG8_SA(b, h) + aoff + m * 2048 + k * 1024); } while (0)
; #define PG8_LDB(dst, b, h) do { _Pragma("unroll") for (int n = 0; n < 2; ++n) _Pragma("unroll") for (int k = 0; k < 2; ++k) dst[n][k] = *(const LAS half8*)(lds + PG8_SB(b, h) + boff + n * 2048 + k * 1024); } while (0)
; #define PG8_MMA(ai, bj, At, Bt) do { __builtin_amdgcn_s_setprio(1); _Pragma("unroll") for (int m = 0; m < 4; ++m) _Pragma("unroll") for (int n = 0; n < 2; ++n) _Pragma("unroll") for (int k = 0; k < 2; ++k) \
;         acc[ai][bj][m][n] = __builtin_amdgcn_mfma_f32_16x16x32_f16(Bt[n][k], At[m][k], acc[ai][bj][m][n], 0, 0, 0); __builtin_amdgcn_s_setprio(0); } while (0)
; #define PG8_WAIT_V(n) asm volatile("s_waitcnt vmcnt(" #n ")" ::: "memory")
; #define PG8_WAIT_L(n) asm volatile("s_waitcnt lgkmcnt(" #n ")" ::: "memory")
; #define PG8_BAR __builtin_amdgcn_s_barrier()
; #define PG8_SCHED __builtin_amdgcn_sched_barrier(0)
; template <class Epi>
; __device__ __forceinline__ void gemm_phase(LAS unsigned char* lds, const Gemm g, const StaticOrder& S, const Epi& E) {
;     ...
;             PG8_WAIT_V(8); PG8_WAIT_L(0); PG8_BAR; PG8_MMA(1, 0, At, B0); PG8_MMA(1, 1, At, B1); PG8_BAR; PG8_SCHED;
;             PG8_LDB(B0, 1, 0); PG8_LDB(B1, 1, 1); PG8_SCHED; PG8_LDA(At, 1, 0); PG8_STAGE(PG8_SA(0, 1), a2 + hA, voffA);
;             PG8_WAIT_V(8); PG8_WAIT_L(0); PG8_BAR; PG8_MMA(0, 0, At, B0); PG8_MMA(0, 1, At, B1); PG8_BAR; PG8_SCHED;
	s_setprio 1
	s_waitcnt lgkmcnt(0)
	v_mfma_f32_16x16x32_f16 v[62:65], v[144:147], v[178:181], v[62:65]
	v_mfma_f32_16x16x32_f16 v[54:57], v[152:155], v[178:181], v[54:57]
	v_mfma_f32_16x16x32_f16 v[46:49], v[144:147], v[186:189], v[46:49]
	v_mfma_f32_16x16x32_f16 v[38:41], v[152:155], v[186:189], v[38:41]
	v_mfma_f32_16x16x32_f16 v[30:33], v[144:147], v[194:197], v[30:33]
	v_mfma_f32_16x16x32_f16 v[22:25], v[152:155], v[194:197], v[22:25]
	v_mfma_f32_16x16x32_f16 v[14:17], v[144:147], v[202:205], v[14:17]
	v_mfma_f32_16x16x32_f16 v[6:9], v[152:155], v[202:205], v[6:9]
	v_mfma_f32_16x16x32_f16 v[62:65], v[148:151], v[182:185], v[62:65]
	v_mfma_f32_16x16x32_f16 v[54:57], v[156:159], v[182:185], v[54:57]
	v_mfma_f32_16x16x32_f16 v[46:49], v[148:151], v[190:193], v[46:49]
	v_mfma_f32_16x16x32_f16 v[38:41], v[156:159], v[190:193], v[38:41]
	v_mfma_f32_16x16x32_f16 v[30:33], v[148:151], v[198:201], v[30:33]
	v_mfma_f32_16x16x32_f16 v[22:25], v[156:159], v[198:201], v[22:25]
	v_mfma_f32_16x16x32_f16 v[14:17], v[148:151], v[206:209], v[14:17]
	v_mfma_f32_16x16x32_f16 v[6:9], v[156:159], v[206:209], v[6:9]
	v_mfma_f32_16x16x32_f16 v[58:61], v[162:165], v[178:181], v[58:61]
	v_mfma_f32_16x16x32_f16 v[50:53], v[170:173], v[178:181], v[50:53]
	v_mfma_f32_16x16x32_f16 v[42:45], v[162:165], v[186:189], v[42:45]
	v_mfma_f32_16x16x32_f16 v[34:37], v[170:173], v[186:189], v[34:37]
	v_mfma_f32_16x16x32_f16 v[26:29], v[162:165], v[194:197], v[26:29]
	v_mfma_f32_16x16x32_f16 v[18:21], v[170:173], v[194:197], v[18:21]
	v_mfma_f32_16x16x32_f16 v[10:13], v[162:165], v[202:205], v[10:13]
	v_mfma_f32_16x16x32_f16 v[2:5], v[170:173], v[202:205], v[2:5]
	v_mfma_f32_16x16x32_f16 v[58:61], v[166:169], v[182:185], v[58:61]
	v_mfma_f32_16x16x32_f16 v[50:53], v[174:177], v[182:185], v[50:53]
	v_mfma_f32_16x16x32_f16 v[42:45], v[166:169], v[190:193], v[42:45]
	v_mfma_f32_16x16x32_f16 v[34:37], v[174:177], v[190:193], v[34:37]
	v_mfma_f32_16x16x32_f16 v[26:29], v[166:169], v[198:201], v[26:29]
	v_mfma_f32_16x16x32_f16 v[18:21], v[174:177], v[198:201], v[18:21]
	v_mfma_f32_16x16x32_f16 v[10:13], v[166:169], v[206:209], v[10:13]
	v_mfma_f32_16x16x32_f16 v[2:5], v[174:177], v[206:209], v[2:5]
	s_setprio 0
	s_barrier
	s_add_i32 s21, 0, 0x18000
	v_add_u32_e32 v0, s21, v142
	s_add_i32 s28, 0, 0x1c000
	ds_read_b128 v[144:147], v0
	ds_read_b128 v[148:151], v0 offset:1024
	ds_read_b128 v[152:155], v0 offset:2048
	ds_read_b128 v[156:159], v0 offset:3072
	v_add_u32_e32 v0, s28, v142
	ds_read_b128 v[162:165], v0
	ds_read_b128 v[166:169], v0 offset:1024
	ds_read_b128 v[170:173], v0 offset:2048
	ds_read_b128 v[174:177], v0 offset:3072
	s_add_u32 s26, s46, 0x40000
	s_addc_u32 s27, s47, 0
	s_mov_b32 m0, s53
	v_lshl_add_u64 v[220:221], s[26:27], 0, v[136:137]
	ds_read_b128 v[178:181], v143 offset:32768
	ds_read_b128 v[182:185], v143 offset:33792
	ds_read_b128 v[186:189], v143 offset:34816
	ds_read_b128 v[190:193], v143 offset:35840
	ds_read_b128 v[194:197], v143 offset:36864
	ds_read_b128 v[198:201], v143 offset:37888
	ds_read_b128 v[202:205], v143 offset:38912
	ds_read_b128 v[206:209], v143 offset:39936
	global_load_lds_dwordx4 v[220:221], off
	v_lshl_add_u64 v[220:221], s[26:27], 0, v[132:133]
	s_mov_b32 m0, s54
	s_nop 0
	global_load_lds_dwordx4 v[220:221], off
	s_waitcnt vmcnt(8)
	s_waitcnt lgkmcnt(0)
	s_barrier
	s_setprio 1
	s_waitcnt lgkmcnt(0)
	v_mfma_f32_16x16x32_f16 v[126:129], v[144:147], v[178:181], v[126:129]
	v_mfma_f32_16x16x32_f16 v[118:121], v[152:155], v[178:181], v[118:121]
	v_mfma_f32_16x16x32_f16 v[110:113], v[144:147], v[186:189], v[110:113]
	v_mfma_f32_16x16x32_f16 v[102:105], v[152:155], v[186:189], v[102:105]
	v_mfma_f32_16x16x32_f16 v[94:97], v[144:147], v[194:197], v[94:97]
	v_mfma_f32_16x16x32_f16 v[86:89], v[152:155], v[194:197], v[86:89]
	v_mfma_f32_16x16x32_f16 v[78:81], v[144:147], v[202:205], v[78:81]
	v_mfma_f32_16x16x32_f16 v[70:73], v[152:155], v[202:205], v[70:73]
	v_mfma_f32_16x16x32_f16 v[126:129], v[148:151], v[182:185], v[126:129]
	v_mfma_f32_16x16x32_f16 v[118:121], v[156:159], v[182:185], v[118:121]
	v_mfma_f32_16x16x32_f16 v[110:113], v[148:151], v[190:193], v[110:113]
	v_mfma_f32_16x16x32_f16 v[102:105], v[156:159], v[190:193], v[102:105]
	v_mfma_f32_16x16x32_f16 v[94:97], v[148:151], v[198:201], v[94:97]
	v_mfma_f32_16x16x32_f16 v[86:89], v[156:159], v[198:201], v[86:89]
	v_mfma_f32_16x16x32_f16 v[78:81], v[148:151], v[206:209], v[78:81]
	v_mfma_f32_16x16x32_f16 v[70:73], v[156:159], v[206:209], v[70:73]
	v_mfma_f32_16x16x32_f16 v[122:125], v[162:165], v[178:181], v[122:125]
	v_mfma_f32_16x16x32_f16 v[114:117], v[170:173], v[178:181], v[114:117]
	v_mfma_f32_16x16x32_f16 v[106:109], v[162:165], v[186:189], v[106:109]
	v_mfma_f32_16x16x32_f16 v[98:101], v[170:173], v[186:189], v[98:101]
	v_mfma_f32_16x16x32_f16 v[90:93], v[162:165], v[194:197], v[90:93]
	v_mfma_f32_16x16x32_f16 v[82:85], v[170:173], v[194:197], v[82:85]
	v_mfma_f32_16x16x32_f16 v[74:77], v[162:165], v[202:205], v[74:77]
	v_mfma_f32_16x16x32_f16 v[66:69], v[170:173], v[202:205], v[66:69]
	v_mfma_f32_16x16x32_f16 v[122:125], v[166:169], v[182:185], v[122:125]
	v_mfma_f32_16x16x32_f16 v[114:117], v[174:177], v[182:185], v[114:117]
	v_mfma_f32_16x16x32_f16 v[106:109], v[166:169], v[190:193], v[106:109]
	v_mfma_f32_16x16x32_f16 v[98:101], v[174:177], v[190:193], v[98:101]
	v_mfma_f32_16x16x32_f16 v[90:93], v[166:169], v[198:201], v[90:93]
	v_mfma_f32_16x16x32_f16 v[82:85], v[174:177], v[198:201], v[82:85]
	v_mfma_f32_16x16x32_f16 v[74:77], v[166:169], v[206:209], v[74:77]
	v_mfma_f32_16x16x32_f16 v[66:69], v[174:177], v[206:209], v[66:69]
	s_setprio 0
	s_barrier
; #define PG8_STAGE(bufoff, gbase, voff) do { _Pragma("unroll") for (int _i = 0; _i < 2; ++_i) \
;         __builtin_amdgcn_global_load_lds((const unsigned*)((const char*)(gbase) + (voff)[_i]), (LAS unsigned*)(lds + (bufoff) + ldsw + _i * 8192), 16, 0, 0); } while (0)
; #define PG8_LDA(dst, b, h) do { _Pragma("unroll") for (int m = 0; m < 4; ++m) _Pragma("unroll") for (int k = 0; k < 2; ++k) dst[m][k] = *(const LAS half8*)(lds + PG8_SA(b, h) + aoff + m * 2048 + k * 1024); } while (0)
; #define PG8_MMA(ai, bj, At, Bt) do { __builtin_amdgcn_s_setprio(1); _Pragma("unroll") for (int m = 0; m < 4; ++m) _Pragma("unroll") for (int n = 0; n < 2; ++n) _Pragma("unroll") for (int k = 0; k < 2; ++k) \
;         acc[ai][bj][m][n] = __builtin_amdgcn_mfma_f32_16x16x32_f16(Bt[n][k], At[m][k], acc[ai][bj][m][n], 0, 0, 0); __builtin_amdgcn_s_setprio(0); } while (0)
; #define PG8_WAIT_V(n) asm volatile("s_waitcnt vmcnt(" #n ")" ::: "memory")
; #define PG8_WAIT_L(n) asm volatile("s_waitcnt lgkmcnt(" #n ")" ::: "memory")
; #define PG8_BAR __builtin_amdgcn_s_barrier()
; #define PG8_SCHED __builtin_amdgcn_sched_barrier(0)
; template <class Epi>
; __device__ __forceinline__ void gemm_phase(LAS unsigned char* lds, const Gemm g, const StaticOrder& S, const Epi& E) {
;     ...
;             PG8_LDA(At, 1, 1); PG8_STAGE(PG8_SB(1, 0), b3, voffB); PG8_STAGE(PG8_SB(1, 1), b3 + hB, voffB); PG8_STAGE(PG8_SA(1, 0), a3, voffA);
;             PG8_WAIT_V(8); PG8_WAIT_L(0); PG8_BAR; PG8_MMA(1, 0, At, B0); PG8_MMA(1, 1, At, B1); PG8_BAR; PG8_SCHED;
;         }
	s_add_i32 s21, s21, s50
	v_lshl_add_u64 v[210:211], v[210:211], 0, s[92:93]
	s_mov_b32 m0, s21
	ds_read_b128 v[178:181], v143 offset:49152
	ds_read_b128 v[182:185], v143 offset:50176
	ds_read_b128 v[186:189], v143 offset:51200
	ds_read_b128 v[190:193], v143 offset:52224
	ds_read_b128 v[194:197], v143 offset:53248
	ds_read_b128 v[198:201], v143 offset:54272
	ds_read_b128 v[202:205], v143 offset:55296
	ds_read_b128 v[206:209], v143 offset:56320
	global_load_lds_dwordx4 v[210:211], off
	s_add_i32 m0, s21, 0x2000
	s_add_u32 s26, s44, 0x40080
	v_lshl_add_u64 v[210:211], v[212:213], 0, s[92:93]
	s_addc_u32 s27, s45, 0
	s_add_i32 s21, s28, s50
	global_load_lds_dwordx4 v[210:211], off
	v_lshl_add_u64 v[210:211], s[26:27], 0, v[134:135]
	s_mov_b32 m0, s21
	s_nop 0
	global_load_lds_dwordx4 v[210:211], off
	v_lshl_add_u64 v[210:211], s[26:27], 0, v[130:131]
	s_add_i32 m0, s21, 0x2000
	s_nop 0
	global_load_lds_dwordx4 v[210:211], off
	v_lshl_add_u64 v[210:211], v[214:215], 0, s[92:93]
	s_mov_b32 m0, s55
	s_nop 0
	global_load_lds_dwordx4 v[210:211], off
	v_lshl_add_u64 v[210:211], v[218:219], 0, s[92:93]
	s_mov_b32 m0, s56
	s_nop 0
	global_load_lds_dwordx4 v[210:211], off
	s_waitcnt vmcnt(8)
	s_waitcnt lgkmcnt(0)
	s_barrier
	s_setprio 1
	s_waitcnt lgkmcnt(0)
	v_mfma_f32_16x16x32_f16 v[62:65], v[144:147], v[178:181], v[62:65]
	v_mfma_f32_16x16x32_f16 v[54:57], v[152:155], v[178:181], v[54:57]
	v_mfma_f32_16x16x32_f16 v[46:49], v[144:147], v[186:189], v[46:49]
	v_mfma_f32_16x16x32_f16 v[38:41], v[152:155], v[186:189], v[38:41]
	v_mfma_f32_16x16x32_f16 v[30:33], v[144:147], v[194:197], v[30:33]
	v_mfma_f32_16x16x32_f16 v[22:25], v[152:155], v[194:197], v[22:25]
	v_mfma_f32_16x16x32_f16 v[14:17], v[144:147], v[202:205], v[14:17]
	v_mfma_f32_16x16x32_f16 v[6:9], v[152:155], v[202:205], v[6:9]
	v_mfma_f32_16x16x32_f16 v[62:65], v[148:151], v[182:185], v[62:65]
	v_mfma_f32_16x16x32_f16 v[54:57], v[156:159], v[182:185], v[54:57]
	v_mfma_f32_16x16x32_f16 v[46:49], v[148:151], v[190:193], v[46:49]
	v_mfma_f32_16x16x32_f16 v[38:41], v[156:159], v[190:193], v[38:41]
	v_mfma_f32_16x16x32_f16 v[30:33], v[148:151], v[198:201], v[30:33]
	v_mfma_f32_16x16x32_f16 v[22:25], v[156:159], v[198:201], v[22:25]
	v_mfma_f32_16x16x32_f16 v[14:17], v[148:151], v[206:209], v[14:17]
	v_mfma_f32_16x16x32_f16 v[6:9], v[156:159], v[206:209], v[6:9]
	v_mfma_f32_16x16x32_f16 v[58:61], v[162:165], v[178:181], v[58:61]
	v_mfma_f32_16x16x32_f16 v[50:53], v[170:173], v[178:181], v[50:53]
	v_mfma_f32_16x16x32_f16 v[42:45], v[162:165], v[186:189], v[42:45]
	v_mfma_f32_16x16x32_f16 v[34:37], v[170:173], v[186:189], v[34:37]
	v_mfma_f32_16x16x32_f16 v[26:29], v[162:165], v[194:197], v[26:29]
	v_mfma_f32_16x16x32_f16 v[18:21], v[170:173], v[194:197], v[18:21]
	v_mfma_f32_16x16x32_f16 v[10:13], v[162:165], v[202:205], v[10:13]
	v_mfma_f32_16x16x32_f16 v[2:5], v[170:173], v[202:205], v[2:5]
	v_mfma_f32_16x16x32_f16 v[58:61], v[166:169], v[182:185], v[58:61]
	v_mfma_f32_16x16x32_f16 v[50:53], v[174:177], v[182:185], v[50:53]
	v_mfma_f32_16x16x32_f16 v[42:45], v[166:169], v[190:193], v[42:45]
	v_mfma_f32_16x16x32_f16 v[34:37], v[174:177], v[190:193], v[34:37]
	v_mfma_f32_16x16x32_f16 v[26:29], v[166:169], v[198:201], v[26:29]
	v_mfma_f32_16x16x32_f16 v[18:21], v[174:177], v[198:201], v[18:21]
	v_mfma_f32_16x16x32_f16 v[10:13], v[166:169], v[206:209], v[10:13]
	v_mfma_f32_16x16x32_f16 v[2:5], v[174:177], v[206:209], v[2:5]
	s_setprio 0
	s_barrier
	s_add_u32 s17, s17, 0x100
	s_addc_u32 s20, s20, 0
	s_add_u32 s42, s42, 0x100
	s_addc_u32 s43, s43, 0
	s_cmp_ge_i32 s22, s23
	s_mov_b32 s21, s22
	s_cbranch_scc0 .LBB0_337
	s_and_b64 vcc, exec, s[8:9]
	s_cbranch_vccz .LBB0_340

; #define PG8_STAGE(bufoff, gbase, voff) do { _Pragma("unroll") for (int _i = 0; _i < 2; ++_i) \
;         __builtin_amdgcn_global_load_lds((const unsigned*)((const char*)(gbase) + (voff)[_i]), (LAS unsigned*)(lds + (bufoff) + ldsw + _i * 8192), 16, 0, 0); } while (0)
; #define PG8_LDA(dst, b, h) do { _Pragma("unroll") for (int m = 0; m < 4; ++m) _Pragma("unroll") for (int k = 0; k < 2; ++k) dst[m][k] = *(const LAS half8*)(lds + PG8_SA(b, h) + aoff + m * 2048 + k * 1024); } while (0)
; #define PG8_LDB(dst, b, h) do { _Pragma("unroll") for (int n = 0; n < 2; ++n) _Pragma("unroll") for (int k = 0; k < 2; ++k) dst[n][k] = *(const LAS half8*)(lds + PG8_SB(b, h) + boff + n * 2048 + k * 1024); } while (0)
; #define PG8_MMA(ai, bj, At, Bt) do { __builtin_amdgcn_s_setprio(1); _Pragma("unroll") for (int m = 0; m < 4; ++m) _Pragma("unroll") for (int n = 0; n < 2; ++n) _Pragma("unroll") for (int k = 0; k < 2; ++k) \
;         acc[ai][bj][m][n] = __builtin_amdgcn_mfma_f32_16x16x32_f16(Bt[n][k], At[m][k], acc[ai][bj][m][n], 0, 0, 0); __builtin_amdgcn_s_setprio(0); } while (0)
; #define PG8_WAIT_V(n) asm volatile("s_waitcnt vmcnt(" #n ")" ::: "memory")
; #define PG8_WAIT_L(n) asm volatile("s_waitcnt lgkmcnt(" #n ")" ::: "memory")
; #define PG8_BAR __builtin_amdgcn_s_barrier()
; #define PG8_SCHED __builtin_amdgcn_sched_barrier(0)
; template <class Epi>
; __device__ __forceinline__ void gemm_phase(LAS unsigned char* lds, const Gemm g, const StaticOrder& S, const Epi& E) {
;     ...
;         for (int t = 0; t < nt; t += 2) {
;             const bool last = (t == nt - 2);
;             const char* a1 = cA + (size_t)(t + 1) * kstep;
;             const char* a2 = last ? nA : cA + (size_t)(t + 2) * kstep; const char* b2 = last ? nB : cB + (size_t)(t + 2) * kstep;
;             const char* a3 = a2 + kstep; const char* b3 = b2 + kstep;
;             PG8_LDB(B0, 0, 0); PG8_LDB(B1, 0, 1); PG8_SCHED; PG8_LDA(At, 0, 0); PG8_STAGE(PG8_SA(1, 1), a1 + hA, voffA);
;             PG8_WAIT_V(8); PG8_WAIT_L(0); PG8_BAR; PG8_MMA(0, 0, At, B0); PG8_MMA(0, 1, At, B1); PG8_BAR; PG8_SCHED;
;             PG8_LDA(At, 0, 1); PG8_STAGE(PG8_SB(0, 0), b2, voffB); PG8_STAGE(PG8_SB(0, 1), b2 + hB, voffB); PG8_STAGE(PG8_SA(0, 0), a2, voffA);
;             PG8_WAIT_V(8); PG8_WAIT_L(0); PG8_BAR; PG8_MMA(1, 0, At, B0); PG8_MMA(1, 1, At, B1); PG8_BAR; PG8_SCHED;
.LBB0_379:
	s_add_i32 s21, s20, 2
	s_add_u32 s22, s0, 0xfffc0080
	s_addc_u32 s24, s1, -1
	s_add_i32 s26, 0, 0x10000
	s_cmp_eq_u32 s64, s20
	s_cselect_b32 s53, s2, s24
	s_cselect_b32 s52, s3, s22
	s_cselect_b32 s25, s11, s17
	s_cselect_b32 s24, s14, s15
	s_add_i32 s20, 0, 0x14000
	v_add_u32_e32 v152, s26, v161
	v_add_u32_e32 v170, s20, v161
	ds_read_b128 v[140:143], v152
	ds_read_b128 v[144:147], v152 offset:1024
	ds_read_b128 v[148:151], v152 offset:2048
	ds_read_b128 v[152:155], v152 offset:3072
	ds_read_b128 v[156:159], v170
	ds_read_b128 v[162:165], v170 offset:1024
	ds_read_b128 v[166:169], v170 offset:2048
	ds_read_b128 v[170:173], v170 offset:3072
	v_lshl_add_u64 v[206:207], s[0:1], 0, v[138:139]
	s_add_i32 m0, s57, 0xc000
	ds_read_b128 v[174:177], v228
	ds_read_b128 v[178:181], v228 offset:1024
	ds_read_b128 v[182:185], v228 offset:2048
	ds_read_b128 v[186:189], v228 offset:3072
	ds_read_b128 v[190:193], v228 offset:4096
	ds_read_b128 v[194:197], v228 offset:5120
	ds_read_b128 v[198:201], v228 offset:6144
	ds_read_b128 v[202:205], v228 offset:7168
	global_load_lds_dwordx4 v[206:207], off
	v_lshl_add_u64 v[206:207], s[0:1], 0, v[136:137]
	s_add_i32 m0, s57, 0xe000
	s_nop 0
	global_load_lds_dwordx4 v[206:207], off
	s_waitcnt vmcnt(8)
	s_waitcnt lgkmcnt(0)
	s_barrier
	s_setprio 1
	s_waitcnt lgkmcnt(0)
	v_mfma_f32_16x16x32_f16 v[122:125], v[140:143], v[174:177], v[122:125]
	v_mfma_f32_16x16x32_f16 v[118:121], v[148:151], v[174:177], v[118:121]
	v_mfma_f32_16x16x32_f16 v[106:109], v[140:143], v[182:185], v[106:109]
	v_mfma_f32_16x16x32_f16 v[102:105], v[148:151], v[182:185], v[102:105]
	v_mfma_f32_16x16x32_f16 v[90:93], v[140:143], v[190:193], v[90:93]
	v_mfma_f32_16x16x32_f16 v[86:89], v[148:151], v[190:193], v[86:89]
	v_mfma_f32_16x16x32_f16 v[74:77], v[140:143], v[198:201], v[74:77]
	v_mfma_f32_16x16x32_f16 v[70:73], v[148:151], v[198:201], v[70:73]
	v_mfma_f32_16x16x32_f16 v[122:125], v[144:147], v[178:181], v[122:125]
	v_mfma_f32_16x16x32_f16 v[118:121], v[152:155], v[178:181], v[118:121]
	v_mfma_f32_16x16x32_f16 v[106:109], v[144:147], v[186:189], v[106:109]
	v_mfma_f32_16x16x32_f16 v[102:105], v[152:155], v[186:189], v[102:105]
	v_mfma_f32_16x16x32_f16 v[90:93], v[144:147], v[194:197], v[90:93]
	v_mfma_f32_16x16x32_f16 v[86:89], v[152:155], v[194:197], v[86:89]
	v_mfma_f32_16x16x32_f16 v[74:77], v[144:147], v[202:205], v[74:77]
	v_mfma_f32_16x16x32_f16 v[70:73], v[152:155], v[202:205], v[70:73]
	v_mfma_f32_16x16x32_f16 v[114:117], v[156:159], v[174:177], v[114:117]
	v_mfma_f32_16x16x32_f16 v[126:129], v[166:169], v[174:177], v[126:129]
	v_mfma_f32_16x16x32_f16 v[98:101], v[156:159], v[182:185], v[98:101]
	v_mfma_f32_16x16x32_f16 v[110:113], v[166:169], v[182:185], v[110:113]
	v_mfma_f32_16x16x32_f16 v[82:85], v[156:159], v[190:193], v[82:85]
	v_mfma_f32_16x16x32_f16 v[94:97], v[166:169], v[190:193], v[94:97]
	v_mfma_f32_16x16x32_f16 v[66:69], v[156:159], v[198:201], v[66:69]
	v_mfma_f32_16x16x32_f16 v[78:81], v[166:169], v[198:201], v[78:81]
	v_mfma_f32_16x16x32_f16 v[114:117], v[162:165], v[178:181], v[114:117]
	v_mfma_f32_16x16x32_f16 v[126:129], v[170:173], v[178:181], v[126:129]
	v_mfma_f32_16x16x32_f16 v[98:101], v[162:165], v[186:189], v[98:101]
	v_mfma_f32_16x16x32_f16 v[110:113], v[170:173], v[186:189], v[110:113]
	v_mfma_f32_16x16x32_f16 v[82:85], v[162:165], v[194:197], v[82:85]
	v_mfma_f32_16x16x32_f16 v[94:97], v[170:173], v[194:197], v[94:97]
	v_mfma_f32_16x16x32_f16 v[66:69], v[162:165], v[202:205], v[66:69]
	v_mfma_f32_16x16x32_f16 v[78:81], v[170:173], v[202:205], v[78:81]
	s_setprio 0
	s_barrier
	s_add_i32 s22, s26, s56
	v_lshl_add_u64 v[206:207], s[24:25], 0, v[0:1]
	s_mov_b32 m0, s22
	ds_read_b128 v[174:177], v228 offset:16384
	ds_read_b128 v[178:181], v228 offset:17408
	ds_read_b128 v[182:185], v228 offset:18432
	ds_read_b128 v[186:189], v228 offset:19456
	ds_read_b128 v[190:193], v228 offset:20480
	ds_read_b128 v[194:197], v228 offset:21504
	ds_read_b128 v[198:201], v228 offset:22528
	ds_read_b128 v[202:205], v228 offset:23552
	global_load_lds_dwordx4 v[206:207], off
	s_add_i32 m0, s22, 0x2000
	s_add_u32 s26, s24, 0x40000
	v_lshl_add_u64 v[208:209], s[24:25], 0, v[134:135]
	s_addc_u32 s27, s25, 0
	s_add_i32 s20, s20, s56
	global_load_lds_dwordx4 v[208:209], off
	v_lshl_add_u64 v[210:211], s[26:27], 0, v[0:1]
	s_mov_b32 m0, s20
	v_lshl_add_u64 v[212:213], s[52:53], 0, v[132:133]
	global_load_lds_dwordx4 v[210:211], off
	v_lshl_add_u64 v[210:211], s[26:27], 0, v[134:135]
	s_add_i32 m0, s20, 0x2000
	s_nop 0
	global_load_lds_dwordx4 v[210:211], off
	v_lshl_add_u64 v[210:211], s[52:53], 0, v[130:131]
	s_mov_b32 m0, s57
	s_nop 0
	global_load_lds_dwordx4 v[210:211], off
	s_mov_b32 m0, s58
	s_nop 0
	global_load_lds_dwordx4 v[212:213], off
	s_waitcnt vmcnt(8)
	s_waitcnt lgkmcnt(0)
	s_barrier
; #define PG8_STAGE(bufoff, gbase, voff) do { _Pragma("unroll") for (int _i = 0; _i < 2; ++_i) \
;         __builtin_amdgcn_global_load_lds((const unsigned*)((const char*)(gbase) + (voff)[_i]), (LAS unsigned*)(lds + (bufoff) + ldsw + _i * 8192), 16, 0, 0); } while (0)
; #define PG8_LDA(dst, b, h) do { _Pragma("unroll") for (int m = 0; m < 4; ++m) _Pragma("unroll") for (int k = 0; k < 2; ++k) dst[m][k] = *(const LAS half8*)(lds + PG8_SA(b, h) + aoff + m * 2048 + k * 1024); } while (0)
; #define PG8_LDB(dst, b, h) do { _Pragma("unroll") for (int n = 0; n < 2; ++n) _Pragma("unroll") for (int k = 0; k < 2; ++k) dst[n][k] = *(const LAS half8*)(lds + PG8_SB(b, h) + boff + n * 2048 + k * 1024); } while (0)
; #define PG8_MMA(ai, bj, At, Bt) do { __builtin_amdgcn_s_setprio(1); _Pragma("unroll") for (int m = 0; m < 4; ++m) _Pragma("unroll") for (int n = 0; n < 2; ++n) _Pragma("unroll") for (int k = 0; k < 2; ++k) \
;         acc[ai][bj][m][n] = __builtin_amdgcn_mfma_f32_16x16x32_f16(Bt[n][k], At[m][k], acc[ai][bj][m][n], 0, 0, 0); __builtin_amdgcn_s_setprio(0); } while (0)
; #define PG8_WAIT_V(n) asm volatile("s_waitcnt vmcnt(" #n ")" ::: "memory")
; #define PG8_WAIT_L(n) asm volatile("s_waitcnt lgkmcnt(" #n ")" ::: "memory")
; #define PG8_BAR __builtin_amdgcn_s_barrier()
; #define PG8_SCHED __builtin_amdgcn_sched_barrier(0)
; template <class Epi>
; __device__ __forceinline__ void gemm_phase(LAS unsigned char* lds, const Gemm g, const StaticOrder& S, const Epi& E) {
;     ...
;             PG8_WAIT_V(8); PG8_WAIT_L(0); PG8_BAR; PG8_MMA(1, 0, At, B0); PG8_MMA(1, 1, At, B1); PG8_BAR; PG8_SCHED;
;             PG8_LDB(B0, 1, 0); PG8_LDB(B1, 1, 1); PG8_SCHED; PG8_LDA(At, 1, 0); PG8_STAGE(PG8_SA(0, 1), a2 + hA, voffA);
;             PG8_WAIT_V(8); PG8_WAIT_L(0); PG8_BAR; PG8_MMA(0, 0, At, B0); PG8_MMA(0, 1, At, B1); PG8_BAR; PG8_SCHED;
	s_setprio 1
	s_waitcnt lgkmcnt(0)
	v_mfma_f32_16x16x32_f16 v[58:61], v[140:143], v[174:177], v[58:61]
	v_mfma_f32_16x16x32_f16 v[54:57], v[148:151], v[174:177], v[54:57]
	v_mfma_f32_16x16x32_f16 v[42:45], v[140:143], v[182:185], v[42:45]
	v_mfma_f32_16x16x32_f16 v[38:41], v[148:151], v[182:185], v[38:41]
	v_mfma_f32_16x16x32_f16 v[26:29], v[140:143], v[190:193], v[26:29]
	v_mfma_f32_16x16x32_f16 v[22:25], v[148:151], v[190:193], v[22:25]
	v_mfma_f32_16x16x32_f16 v[10:13], v[140:143], v[198:201], v[10:13]
	v_mfma_f32_16x16x32_f16 v[6:9], v[148:151], v[198:201], v[6:9]
	v_mfma_f32_16x16x32_f16 v[58:61], v[144:147], v[178:181], v[58:61]
	v_mfma_f32_16x16x32_f16 v[54:57], v[152:155], v[178:181], v[54:57]
	v_mfma_f32_16x16x32_f16 v[42:45], v[144:147], v[186:189], v[42:45]
	v_mfma_f32_16x16x32_f16 v[38:41], v[152:155], v[186:189], v[38:41]
	v_mfma_f32_16x16x32_f16 v[26:29], v[144:147], v[194:197], v[26:29]
	v_mfma_f32_16x16x32_f16 v[22:25], v[152:155], v[194:197], v[22:25]
	v_mfma_f32_16x16x32_f16 v[10:13], v[144:147], v[202:205], v[10:13]
	v_mfma_f32_16x16x32_f16 v[6:9], v[152:155], v[202:205], v[6:9]
	v_mfma_f32_16x16x32_f16 v[50:53], v[156:159], v[174:177], v[50:53]
	v_mfma_f32_16x16x32_f16 v[62:65], v[166:169], v[174:177], v[62:65]
	v_mfma_f32_16x16x32_f16 v[34:37], v[156:159], v[182:185], v[34:37]
	v_mfma_f32_16x16x32_f16 v[46:49], v[166:169], v[182:185], v[46:49]
	v_mfma_f32_16x16x32_f16 v[18:21], v[156:159], v[190:193], v[18:21]
	v_mfma_f32_16x16x32_f16 v[30:33], v[166:169], v[190:193], v[30:33]
	v_mfma_f32_16x16x32_f16 v[2:5], v[156:159], v[198:201], v[2:5]
	v_mfma_f32_16x16x32_f16 v[14:17], v[166:169], v[198:201], v[14:17]
	v_mfma_f32_16x16x32_f16 v[50:53], v[162:165], v[178:181], v[50:53]
	v_mfma_f32_16x16x32_f16 v[62:65], v[170:173], v[178:181], v[62:65]
	v_mfma_f32_16x16x32_f16 v[34:37], v[162:165], v[186:189], v[34:37]
	v_mfma_f32_16x16x32_f16 v[46:49], v[170:173], v[186:189], v[46:49]
	v_mfma_f32_16x16x32_f16 v[18:21], v[162:165], v[194:197], v[18:21]
	v_mfma_f32_16x16x32_f16 v[30:33], v[170:173], v[194:197], v[30:33]
	v_mfma_f32_16x16x32_f16 v[2:5], v[162:165], v[202:205], v[2:5]
	v_mfma_f32_16x16x32_f16 v[14:17], v[170:173], v[202:205], v[14:17]
	s_setprio 0
	s_barrier
	s_add_i32 s20, 0, 0x18000
	s_add_i32 s22, 0, 0x1c000
	v_add_u32_e32 v152, s20, v161
	v_add_u32_e32 v170, s22, v161
	ds_read_b128 v[140:143], v152
	ds_read_b128 v[144:147], v152 offset:1024
	ds_read_b128 v[148:151], v152 offset:2048
	ds_read_b128 v[152:155], v152 offset:3072
	ds_read_b128 v[156:159], v170
	ds_read_b128 v[162:165], v170 offset:1024
	ds_read_b128 v[166:169], v170 offset:2048
	ds_read_b128 v[170:173], v170 offset:3072
	s_add_u32 s26, s52, 0x40000
	s_addc_u32 s27, s53, 0
	s_mov_b32 m0, s59
	v_lshl_add_u64 v[214:215], s[26:27], 0, v[130:131]
	ds_read_b128 v[174:177], v228 offset:32768
	ds_read_b128 v[178:181], v228 offset:33792
	ds_read_b128 v[182:185], v228 offset:34816
	ds_read_b128 v[186:189], v228 offset:35840
	ds_read_b128 v[190:193], v228 offset:36864
	ds_read_b128 v[194:197], v228 offset:37888
	ds_read_b128 v[198:201], v228 offset:38912
	ds_read_b128 v[202:205], v228 offset:39936
	global_load_lds_dwordx4 v[214:215], off
	v_lshl_add_u64 v[214:215], s[26:27], 0, v[132:133]
	s_mov_b32 m0, s60
	s_nop 0
	global_load_lds_dwordx4 v[214:215], off
	s_waitcnt vmcnt(8)
	s_waitcnt lgkmcnt(0)
	s_barrier
	s_setprio 1
	s_waitcnt lgkmcnt(0)
	v_mfma_f32_16x16x32_f16 v[122:125], v[140:143], v[174:177], v[122:125]
	v_mfma_f32_16x16x32_f16 v[118:121], v[148:151], v[174:177], v[118:121]
	v_mfma_f32_16x16x32_f16 v[106:109], v[140:143], v[182:185], v[106:109]
	v_mfma_f32_16x16x32_f16 v[102:105], v[148:151], v[182:185], v[102:105]
	v_mfma_f32_16x16x32_f16 v[90:93], v[140:143], v[190:193], v[90:93]
	v_mfma_f32_16x16x32_f16 v[86:89], v[148:151], v[190:193], v[86:89]
	v_mfma_f32_16x16x32_f16 v[74:77], v[140:143], v[198:201], v[74:77]
	v_mfma_f32_16x16x32_f16 v[70:73], v[148:151], v[198:201], v[70:73]
	v_mfma_f32_16x16x32_f16 v[122:125], v[144:147], v[178:181], v[122:125]
	v_mfma_f32_16x16x32_f16 v[118:121], v[152:155], v[178:181], v[118:121]
	v_mfma_f32_16x16x32_f16 v[106:109], v[144:147], v[186:189], v[106:109]
	v_mfma_f32_16x16x32_f16 v[102:105], v[152:155], v[186:189], v[102:105]
	v_mfma_f32_16x16x32_f16 v[90:93], v[144:147], v[194:197], v[90:93]
	v_mfma_f32_16x16x32_f16 v[86:89], v[152:155], v[194:197], v[86:89]
	v_mfma_f32_16x16x32_f16 v[74:77], v[144:147], v[202:205], v[74:77]
	v_mfma_f32_16x16x32_f16 v[70:73], v[152:155], v[202:205], v[70:73]
	v_mfma_f32_16x16x32_f16 v[114:117], v[156:159], v[174:177], v[114:117]
	v_mfma_f32_16x16x32_f16 v[126:129], v[166:169], v[174:177], v[126:129]
	v_mfma_f32_16x16x32_f16 v[98:101], v[156:159], v[182:185], v[98:101]
	v_mfma_f32_16x16x32_f16 v[110:113], v[166:169], v[182:185], v[110:113]
	v_mfma_f32_16x16x32_f16 v[82:85], v[156:159], v[190:193], v[82:85]
	v_mfma_f32_16x16x32_f16 v[94:97], v[166:169], v[190:193], v[94:97]
	v_mfma_f32_16x16x32_f16 v[66:69], v[156:159], v[198:201], v[66:69]
	v_mfma_f32_16x16x32_f16 v[78:81], v[166:169], v[198:201], v[78:81]
	v_mfma_f32_16x16x32_f16 v[114:117], v[162:165], v[178:181], v[114:117]
	v_mfma_f32_16x16x32_f16 v[126:129], v[170:173], v[178:181], v[126:129]
	v_mfma_f32_16x16x32_f16 v[98:101], v[162:165], v[186:189], v[98:101]
	v_mfma_f32_16x16x32_f16 v[110:113], v[170:173], v[186:189], v[110:113]
	v_mfma_f32_16x16x32_f16 v[82:85], v[162:165], v[194:197], v[82:85]
	v_mfma_f32_16x16x32_f16 v[94:97], v[170:173], v[194:197], v[94:97]
	v_mfma_f32_16x16x32_f16 v[66:69], v[162:165], v[202:205], v[66:69]
	v_mfma_f32_16x16x32_f16 v[78:81], v[170:173], v[202:205], v[78:81]
	s_setprio 0
	s_barrier
; #define PG8_STAGE(bufoff, gbase, voff) do { _Pragma("unroll") for (int _i = 0; _i < 2; ++_i) \
;         __builtin_amdgcn_global_load_lds((const unsigned*)((const char*)(gbase) + (voff)[_i]), (LAS unsigned*)(lds + (bufoff) + ldsw + _i * 8192), 16, 0, 0); } while (0)
; #define PG8_LDA(dst, b, h) do { _Pragma("unroll") for (int m = 0; m < 4; ++m) _Pragma("unroll") for (int k = 0; k < 2; ++k) dst[m][k] = *(const LAS half8*)(lds + PG8_SA(b, h) + aoff + m * 2048 + k * 1024); } while (0)
; #define PG8_MMA(ai, bj, At, Bt) do { __builtin_amdgcn_s_setprio(1); _Pragma("unroll") for (int m = 0; m < 4; ++m) _Pragma("unroll") for (int n = 0; n < 2; ++n) _Pragma("unroll") for (int k = 0; k < 2; ++k) \
;         acc[ai][bj][m][n] = __builtin_amdgcn_mfma_f32_16x16x32_f16(Bt[n][k], At[m][k], acc[ai][bj][m][n], 0, 0, 0); __builtin_amdgcn_s_setprio(0); } while (0)
; #define PG8_WAIT_V(n) asm volatile("s_waitcnt vmcnt(" #n ")" ::: "memory")
; #define PG8_WAIT_L(n) asm volatile("s_waitcnt lgkmcnt(" #n ")" ::: "memory")
; #define PG8_BAR __builtin_amdgcn_s_barrier()
; #define PG8_SCHED __builtin_amdgcn_sched_barrier(0)
; template <class Epi>
; __device__ __forceinline__ void gemm_phase(LAS unsigned char* lds, const Gemm g, const StaticOrder& S, const Epi& E) {
;     ...
;             PG8_LDA(At, 1, 1); PG8_STAGE(PG8_SB(1, 0), b3, voffB); PG8_STAGE(PG8_SB(1, 1), b3 + hB, voffB); PG8_STAGE(PG8_SA(1, 0), a3, voffA);
;             PG8_WAIT_V(8); PG8_WAIT_L(0); PG8_BAR; PG8_MMA(1, 0, At, B0); PG8_MMA(1, 1, At, B1); PG8_BAR; PG8_SCHED;
;         }
	s_add_i32 s20, s20, s56
	v_lshl_add_u64 v[206:207], v[206:207], 0, s[92:93]
	s_mov_b32 m0, s20
	ds_read_b128 v[174:177], v228 offset:49152
	ds_read_b128 v[178:181], v228 offset:50176
	ds_read_b128 v[182:185], v228 offset:51200
	ds_read_b128 v[186:189], v228 offset:52224
	ds_read_b128 v[190:193], v228 offset:53248
	ds_read_b128 v[194:197], v228 offset:54272
	ds_read_b128 v[198:201], v228 offset:55296
	ds_read_b128 v[202:205], v228 offset:56320
	global_load_lds_dwordx4 v[206:207], off
	s_add_i32 m0, s20, 0x2000
	s_add_u32 s24, s24, 0x40080
	v_lshl_add_u64 v[206:207], v[208:209], 0, s[92:93]
	s_addc_u32 s25, s25, 0
	s_add_i32 s20, s22, s56
	global_load_lds_dwordx4 v[206:207], off
	v_lshl_add_u64 v[206:207], s[24:25], 0, v[0:1]
	s_mov_b32 m0, s20
	s_nop 0
	global_load_lds_dwordx4 v[206:207], off
	v_lshl_add_u64 v[206:207], s[24:25], 0, v[134:135]
	s_add_i32 m0, s20, 0x2000
	s_nop 0
	global_load_lds_dwordx4 v[206:207], off
	v_lshl_add_u64 v[206:207], v[210:211], 0, s[92:93]
	s_mov_b32 m0, s61
	s_nop 0
	global_load_lds_dwordx4 v[206:207], off
	v_lshl_add_u64 v[206:207], v[212:213], 0, s[92:93]
	s_mov_b32 m0, s62
	s_nop 0
	global_load_lds_dwordx4 v[206:207], off
	s_waitcnt vmcnt(8)
	s_waitcnt lgkmcnt(0)
	s_barrier
	s_setprio 1
	s_waitcnt lgkmcnt(0)
	v_mfma_f32_16x16x32_f16 v[58:61], v[140:143], v[174:177], v[58:61]
	v_mfma_f32_16x16x32_f16 v[54:57], v[148:151], v[174:177], v[54:57]
	v_mfma_f32_16x16x32_f16 v[42:45], v[140:143], v[182:185], v[42:45]
	v_mfma_f32_16x16x32_f16 v[38:41], v[148:151], v[182:185], v[38:41]
	v_mfma_f32_16x16x32_f16 v[26:29], v[140:143], v[190:193], v[26:29]
	v_mfma_f32_16x16x32_f16 v[22:25], v[148:151], v[190:193], v[22:25]
	v_mfma_f32_16x16x32_f16 v[10:13], v[140:143], v[198:201], v[10:13]
	v_mfma_f32_16x16x32_f16 v[6:9], v[148:151], v[198:201], v[6:9]
	v_mfma_f32_16x16x32_f16 v[58:61], v[144:147], v[178:181], v[58:61]
	v_mfma_f32_16x16x32_f16 v[54:57], v[152:155], v[178:181], v[54:57]
	v_mfma_f32_16x16x32_f16 v[42:45], v[144:147], v[186:189], v[42:45]
	v_mfma_f32_16x16x32_f16 v[38:41], v[152:155], v[186:189], v[38:41]
	v_mfma_f32_16x16x32_f16 v[26:29], v[144:147], v[194:197], v[26:29]
	v_mfma_f32_16x16x32_f16 v[22:25], v[152:155], v[194:197], v[22:25]
	v_mfma_f32_16x16x32_f16 v[10:13], v[144:147], v[202:205], v[10:13]
	v_mfma_f32_16x16x32_f16 v[6:9], v[152:155], v[202:205], v[6:9]
	v_mfma_f32_16x16x32_f16 v[50:53], v[156:159], v[174:177], v[50:53]
	v_mfma_f32_16x16x32_f16 v[62:65], v[166:169], v[174:177], v[62:65]
	v_mfma_f32_16x16x32_f16 v[34:37], v[156:159], v[182:185], v[34:37]
	v_mfma_f32_16x16x32_f16 v[46:49], v[166:169], v[182:185], v[46:49]
	v_mfma_f32_16x16x32_f16 v[18:21], v[156:159], v[190:193], v[18:21]
	v_mfma_f32_16x16x32_f16 v[30:33], v[166:169], v[190:193], v[30:33]
	v_mfma_f32_16x16x32_f16 v[2:5], v[156:159], v[198:201], v[2:5]
	v_mfma_f32_16x16x32_f16 v[14:17], v[166:169], v[198:201], v[14:17]
	v_mfma_f32_16x16x32_f16 v[50:53], v[162:165], v[178:181], v[50:53]
	v_mfma_f32_16x16x32_f16 v[62:65], v[170:173], v[178:181], v[62:65]
	v_mfma_f32_16x16x32_f16 v[34:37], v[162:165], v[186:189], v[34:37]
	v_mfma_f32_16x16x32_f16 v[46:49], v[170:173], v[186:189], v[46:49]
	v_mfma_f32_16x16x32_f16 v[18:21], v[162:165], v[194:197], v[18:21]
	v_mfma_f32_16x16x32_f16 v[30:33], v[170:173], v[194:197], v[30:33]
	v_mfma_f32_16x16x32_f16 v[2:5], v[162:165], v[202:205], v[2:5]
	v_mfma_f32_16x16x32_f16 v[14:17], v[170:173], v[202:205], v[14:17]
	s_setprio 0
	s_barrier
	s_add_u32 s15, s15, 0x100
	s_addc_u32 s17, s17, 0
	s_add_u32 s0, s0, 0x100
	s_addc_u32 s1, s1, 0
	s_cmp_ge_i32 s21, s23
	s_mov_b32 s20, s21
	s_cbranch_scc0 .LBB0_379
	s_and_b64 vcc, exec, s[40:41]
	s_cbranch_vccz .LBB0_382

; #define PG8_STAGE(bufoff, gbase, voff) do { _Pragma("unroll") for (int _i = 0; _i < 2; ++_i) \
;         __builtin_amdgcn_global_load_lds((const unsigned*)((const char*)(gbase) + (voff)[_i]), (LAS unsigned*)(lds + (bufoff) + ldsw + _i * 8192), 16, 0, 0); } while (0)
; #define PG8_LDA(dst, b, h) do { _Pragma("unroll") for (int m = 0; m < 4; ++m) _Pragma("unroll") for (int k = 0; k < 2; ++k) dst[m][k] = *(const LAS half8*)(lds + PG8_SA(b, h) + aoff + m * 2048 + k * 1024); } while (0)
; #define PG8_LDB(dst, b, h) do { _Pragma("unroll") for (int n = 0; n < 2; ++n) _Pragma("unroll") for (int k = 0; k < 2; ++k) dst[n][k] = *(const LAS half8*)(lds + PG8_SB(b, h) + boff + n * 2048 + k * 1024); } while (0)
; #define PG8_MMA(ai, bj, At, Bt) do { __builtin_amdgcn_s_setprio(1); _Pragma("unroll") for (int m = 0; m < 4; ++m) _Pragma("unroll") for (int n = 0; n < 2; ++n) _Pragma("unroll") for (int k = 0; k < 2; ++k) \
;         acc[ai][bj][m][n] = __builtin_amdgcn_mfma_f32_16x16x32_f16(Bt[n][k], At[m][k], acc[ai][bj][m][n], 0, 0, 0); __builtin_amdgcn_s_setprio(0); } while (0)
; #define PG8_WAIT_V(n) asm volatile("s_waitcnt vmcnt(" #n ")" ::: "memory")
; #define PG8_WAIT_L(n) asm volatile("s_waitcnt lgkmcnt(" #n ")" ::: "memory")
; #define PG8_BAR __builtin_amdgcn_s_barrier()
; #define PG8_SCHED __builtin_amdgcn_sched_barrier(0)
; template <class Epi>
; __device__ __forceinline__ void gemm_phase(LAS unsigned char* lds, const Gemm g, const StaticOrder& S, const Epi& E) {
;     ...
;         for (int t = 0; t < nt; t += 2) {
;             const bool last = (t == nt - 2);
;             const char* a1 = cA + (size_t)(t + 1) * kstep;
;             const char* a2 = last ? nA : cA + (size_t)(t + 2) * kstep; const char* b2 = last ? nB : cB + (size_t)(t + 2) * kstep;
;             const char* a3 = a2 + kstep; const char* b3 = b2 + kstep;
;             PG8_LDB(B0, 0, 0); PG8_LDB(B1, 0, 1); PG8_SCHED; PG8_LDA(At, 0, 0); PG8_STAGE(PG8_SA(1, 1), a1 + hA, voffA);
;             PG8_WAIT_V(8); PG8_WAIT_L(0); PG8_BAR; PG8_MMA(0, 0, At, B0); PG8_MMA(0, 1, At, B1); PG8_BAR; PG8_SCHED;
;             PG8_LDA(At, 0, 1); PG8_STAGE(PG8_SB(0, 0), b2, voffB); PG8_STAGE(PG8_SB(0, 1), b2 + hB, voffB); PG8_STAGE(PG8_SA(0, 0), a2, voffA);
;             PG8_WAIT_V(8); PG8_WAIT_L(0); PG8_BAR; PG8_MMA(1, 0, At, B0); PG8_MMA(1, 1, At, B1); PG8_BAR; PG8_SCHED;
.LBB0_634:
	s_add_i32 s26, s24, 2
	s_add_u32 s0, s18, 0x100
	s_addc_u32 s1, s19, 0
	s_add_i32 s27, 0, 0x10000
	s_cmp_eq_u32 s60, s24
	s_cselect_b32 s45, s15, s1
	s_cselect_b32 s44, s14, s0
	v_add_u32_e32 v0, s27, v149
	s_cselect_b32 s25, s13, s22
	s_cselect_b32 s24, s20, s21
	s_add_i32 s28, 0, 0x14000
	ds_read_b128 v[142:145], v0
	ds_read_b128 v[152:155], v0 offset:1024
	ds_read_b128 v[156:159], v0 offset:2048
	ds_read_b128 v[162:165], v0 offset:3072
	v_add_u32_e32 v0, s28, v149
	ds_read_b128 v[166:169], v0
	ds_read_b128 v[170:173], v0 offset:1024
	ds_read_b128 v[174:177], v0 offset:2048
	ds_read_b128 v[178:181], v0 offset:3072
	v_lshl_add_u64 v[146:147], s[18:19], 0, v[140:141]
	s_add_i32 m0, s52, 0xc000
	ds_read_b128 v[182:185], v150
	ds_read_b128 v[186:189], v150 offset:1024
	ds_read_b128 v[190:193], v150 offset:2048
	ds_read_b128 v[194:197], v150 offset:3072
	ds_read_b128 v[198:201], v150 offset:4096
	ds_read_b128 v[202:205], v150 offset:5120
	ds_read_b128 v[206:209], v150 offset:6144
	ds_read_b128 v[210:213], v150 offset:7168
	global_load_lds_dwordx4 v[146:147], off
	v_lshl_add_u64 v[146:147], s[18:19], 0, v[138:139]
	s_add_i32 m0, s52, 0xe000
	s_nop 0
	global_load_lds_dwordx4 v[146:147], off
	s_waitcnt vmcnt(8)
	s_waitcnt lgkmcnt(0)
	s_barrier
	s_setprio 1
	s_waitcnt lgkmcnt(0)
	v_mfma_f32_16x16x32_f16 v[126:129], v[142:145], v[182:185], v[126:129]
	v_mfma_f32_16x16x32_f16 v[122:125], v[156:159], v[182:185], v[122:125]
	v_mfma_f32_16x16x32_f16 v[110:113], v[142:145], v[190:193], v[110:113]
	v_mfma_f32_16x16x32_f16 v[106:109], v[156:159], v[190:193], v[106:109]
	v_mfma_f32_16x16x32_f16 v[94:97], v[142:145], v[198:201], v[94:97]
	v_mfma_f32_16x16x32_f16 v[90:93], v[156:159], v[198:201], v[90:93]
	v_mfma_f32_16x16x32_f16 v[78:81], v[142:145], v[206:209], v[78:81]
	v_mfma_f32_16x16x32_f16 v[74:77], v[156:159], v[206:209], v[74:77]
	v_mfma_f32_16x16x32_f16 v[126:129], v[152:155], v[186:189], v[126:129]
	v_mfma_f32_16x16x32_f16 v[122:125], v[162:165], v[186:189], v[122:125]
	v_mfma_f32_16x16x32_f16 v[110:113], v[152:155], v[194:197], v[110:113]
	v_mfma_f32_16x16x32_f16 v[106:109], v[162:165], v[194:197], v[106:109]
	v_mfma_f32_16x16x32_f16 v[94:97], v[152:155], v[202:205], v[94:97]
	v_mfma_f32_16x16x32_f16 v[90:93], v[162:165], v[202:205], v[90:93]
	v_mfma_f32_16x16x32_f16 v[78:81], v[152:155], v[210:213], v[78:81]
	v_mfma_f32_16x16x32_f16 v[74:77], v[162:165], v[210:213], v[74:77]
	v_mfma_f32_16x16x32_f16 v[118:121], v[166:169], v[182:185], v[118:121]
	v_mfma_f32_16x16x32_f16 v[114:117], v[174:177], v[182:185], v[114:117]
	v_mfma_f32_16x16x32_f16 v[102:105], v[166:169], v[190:193], v[102:105]
	v_mfma_f32_16x16x32_f16 v[98:101], v[174:177], v[190:193], v[98:101]
	v_mfma_f32_16x16x32_f16 v[86:89], v[166:169], v[198:201], v[86:89]
	v_mfma_f32_16x16x32_f16 v[82:85], v[174:177], v[198:201], v[82:85]
	v_mfma_f32_16x16x32_f16 v[70:73], v[166:169], v[206:209], v[70:73]
	v_mfma_f32_16x16x32_f16 v[66:69], v[174:177], v[206:209], v[66:69]
	v_mfma_f32_16x16x32_f16 v[118:121], v[170:173], v[186:189], v[118:121]
	v_mfma_f32_16x16x32_f16 v[114:117], v[178:181], v[186:189], v[114:117]
	v_mfma_f32_16x16x32_f16 v[102:105], v[170:173], v[194:197], v[102:105]
	v_mfma_f32_16x16x32_f16 v[98:101], v[178:181], v[194:197], v[98:101]
	v_mfma_f32_16x16x32_f16 v[86:89], v[170:173], v[202:205], v[86:89]
	v_mfma_f32_16x16x32_f16 v[82:85], v[178:181], v[202:205], v[82:85]
	v_mfma_f32_16x16x32_f16 v[70:73], v[170:173], v[210:213], v[70:73]
	v_mfma_f32_16x16x32_f16 v[66:69], v[178:181], v[210:213], v[66:69]
	s_setprio 0
	s_barrier
	s_add_i32 s18, s27, s51
	v_lshl_add_u64 v[146:147], s[24:25], 0, v[132:133]
	s_mov_b32 m0, s18
	ds_read_b128 v[182:185], v150 offset:16384
	ds_read_b128 v[186:189], v150 offset:17408
	ds_read_b128 v[190:193], v150 offset:18432
	ds_read_b128 v[194:197], v150 offset:19456
	ds_read_b128 v[198:201], v150 offset:20480
	ds_read_b128 v[202:205], v150 offset:21504
	ds_read_b128 v[206:209], v150 offset:22528
	ds_read_b128 v[210:213], v150 offset:23552
	global_load_lds_dwordx4 v[146:147], off
	s_add_i32 m0, s18, 0x2000
	s_add_u32 s18, s24, 0x8000
	v_lshl_add_u64 v[214:215], s[24:25], 0, v[136:137]
	s_addc_u32 s19, s25, 0
	s_add_i32 s27, s28, s51
	global_load_lds_dwordx4 v[214:215], off
	v_lshl_add_u64 v[218:219], s[18:19], 0, v[132:133]
	s_mov_b32 m0, s27
	v_lshl_add_u64 v[220:221], s[44:45], 0, v[134:135]
	global_load_lds_dwordx4 v[218:219], off
	v_lshl_add_u64 v[218:219], s[18:19], 0, v[136:137]
	s_add_i32 m0, s27, 0x2000
	s_nop 0
	global_load_lds_dwordx4 v[218:219], off
	v_lshl_add_u64 v[218:219], s[44:45], 0, v[130:131]
	s_mov_b32 m0, s52
	s_nop 0
	global_load_lds_dwordx4 v[218:219], off
	s_mov_b32 m0, s53
	s_nop 0
	global_load_lds_dwordx4 v[220:221], off
	s_waitcnt vmcnt(8)
	s_waitcnt lgkmcnt(0)
	s_barrier
; #define PG8_STAGE(bufoff, gbase, voff) do { _Pragma("unroll") for (int _i = 0; _i < 2; ++_i) \
;         __builtin_amdgcn_global_load_lds((const unsigned*)((const char*)(gbase) + (voff)[_i]), (LAS unsigned*)(lds + (bufoff) + ldsw + _i * 8192), 16, 0, 0); } while (0)
; #define PG8_LDA(dst, b, h) do { _Pragma("unroll") for (int m = 0; m < 4; ++m) _Pragma("unroll") for (int k = 0; k < 2; ++k) dst[m][k] = *(const LAS half8*)(lds + PG8_SA(b, h) + aoff + m * 2048 + k * 1024); } while (0)
; #define PG8_LDB(dst, b, h) do { _Pragma("unroll") for (int n = 0; n < 2; ++n) _Pragma("unroll") for (int k = 0; k < 2; ++k) dst[n][k] = *(const LAS half8*)(lds + PG8_SB(b, h) + boff + n * 2048 + k * 1024); } while (0)
; #define PG8_MMA(ai, bj, At, Bt) do { __builtin_amdgcn_s_setprio(1); _Pragma("unroll") for (int m = 0; m < 4; ++m) _Pragma("unroll") for (int n = 0; n < 2; ++n) _Pragma("unroll") for (int k = 0; k < 2; ++k) \
;         acc[ai][bj][m][n] = __builtin_amdgcn_mfma_f32_16x16x32_f16(Bt[n][k], At[m][k], acc[ai][bj][m][n], 0, 0, 0); __builtin_amdgcn_s_setprio(0); } while (0)
; #define PG8_WAIT_V(n) asm volatile("s_waitcnt vmcnt(" #n ")" ::: "memory")
; #define PG8_WAIT_L(n) asm volatile("s_waitcnt lgkmcnt(" #n ")" ::: "memory")
; #define PG8_BAR __builtin_amdgcn_s_barrier()
; #define PG8_SCHED __builtin_amdgcn_sched_barrier(0)
; template <class Epi>
; __device__ __forceinline__ void gemm_phase(LAS unsigned char* lds, const Gemm g, const StaticOrder& S, const Epi& E) {
;     ...
;             PG8_WAIT_V(8); PG8_WAIT_L(0); PG8_BAR; PG8_MMA(1, 0, At, B0); PG8_MMA(1, 1, At, B1); PG8_BAR; PG8_SCHED;
;             PG8_LDB(B0, 1, 0); PG8_LDB(B1, 1, 1); PG8_SCHED; PG8_LDA(At, 1, 0); PG8_STAGE(PG8_SA(0, 1), a2 + hA, voffA);
;             PG8_WAIT_V(8); PG8_WAIT_L(0); PG8_BAR; PG8_MMA(0, 0, At, B0); PG8_MMA(0, 1, At, B1); PG8_BAR; PG8_SCHED;
	s_setprio 1
	s_waitcnt lgkmcnt(0)
	v_mfma_f32_16x16x32_f16 v[62:65], v[142:145], v[182:185], v[62:65]
	v_mfma_f32_16x16x32_f16 v[58:61], v[156:159], v[182:185], v[58:61]
	v_mfma_f32_16x16x32_f16 v[46:49], v[142:145], v[190:193], v[46:49]
	v_mfma_f32_16x16x32_f16 v[42:45], v[156:159], v[190:193], v[42:45]
	v_mfma_f32_16x16x32_f16 v[30:33], v[142:145], v[198:201], v[30:33]
	v_mfma_f32_16x16x32_f16 v[26:29], v[156:159], v[198:201], v[26:29]
	v_mfma_f32_16x16x32_f16 v[14:17], v[142:145], v[206:209], v[14:17]
	v_mfma_f32_16x16x32_f16 v[10:13], v[156:159], v[206:209], v[10:13]
	v_mfma_f32_16x16x32_f16 v[62:65], v[152:155], v[186:189], v[62:65]
	v_mfma_f32_16x16x32_f16 v[58:61], v[162:165], v[186:189], v[58:61]
	v_mfma_f32_16x16x32_f16 v[46:49], v[152:155], v[194:197], v[46:49]
	v_mfma_f32_16x16x32_f16 v[42:45], v[162:165], v[194:197], v[42:45]
	v_mfma_f32_16x16x32_f16 v[30:33], v[152:155], v[202:205], v[30:33]
	v_mfma_f32_16x16x32_f16 v[26:29], v[162:165], v[202:205], v[26:29]
	v_mfma_f32_16x16x32_f16 v[14:17], v[152:155], v[210:213], v[14:17]
	v_mfma_f32_16x16x32_f16 v[10:13], v[162:165], v[210:213], v[10:13]
	v_mfma_f32_16x16x32_f16 v[54:57], v[166:169], v[182:185], v[54:57]
	v_mfma_f32_16x16x32_f16 v[50:53], v[174:177], v[182:185], v[50:53]
	v_mfma_f32_16x16x32_f16 v[38:41], v[166:169], v[190:193], v[38:41]
	v_mfma_f32_16x16x32_f16 v[34:37], v[174:177], v[190:193], v[34:37]
	v_mfma_f32_16x16x32_f16 v[22:25], v[166:169], v[198:201], v[22:25]
	v_mfma_f32_16x16x32_f16 v[18:21], v[174:177], v[198:201], v[18:21]
	v_mfma_f32_16x16x32_f16 v[6:9], v[166:169], v[206:209], v[6:9]
	v_mfma_f32_16x16x32_f16 v[2:5], v[174:177], v[206:209], v[2:5]
	v_mfma_f32_16x16x32_f16 v[54:57], v[170:173], v[186:189], v[54:57]
	v_mfma_f32_16x16x32_f16 v[50:53], v[178:181], v[186:189], v[50:53]
	v_mfma_f32_16x16x32_f16 v[38:41], v[170:173], v[194:197], v[38:41]
	v_mfma_f32_16x16x32_f16 v[34:37], v[178:181], v[194:197], v[34:37]
	v_mfma_f32_16x16x32_f16 v[22:25], v[170:173], v[202:205], v[22:25]
	v_mfma_f32_16x16x32_f16 v[18:21], v[178:181], v[202:205], v[18:21]
	v_mfma_f32_16x16x32_f16 v[6:9], v[170:173], v[210:213], v[6:9]
	v_mfma_f32_16x16x32_f16 v[2:5], v[178:181], v[210:213], v[2:5]
	s_setprio 0
	s_barrier
	s_add_i32 s27, 0, 0x18000
	v_add_u32_e32 v0, s27, v149
	s_add_i32 s28, 0, 0x1c000
	ds_read_b128 v[142:145], v0
	ds_read_b128 v[152:155], v0 offset:1024
	ds_read_b128 v[156:159], v0 offset:2048
	ds_read_b128 v[162:165], v0 offset:3072
	v_add_u32_e32 v0, s28, v149
	ds_read_b128 v[166:169], v0
	ds_read_b128 v[170:173], v0 offset:1024
	ds_read_b128 v[174:177], v0 offset:2048
	ds_read_b128 v[178:181], v0 offset:3072
	s_add_u32 s18, s44, 0x50000
	s_addc_u32 s19, s45, 0
	s_mov_b32 m0, s54
	v_lshl_add_u64 v[222:223], s[18:19], 0, v[130:131]
	ds_read_b128 v[182:185], v150 offset:32768
	ds_read_b128 v[186:189], v150 offset:33792
	ds_read_b128 v[190:193], v150 offset:34816
	ds_read_b128 v[194:197], v150 offset:35840
	ds_read_b128 v[198:201], v150 offset:36864
	ds_read_b128 v[202:205], v150 offset:37888
	ds_read_b128 v[206:209], v150 offset:38912
	ds_read_b128 v[210:213], v150 offset:39936
	global_load_lds_dwordx4 v[222:223], off
	v_lshl_add_u64 v[222:223], s[18:19], 0, v[134:135]
	s_mov_b32 m0, s55
	s_nop 0
	global_load_lds_dwordx4 v[222:223], off
	s_waitcnt vmcnt(8)
	s_waitcnt lgkmcnt(0)
	s_barrier
	s_setprio 1
	s_waitcnt lgkmcnt(0)
	v_mfma_f32_16x16x32_f16 v[126:129], v[142:145], v[182:185], v[126:129]
	v_mfma_f32_16x16x32_f16 v[122:125], v[156:159], v[182:185], v[122:125]
	v_mfma_f32_16x16x32_f16 v[110:113], v[142:145], v[190:193], v[110:113]
	v_mfma_f32_16x16x32_f16 v[106:109], v[156:159], v[190:193], v[106:109]
	v_mfma_f32_16x16x32_f16 v[94:97], v[142:145], v[198:201], v[94:97]
	v_mfma_f32_16x16x32_f16 v[90:93], v[156:159], v[198:201], v[90:93]
	v_mfma_f32_16x16x32_f16 v[78:81], v[142:145], v[206:209], v[78:81]
	v_mfma_f32_16x16x32_f16 v[74:77], v[156:159], v[206:209], v[74:77]
	v_mfma_f32_16x16x32_f16 v[126:129], v[152:155], v[186:189], v[126:129]
	v_mfma_f32_16x16x32_f16 v[122:125], v[162:165], v[186:189], v[122:125]
	v_mfma_f32_16x16x32_f16 v[110:113], v[152:155], v[194:197], v[110:113]
	v_mfma_f32_16x16x32_f16 v[106:109], v[162:165], v[194:197], v[106:109]
	v_mfma_f32_16x16x32_f16 v[94:97], v[152:155], v[202:205], v[94:97]
	v_mfma_f32_16x16x32_f16 v[90:93], v[162:165], v[202:205], v[90:93]
	v_mfma_f32_16x16x32_f16 v[78:81], v[152:155], v[210:213], v[78:81]
	v_mfma_f32_16x16x32_f16 v[74:77], v[162:165], v[210:213], v[74:77]
	v_mfma_f32_16x16x32_f16 v[118:121], v[166:169], v[182:185], v[118:121]
	v_mfma_f32_16x16x32_f16 v[114:117], v[174:177], v[182:185], v[114:117]
	v_mfma_f32_16x16x32_f16 v[102:105], v[166:169], v[190:193], v[102:105]
	v_mfma_f32_16x16x32_f16 v[98:101], v[174:177], v[190:193], v[98:101]
	v_mfma_f32_16x16x32_f16 v[86:89], v[166:169], v[198:201], v[86:89]
	v_mfma_f32_16x16x32_f16 v[82:85], v[174:177], v[198:201], v[82:85]
	v_mfma_f32_16x16x32_f16 v[70:73], v[166:169], v[206:209], v[70:73]
	v_mfma_f32_16x16x32_f16 v[66:69], v[174:177], v[206:209], v[66:69]
	v_mfma_f32_16x16x32_f16 v[118:121], v[170:173], v[186:189], v[118:121]
	v_mfma_f32_16x16x32_f16 v[114:117], v[178:181], v[186:189], v[114:117]
	v_mfma_f32_16x16x32_f16 v[102:105], v[170:173], v[194:197], v[102:105]
	v_mfma_f32_16x16x32_f16 v[98:101], v[178:181], v[194:197], v[98:101]
	v_mfma_f32_16x16x32_f16 v[86:89], v[170:173], v[202:205], v[86:89]
	v_mfma_f32_16x16x32_f16 v[82:85], v[178:181], v[202:205], v[82:85]
	v_mfma_f32_16x16x32_f16 v[70:73], v[170:173], v[210:213], v[70:73]
	v_mfma_f32_16x16x32_f16 v[66:69], v[178:181], v[210:213], v[66:69]
	s_setprio 0
	s_barrier
; #define PG8_STAGE(bufoff, gbase, voff) do { _Pragma("unroll") for (int _i = 0; _i < 2; ++_i) \
;         __builtin_amdgcn_global_load_lds((const unsigned*)((const char*)(gbase) + (voff)[_i]), (LAS unsigned*)(lds + (bufoff) + ldsw + _i * 8192), 16, 0, 0); } while (0)
; #define PG8_LDA(dst, b, h) do { _Pragma("unroll") for (int m = 0; m < 4; ++m) _Pragma("unroll") for (int k = 0; k < 2; ++k) dst[m][k] = *(const LAS half8*)(lds + PG8_SA(b, h) + aoff + m * 2048 + k * 1024); } while (0)
; #define PG8_MMA(ai, bj, At, Bt) do { __builtin_amdgcn_s_setprio(1); _Pragma("unroll") for (int m = 0; m < 4; ++m) _Pragma("unroll") for (int n = 0; n < 2; ++n) _Pragma("unroll") for (int k = 0; k < 2; ++k) \
;         acc[ai][bj][m][n] = __builtin_amdgcn_mfma_f32_16x16x32_f16(Bt[n][k], At[m][k], acc[ai][bj][m][n], 0, 0, 0); __builtin_amdgcn_s_setprio(0); } while (0)
; #define PG8_WAIT_V(n) asm volatile("s_waitcnt vmcnt(" #n ")" ::: "memory")
; #define PG8_WAIT_L(n) asm volatile("s_waitcnt lgkmcnt(" #n ")" ::: "memory")
; #define PG8_BAR __builtin_amdgcn_s_barrier()
; #define PG8_SCHED __builtin_amdgcn_sched_barrier(0)
; template <class Epi>
; __device__ __forceinline__ void gemm_phase(LAS unsigned char* lds, const Gemm g, const StaticOrder& S, const Epi& E) {
;     ...
;             PG8_LDA(At, 1, 1); PG8_STAGE(PG8_SB(1, 0), b3, voffB); PG8_STAGE(PG8_SB(1, 1), b3 + hB, voffB); PG8_STAGE(PG8_SA(1, 0), a3, voffA);
;             PG8_WAIT_V(8); PG8_WAIT_L(0); PG8_BAR; PG8_MMA(1, 0, At, B0); PG8_MMA(1, 1, At, B1); PG8_BAR; PG8_SCHED;
;         }
	s_add_i32 s18, s27, s51
	v_lshl_add_u64 v[146:147], v[146:147], 0, s[92:93]
	s_mov_b32 m0, s18
	ds_read_b128 v[182:185], v150 offset:49152
	ds_read_b128 v[186:189], v150 offset:50176
	ds_read_b128 v[190:193], v150 offset:51200
	ds_read_b128 v[194:197], v150 offset:52224
	ds_read_b128 v[198:201], v150 offset:53248
	ds_read_b128 v[202:205], v150 offset:54272
	ds_read_b128 v[206:209], v150 offset:55296
	ds_read_b128 v[210:213], v150 offset:56320
	global_load_lds_dwordx4 v[146:147], off
	s_add_i32 m0, s18, 0x2000
	s_add_u32 s18, s24, 0x8080
	v_lshl_add_u64 v[146:147], v[214:215], 0, s[92:93]
	s_addc_u32 s19, s25, 0
	s_add_i32 s24, s28, s51
	global_load_lds_dwordx4 v[146:147], off
	v_lshl_add_u64 v[146:147], s[18:19], 0, v[132:133]
	s_mov_b32 m0, s24
	s_nop 0
	global_load_lds_dwordx4 v[146:147], off
	v_lshl_add_u64 v[146:147], s[18:19], 0, v[136:137]
	s_add_i32 m0, s24, 0x2000
	s_nop 0
	global_load_lds_dwordx4 v[146:147], off
	v_lshl_add_u64 v[146:147], v[218:219], 0, s[92:93]
	s_mov_b32 m0, s57
	s_nop 0
	global_load_lds_dwordx4 v[146:147], off
	v_lshl_add_u64 v[146:147], v[220:221], 0, s[92:93]
	s_mov_b32 m0, s58
	s_nop 0
	global_load_lds_dwordx4 v[146:147], off
	s_waitcnt vmcnt(8)
	s_waitcnt lgkmcnt(0)
	s_barrier
	s_setprio 1
	s_waitcnt lgkmcnt(0)
	v_mfma_f32_16x16x32_f16 v[62:65], v[142:145], v[182:185], v[62:65]
	v_mfma_f32_16x16x32_f16 v[58:61], v[156:159], v[182:185], v[58:61]
	v_mfma_f32_16x16x32_f16 v[46:49], v[142:145], v[190:193], v[46:49]
	v_mfma_f32_16x16x32_f16 v[42:45], v[156:159], v[190:193], v[42:45]
	v_mfma_f32_16x16x32_f16 v[30:33], v[142:145], v[198:201], v[30:33]
	v_mfma_f32_16x16x32_f16 v[26:29], v[156:159], v[198:201], v[26:29]
	v_mfma_f32_16x16x32_f16 v[14:17], v[142:145], v[206:209], v[14:17]
	v_mfma_f32_16x16x32_f16 v[10:13], v[156:159], v[206:209], v[10:13]
	v_mfma_f32_16x16x32_f16 v[62:65], v[152:155], v[186:189], v[62:65]
	v_mfma_f32_16x16x32_f16 v[58:61], v[162:165], v[186:189], v[58:61]
	v_mfma_f32_16x16x32_f16 v[46:49], v[152:155], v[194:197], v[46:49]
	v_mfma_f32_16x16x32_f16 v[42:45], v[162:165], v[194:197], v[42:45]
	v_mfma_f32_16x16x32_f16 v[30:33], v[152:155], v[202:205], v[30:33]
	v_mfma_f32_16x16x32_f16 v[26:29], v[162:165], v[202:205], v[26:29]
	v_mfma_f32_16x16x32_f16 v[14:17], v[152:155], v[210:213], v[14:17]
	v_mfma_f32_16x16x32_f16 v[10:13], v[162:165], v[210:213], v[10:13]
	v_mfma_f32_16x16x32_f16 v[54:57], v[166:169], v[182:185], v[54:57]
	v_mfma_f32_16x16x32_f16 v[50:53], v[174:177], v[182:185], v[50:53]
	v_mfma_f32_16x16x32_f16 v[38:41], v[166:169], v[190:193], v[38:41]
	v_mfma_f32_16x16x32_f16 v[34:37], v[174:177], v[190:193], v[34:37]
	v_mfma_f32_16x16x32_f16 v[22:25], v[166:169], v[198:201], v[22:25]
	v_mfma_f32_16x16x32_f16 v[18:21], v[174:177], v[198:201], v[18:21]
	v_mfma_f32_16x16x32_f16 v[6:9], v[166:169], v[206:209], v[6:9]
	v_mfma_f32_16x16x32_f16 v[2:5], v[174:177], v[206:209], v[2:5]
	v_mfma_f32_16x16x32_f16 v[54:57], v[170:173], v[186:189], v[54:57]
	v_mfma_f32_16x16x32_f16 v[50:53], v[178:181], v[186:189], v[50:53]
	v_mfma_f32_16x16x32_f16 v[38:41], v[170:173], v[194:197], v[38:41]
	v_mfma_f32_16x16x32_f16 v[34:37], v[178:181], v[194:197], v[34:37]
	v_mfma_f32_16x16x32_f16 v[22:25], v[170:173], v[202:205], v[22:25]
	v_mfma_f32_16x16x32_f16 v[18:21], v[178:181], v[202:205], v[18:21]
	v_mfma_f32_16x16x32_f16 v[6:9], v[170:173], v[210:213], v[6:9]
	v_mfma_f32_16x16x32_f16 v[2:5], v[178:181], v[210:213], v[2:5]
	s_setprio 0
	s_barrier
	s_add_u32 s21, s21, 0x100
	s_addc_u32 s22, s22, 0
	s_cmp_ge_i32 s26, s23
	s_mov_b64 s[18:19], s[0:1]
	s_mov_b32 s24, s26
	s_cbranch_scc0 .LBB0_634
	s_and_b64 vcc, exec, s[10:11]
	s_cbranch_vccz .LBB0_637

; #define PG8_STAGE(bufoff, gbase, voff) do { _Pragma("unroll") for (int _i = 0; _i < 2; ++_i) \
;         __builtin_amdgcn_global_load_lds((const unsigned*)((const char*)(gbase) + (voff)[_i]), (LAS unsigned*)(lds + (bufoff) + ldsw + _i * 8192), 16, 0, 0); } while (0)
; #define PG8_LDA(dst, b, h) do { _Pragma("unroll") for (int m = 0; m < 4; ++m) _Pragma("unroll") for (int k = 0; k < 2; ++k) dst[m][k] = *(const LAS half8*)(lds + PG8_SA(b, h) + aoff + m * 2048 + k * 1024); } while (0)
; #define PG8_LDB(dst, b, h) do { _Pragma("unroll") for (int n = 0; n < 2; ++n) _Pragma("unroll") for (int k = 0; k < 2; ++k) dst[n][k] = *(const LAS half8*)(lds + PG8_SB(b, h) + boff + n * 2048 + k * 1024); } while (0)
; #define PG8_MMA(ai, bj, At, Bt) do { __builtin_amdgcn_s_setprio(1); _Pragma("unroll") for (int m = 0; m < 4; ++m) _Pragma("unroll") for (int n = 0; n < 2; ++n) _Pragma("unroll") for (int k = 0; k < 2; ++k) \
;         acc[ai][bj][m][n] = __builtin_amdgcn_mfma_f32_16x16x32_f16(Bt[n][k], At[m][k], acc[ai][bj][m][n], 0, 0, 0); __builtin_amdgcn_s_setprio(0); } while (0)
; #define PG8_WAIT_V(n) asm volatile("s_waitcnt vmcnt(" #n ")" ::: "memory")
; #define PG8_WAIT_L(n) asm volatile("s_waitcnt lgkmcnt(" #n ")" ::: "memory")
; #define PG8_BAR __builtin_amdgcn_s_barrier()
; #define PG8_SCHED __builtin_amdgcn_sched_barrier(0)
; template <class Epi>
; __device__ __forceinline__ void gemm_phase(LAS unsigned char* lds, const Gemm g, const StaticOrder& S, const Epi& E) {
;     ...
;         for (int t = 0; t < nt; t += 2) {
;             const bool last = (t == nt - 2);
;             const char* a1 = cA + (size_t)(t + 1) * kstep;
;             const char* a2 = last ? nA : cA + (size_t)(t + 2) * kstep; const char* b2 = last ? nB : cB + (size_t)(t + 2) * kstep;
;             const char* a3 = a2 + kstep; const char* b3 = b2 + kstep;
;             PG8_LDB(B0, 0, 0); PG8_LDB(B1, 0, 1); PG8_SCHED; PG8_LDA(At, 0, 0); PG8_STAGE(PG8_SA(1, 1), a1 + hA, voffA);
;             PG8_WAIT_V(8); PG8_WAIT_L(0); PG8_BAR; PG8_MMA(0, 0, At, B0); PG8_MMA(0, 1, At, B1); PG8_BAR; PG8_SCHED;
;             PG8_LDA(At, 0, 1); PG8_STAGE(PG8_SB(0, 0), b2, voffB); PG8_STAGE(PG8_SB(0, 1), b2 + hB, voffB); PG8_STAGE(PG8_SA(0, 0), a2, voffA);
;             PG8_WAIT_V(8); PG8_WAIT_L(0); PG8_BAR; PG8_MMA(1, 0, At, B0); PG8_MMA(1, 1, At, B1); PG8_BAR; PG8_SCHED;
.LBB0_659:
	s_add_i32 s26, s24, 2
	s_add_u32 s0, s20, 0x100
	s_addc_u32 s1, s21, 0
	s_add_i32 s27, 0, 0x10000
	s_cmp_eq_u32 s58, s24
	s_cselect_b32 s45, s17, s1
	s_cselect_b32 s44, s16, s0
	v_add_u32_e32 v0, s27, v154
	s_cselect_b32 s25, s3, s22
	s_cselect_b32 s24, s7, s15
	s_add_i32 s28, 0, 0x14000
	ds_read_b128 v[142:145], v0
	ds_read_b128 v[146:149], v0 offset:1024
	ds_read_b128 v[150:153], v0 offset:2048
	ds_read_b128 v[156:159], v0 offset:3072
	v_add_u32_e32 v0, s28, v154
	ds_read_b128 v[162:165], v0
	ds_read_b128 v[166:169], v0 offset:1024
	ds_read_b128 v[170:173], v0 offset:2048
	ds_read_b128 v[174:177], v0 offset:3072
	v_lshl_add_u64 v[210:211], s[20:21], 0, v[140:141]
	s_add_i32 m0, s51, 0xc000
	ds_read_b128 v[178:181], v155
	ds_read_b128 v[182:185], v155 offset:1024
	ds_read_b128 v[186:189], v155 offset:2048
	ds_read_b128 v[190:193], v155 offset:3072
	ds_read_b128 v[194:197], v155 offset:4096
	ds_read_b128 v[198:201], v155 offset:5120
	ds_read_b128 v[202:205], v155 offset:6144
	ds_read_b128 v[206:209], v155 offset:7168
	global_load_lds_dwordx4 v[210:211], off
	v_lshl_add_u64 v[210:211], s[20:21], 0, v[138:139]
	s_add_i32 m0, s51, 0xe000
	s_nop 0
	global_load_lds_dwordx4 v[210:211], off
	s_waitcnt vmcnt(8)
	s_waitcnt lgkmcnt(0)
	s_barrier
	s_setprio 1
	s_waitcnt lgkmcnt(0)
	v_mfma_f32_16x16x32_f16 v[126:129], v[142:145], v[178:181], v[126:129]
	v_mfma_f32_16x16x32_f16 v[122:125], v[150:153], v[178:181], v[122:125]
	v_mfma_f32_16x16x32_f16 v[110:113], v[142:145], v[186:189], v[110:113]
	v_mfma_f32_16x16x32_f16 v[106:109], v[150:153], v[186:189], v[106:109]
	v_mfma_f32_16x16x32_f16 v[94:97], v[142:145], v[194:197], v[94:97]
	v_mfma_f32_16x16x32_f16 v[90:93], v[150:153], v[194:197], v[90:93]
	v_mfma_f32_16x16x32_f16 v[78:81], v[142:145], v[202:205], v[78:81]
	v_mfma_f32_16x16x32_f16 v[74:77], v[150:153], v[202:205], v[74:77]
	v_mfma_f32_16x16x32_f16 v[126:129], v[146:149], v[182:185], v[126:129]
	v_mfma_f32_16x16x32_f16 v[122:125], v[156:159], v[182:185], v[122:125]
	v_mfma_f32_16x16x32_f16 v[110:113], v[146:149], v[190:193], v[110:113]
	v_mfma_f32_16x16x32_f16 v[106:109], v[156:159], v[190:193], v[106:109]
	v_mfma_f32_16x16x32_f16 v[94:97], v[146:149], v[198:201], v[94:97]
	v_mfma_f32_16x16x32_f16 v[90:93], v[156:159], v[198:201], v[90:93]
	v_mfma_f32_16x16x32_f16 v[78:81], v[146:149], v[206:209], v[78:81]
	v_mfma_f32_16x16x32_f16 v[74:77], v[156:159], v[206:209], v[74:77]
	v_mfma_f32_16x16x32_f16 v[118:121], v[162:165], v[178:181], v[118:121]
	v_mfma_f32_16x16x32_f16 v[114:117], v[170:173], v[178:181], v[114:117]
	v_mfma_f32_16x16x32_f16 v[102:105], v[162:165], v[186:189], v[102:105]
	v_mfma_f32_16x16x32_f16 v[98:101], v[170:173], v[186:189], v[98:101]
	v_mfma_f32_16x16x32_f16 v[86:89], v[162:165], v[194:197], v[86:89]
	v_mfma_f32_16x16x32_f16 v[82:85], v[170:173], v[194:197], v[82:85]
	v_mfma_f32_16x16x32_f16 v[70:73], v[162:165], v[202:205], v[70:73]
	v_mfma_f32_16x16x32_f16 v[66:69], v[170:173], v[202:205], v[66:69]
	v_mfma_f32_16x16x32_f16 v[118:121], v[166:169], v[182:185], v[118:121]
	v_mfma_f32_16x16x32_f16 v[114:117], v[174:177], v[182:185], v[114:117]
	v_mfma_f32_16x16x32_f16 v[102:105], v[166:169], v[190:193], v[102:105]
	v_mfma_f32_16x16x32_f16 v[98:101], v[174:177], v[190:193], v[98:101]
	v_mfma_f32_16x16x32_f16 v[86:89], v[166:169], v[198:201], v[86:89]
	v_mfma_f32_16x16x32_f16 v[82:85], v[174:177], v[198:201], v[82:85]
	v_mfma_f32_16x16x32_f16 v[70:73], v[166:169], v[206:209], v[70:73]
	v_mfma_f32_16x16x32_f16 v[66:69], v[174:177], v[206:209], v[66:69]
	s_setprio 0
	s_barrier
	s_add_i32 s20, s27, s50
	v_lshl_add_u64 v[210:211], s[24:25], 0, v[132:133]
	s_mov_b32 m0, s20
	ds_read_b128 v[178:181], v155 offset:16384
	ds_read_b128 v[182:185], v155 offset:17408
	ds_read_b128 v[186:189], v155 offset:18432
	ds_read_b128 v[190:193], v155 offset:19456
	ds_read_b128 v[194:197], v155 offset:20480
	ds_read_b128 v[198:201], v155 offset:21504
	ds_read_b128 v[202:205], v155 offset:22528
	ds_read_b128 v[206:209], v155 offset:23552
	global_load_lds_dwordx4 v[210:211], off
	s_add_i32 m0, s20, 0x2000
	s_add_u32 s20, s24, 0x10000
	v_lshl_add_u64 v[212:213], s[24:25], 0, v[136:137]
	s_addc_u32 s21, s25, 0
	s_add_i32 s27, s28, s50
	global_load_lds_dwordx4 v[212:213], off
	v_lshl_add_u64 v[214:215], s[20:21], 0, v[132:133]
	s_mov_b32 m0, s27
	v_lshl_add_u64 v[218:219], s[44:45], 0, v[134:135]
	global_load_lds_dwordx4 v[214:215], off
	v_lshl_add_u64 v[214:215], s[20:21], 0, v[136:137]
	s_add_i32 m0, s27, 0x2000
	s_nop 0
	global_load_lds_dwordx4 v[214:215], off
	v_lshl_add_u64 v[214:215], s[44:45], 0, v[130:131]
	s_mov_b32 m0, s51
	s_nop 0
	global_load_lds_dwordx4 v[214:215], off
	s_mov_b32 m0, s52
	s_nop 0
	global_load_lds_dwordx4 v[218:219], off
	s_waitcnt vmcnt(8)
	s_waitcnt lgkmcnt(0)
	s_barrier
; #define PG8_STAGE(bufoff, gbase, voff) do { _Pragma("unroll") for (int _i = 0; _i < 2; ++_i) \
;         __builtin_amdgcn_global_load_lds((const unsigned*)((const char*)(gbase) + (voff)[_i]), (LAS unsigned*)(lds + (bufoff) + ldsw + _i * 8192), 16, 0, 0); } while (0)
; #define PG8_LDA(dst, b, h) do { _Pragma("unroll") for (int m = 0; m < 4; ++m) _Pragma("unroll") for (int k = 0; k < 2; ++k) dst[m][k] = *(const LAS half8*)(lds + PG8_SA(b, h) + aoff + m * 2048 + k * 1024); } while (0)
; #define PG8_LDB(dst, b, h) do { _Pragma("unroll") for (int n = 0; n < 2; ++n) _Pragma("unroll") for (int k = 0; k < 2; ++k) dst[n][k] = *(const LAS half8*)(lds + PG8_SB(b, h) + boff + n * 2048 + k * 1024); } while (0)
; #define PG8_MMA(ai, bj, At, Bt) do { __builtin_amdgcn_s_setprio(1); _Pragma("unroll") for (int m = 0; m < 4; ++m) _Pragma("unroll") for (int n = 0; n < 2; ++n) _Pragma("unroll") for (int k = 0; k < 2; ++k) \
;         acc[ai][bj][m][n] = __builtin_amdgcn_mfma_f32_16x16x32_f16(Bt[n][k], At[m][k], acc[ai][bj][m][n], 0, 0, 0); __builtin_amdgcn_s_setprio(0); } while (0)
; #define PG8_WAIT_V(n) asm volatile("s_waitcnt vmcnt(" #n ")" ::: "memory")
; #define PG8_WAIT_L(n) asm volatile("s_waitcnt lgkmcnt(" #n ")" ::: "memory")
; #define PG8_BAR __builtin_amdgcn_s_barrier()
; #define PG8_SCHED __builtin_amdgcn_sched_barrier(0)
; template <class Epi>
; __device__ __forceinline__ void gemm_phase(LAS unsigned char* lds, const Gemm g, const StaticOrder& S, const Epi& E) {
;     ...
;             PG8_WAIT_V(8); PG8_WAIT_L(0); PG8_BAR; PG8_MMA(1, 0, At, B0); PG8_MMA(1, 1, At, B1); PG8_BAR; PG8_SCHED;
;             PG8_LDB(B0, 1, 0); PG8_LDB(B1, 1, 1); PG8_SCHED; PG8_LDA(At, 1, 0); PG8_STAGE(PG8_SA(0, 1), a2 + hA, voffA);
;             PG8_WAIT_V(8); PG8_WAIT_L(0); PG8_BAR; PG8_MMA(0, 0, At, B0); PG8_MMA(0, 1, At, B1); PG8_BAR; PG8_SCHED;
	s_setprio 1
	s_waitcnt lgkmcnt(0)
	v_mfma_f32_16x16x32_f16 v[62:65], v[142:145], v[178:181], v[62:65]
	v_mfma_f32_16x16x32_f16 v[58:61], v[150:153], v[178:181], v[58:61]
	v_mfma_f32_16x16x32_f16 v[46:49], v[142:145], v[186:189], v[46:49]
	v_mfma_f32_16x16x32_f16 v[42:45], v[150:153], v[186:189], v[42:45]
	v_mfma_f32_16x16x32_f16 v[30:33], v[142:145], v[194:197], v[30:33]
	v_mfma_f32_16x16x32_f16 v[26:29], v[150:153], v[194:197], v[26:29]
	v_mfma_f32_16x16x32_f16 v[14:17], v[142:145], v[202:205], v[14:17]
	v_mfma_f32_16x16x32_f16 v[10:13], v[150:153], v[202:205], v[10:13]
	v_mfma_f32_16x16x32_f16 v[62:65], v[146:149], v[182:185], v[62:65]
	v_mfma_f32_16x16x32_f16 v[58:61], v[156:159], v[182:185], v[58:61]
	v_mfma_f32_16x16x32_f16 v[46:49], v[146:149], v[190:193], v[46:49]
	v_mfma_f32_16x16x32_f16 v[42:45], v[156:159], v[190:193], v[42:45]
	v_mfma_f32_16x16x32_f16 v[30:33], v[146:149], v[198:201], v[30:33]
	v_mfma_f32_16x16x32_f16 v[26:29], v[156:159], v[198:201], v[26:29]
	v_mfma_f32_16x16x32_f16 v[14:17], v[146:149], v[206:209], v[14:17]
	v_mfma_f32_16x16x32_f16 v[10:13], v[156:159], v[206:209], v[10:13]
	v_mfma_f32_16x16x32_f16 v[54:57], v[162:165], v[178:181], v[54:57]
	v_mfma_f32_16x16x32_f16 v[50:53], v[170:173], v[178:181], v[50:53]
	v_mfma_f32_16x16x32_f16 v[38:41], v[162:165], v[186:189], v[38:41]
	v_mfma_f32_16x16x32_f16 v[34:37], v[170:173], v[186:189], v[34:37]
	v_mfma_f32_16x16x32_f16 v[22:25], v[162:165], v[194:197], v[22:25]
	v_mfma_f32_16x16x32_f16 v[18:21], v[170:173], v[194:197], v[18:21]
	v_mfma_f32_16x16x32_f16 v[6:9], v[162:165], v[202:205], v[6:9]
	v_mfma_f32_16x16x32_f16 v[2:5], v[170:173], v[202:205], v[2:5]
	v_mfma_f32_16x16x32_f16 v[54:57], v[166:169], v[182:185], v[54:57]
	v_mfma_f32_16x16x32_f16 v[50:53], v[174:177], v[182:185], v[50:53]
	v_mfma_f32_16x16x32_f16 v[38:41], v[166:169], v[190:193], v[38:41]
	v_mfma_f32_16x16x32_f16 v[34:37], v[174:177], v[190:193], v[34:37]
	v_mfma_f32_16x16x32_f16 v[22:25], v[166:169], v[198:201], v[22:25]
	v_mfma_f32_16x16x32_f16 v[18:21], v[174:177], v[198:201], v[18:21]
	v_mfma_f32_16x16x32_f16 v[6:9], v[166:169], v[206:209], v[6:9]
	v_mfma_f32_16x16x32_f16 v[2:5], v[174:177], v[206:209], v[2:5]
	s_setprio 0
	s_barrier
	s_add_i32 s27, 0, 0x18000
	v_add_u32_e32 v0, s27, v154
	s_add_i32 s28, 0, 0x1c000
	ds_read_b128 v[142:145], v0
	ds_read_b128 v[146:149], v0 offset:1024
	ds_read_b128 v[150:153], v0 offset:2048
	ds_read_b128 v[156:159], v0 offset:3072
	v_add_u32_e32 v0, s28, v154
	ds_read_b128 v[162:165], v0
	ds_read_b128 v[166:169], v0 offset:1024
	ds_read_b128 v[170:173], v0 offset:2048
	ds_read_b128 v[174:177], v0 offset:3072
	s_add_u32 s20, s44, 0x50000
	s_addc_u32 s21, s45, 0
	s_mov_b32 m0, s53
	v_lshl_add_u64 v[220:221], s[20:21], 0, v[130:131]
	ds_read_b128 v[178:181], v155 offset:32768
	ds_read_b128 v[182:185], v155 offset:33792
	ds_read_b128 v[186:189], v155 offset:34816
	ds_read_b128 v[190:193], v155 offset:35840
	ds_read_b128 v[194:197], v155 offset:36864
	ds_read_b128 v[198:201], v155 offset:37888
	ds_read_b128 v[202:205], v155 offset:38912
	ds_read_b128 v[206:209], v155 offset:39936
	global_load_lds_dwordx4 v[220:221], off
	v_lshl_add_u64 v[220:221], s[20:21], 0, v[134:135]
	s_mov_b32 m0, s54
	s_nop 0
	global_load_lds_dwordx4 v[220:221], off
	s_waitcnt vmcnt(8)
	s_waitcnt lgkmcnt(0)
	s_barrier
	s_setprio 1
	s_waitcnt lgkmcnt(0)
	v_mfma_f32_16x16x32_f16 v[126:129], v[142:145], v[178:181], v[126:129]
	v_mfma_f32_16x16x32_f16 v[122:125], v[150:153], v[178:181], v[122:125]
	v_mfma_f32_16x16x32_f16 v[110:113], v[142:145], v[186:189], v[110:113]
	v_mfma_f32_16x16x32_f16 v[106:109], v[150:153], v[186:189], v[106:109]
	v_mfma_f32_16x16x32_f16 v[94:97], v[142:145], v[194:197], v[94:97]
	v_mfma_f32_16x16x32_f16 v[90:93], v[150:153], v[194:197], v[90:93]
	v_mfma_f32_16x16x32_f16 v[78:81], v[142:145], v[202:205], v[78:81]
	v_mfma_f32_16x16x32_f16 v[74:77], v[150:153], v[202:205], v[74:77]
	v_mfma_f32_16x16x32_f16 v[126:129], v[146:149], v[182:185], v[126:129]
	v_mfma_f32_16x16x32_f16 v[122:125], v[156:159], v[182:185], v[122:125]
	v_mfma_f32_16x16x32_f16 v[110:113], v[146:149], v[190:193], v[110:113]
	v_mfma_f32_16x16x32_f16 v[106:109], v[156:159], v[190:193], v[106:109]
	v_mfma_f32_16x16x32_f16 v[94:97], v[146:149], v[198:201], v[94:97]
	v_mfma_f32_16x16x32_f16 v[90:93], v[156:159], v[198:201], v[90:93]
	v_mfma_f32_16x16x32_f16 v[78:81], v[146:149], v[206:209], v[78:81]
	v_mfma_f32_16x16x32_f16 v[74:77], v[156:159], v[206:209], v[74:77]
	v_mfma_f32_16x16x32_f16 v[118:121], v[162:165], v[178:181], v[118:121]
	v_mfma_f32_16x16x32_f16 v[114:117], v[170:173], v[178:181], v[114:117]
	v_mfma_f32_16x16x32_f16 v[102:105], v[162:165], v[186:189], v[102:105]
	v_mfma_f32_16x16x32_f16 v[98:101], v[170:173], v[186:189], v[98:101]
	v_mfma_f32_16x16x32_f16 v[86:89], v[162:165], v[194:197], v[86:89]
	v_mfma_f32_16x16x32_f16 v[82:85], v[170:173], v[194:197], v[82:85]
	v_mfma_f32_16x16x32_f16 v[70:73], v[162:165], v[202:205], v[70:73]
	v_mfma_f32_16x16x32_f16 v[66:69], v[170:173], v[202:205], v[66:69]
	v_mfma_f32_16x16x32_f16 v[118:121], v[166:169], v[182:185], v[118:121]
	v_mfma_f32_16x16x32_f16 v[114:117], v[174:177], v[182:185], v[114:117]
	v_mfma_f32_16x16x32_f16 v[102:105], v[166:169], v[190:193], v[102:105]
	v_mfma_f32_16x16x32_f16 v[98:101], v[174:177], v[190:193], v[98:101]
	v_mfma_f32_16x16x32_f16 v[86:89], v[166:169], v[198:201], v[86:89]
	v_mfma_f32_16x16x32_f16 v[82:85], v[174:177], v[198:201], v[82:85]
	v_mfma_f32_16x16x32_f16 v[70:73], v[166:169], v[206:209], v[70:73]
	v_mfma_f32_16x16x32_f16 v[66:69], v[174:177], v[206:209], v[66:69]
	s_setprio 0
	s_barrier
; #define PG8_STAGE(bufoff, gbase, voff) do { _Pragma("unroll") for (int _i = 0; _i < 2; ++_i) \
;         __builtin_amdgcn_global_load_lds((const unsigned*)((const char*)(gbase) + (voff)[_i]), (LAS unsigned*)(lds + (bufoff) + ldsw + _i * 8192), 16, 0, 0); } while (0)
; #define PG8_LDA(dst, b, h) do { _Pragma("unroll") for (int m = 0; m < 4; ++m) _Pragma("unroll") for (int k = 0; k < 2; ++k) dst[m][k] = *(const LAS half8*)(lds + PG8_SA(b, h) + aoff + m * 2048 + k * 1024); } while (0)
; #define PG8_MMA(ai, bj, At, Bt) do { __builtin_amdgcn_s_setprio(1); _Pragma("unroll") for (int m = 0; m < 4; ++m) _Pragma("unroll") for (int n = 0; n < 2; ++n) _Pragma("unroll") for (int k = 0; k < 2; ++k) \
;         acc[ai][bj][m][n] = __builtin_amdgcn_mfma_f32_16x16x32_f16(Bt[n][k], At[m][k], acc[ai][bj][m][n], 0, 0, 0); __builtin_amdgcn_s_setprio(0); } while (0)
; #define PG8_WAIT_V(n) asm volatile("s_waitcnt vmcnt(" #n ")" ::: "memory")
; #define PG8_WAIT_L(n) asm volatile("s_waitcnt lgkmcnt(" #n ")" ::: "memory")
; #define PG8_BAR __builtin_amdgcn_s_barrier()
; #define PG8_SCHED __builtin_amdgcn_sched_barrier(0)
; template <class Epi>
; __device__ __forceinline__ void gemm_phase(LAS unsigned char* lds, const Gemm g, const StaticOrder& S, const Epi& E) {
;     ...
;             PG8_LDA(At, 1, 1); PG8_STAGE(PG8_SB(1, 0), b3, voffB); PG8_STAGE(PG8_SB(1, 1), b3 + hB, voffB); PG8_STAGE(PG8_SA(1, 0), a3, voffA);
;             PG8_WAIT_V(8); PG8_WAIT_L(0); PG8_BAR; PG8_MMA(1, 0, At, B0); PG8_MMA(1, 1, At, B1); PG8_BAR; PG8_SCHED;
;         }
	s_add_i32 s20, s27, s50
	v_lshl_add_u64 v[210:211], v[210:211], 0, s[92:93]
	s_mov_b32 m0, s20
	ds_read_b128 v[178:181], v155 offset:49152
	ds_read_b128 v[182:185], v155 offset:50176
	ds_read_b128 v[186:189], v155 offset:51200
	ds_read_b128 v[190:193], v155 offset:52224
	ds_read_b128 v[194:197], v155 offset:53248
	ds_read_b128 v[198:201], v155 offset:54272
	ds_read_b128 v[202:205], v155 offset:55296
	ds_read_b128 v[206:209], v155 offset:56320
	global_load_lds_dwordx4 v[210:211], off
	s_add_i32 m0, s20, 0x2000
	s_add_u32 s20, s24, 0x10080
	v_lshl_add_u64 v[210:211], v[212:213], 0, s[92:93]
	s_addc_u32 s21, s25, 0
	s_add_i32 s24, s28, s50
	global_load_lds_dwordx4 v[210:211], off
	v_lshl_add_u64 v[210:211], s[20:21], 0, v[132:133]
	s_mov_b32 m0, s24
	s_nop 0
	global_load_lds_dwordx4 v[210:211], off
	v_lshl_add_u64 v[210:211], s[20:21], 0, v[136:137]
	s_add_i32 m0, s24, 0x2000
	s_nop 0
	global_load_lds_dwordx4 v[210:211], off
	v_lshl_add_u64 v[210:211], v[214:215], 0, s[92:93]
	s_mov_b32 m0, s55
	s_nop 0
	global_load_lds_dwordx4 v[210:211], off
	v_lshl_add_u64 v[210:211], v[218:219], 0, s[92:93]
	s_mov_b32 m0, s56
	s_nop 0
	global_load_lds_dwordx4 v[210:211], off
	s_waitcnt vmcnt(8)
	s_waitcnt lgkmcnt(0)
	s_barrier
	s_setprio 1
	s_waitcnt lgkmcnt(0)
	v_mfma_f32_16x16x32_f16 v[62:65], v[142:145], v[178:181], v[62:65]
	v_mfma_f32_16x16x32_f16 v[58:61], v[150:153], v[178:181], v[58:61]
	v_mfma_f32_16x16x32_f16 v[46:49], v[142:145], v[186:189], v[46:49]
	v_mfma_f32_16x16x32_f16 v[42:45], v[150:153], v[186:189], v[42:45]
	v_mfma_f32_16x16x32_f16 v[30:33], v[142:145], v[194:197], v[30:33]
	v_mfma_f32_16x16x32_f16 v[26:29], v[150:153], v[194:197], v[26:29]
	v_mfma_f32_16x16x32_f16 v[14:17], v[142:145], v[202:205], v[14:17]
	v_mfma_f32_16x16x32_f16 v[10:13], v[150:153], v[202:205], v[10:13]
	v_mfma_f32_16x16x32_f16 v[62:65], v[146:149], v[182:185], v[62:65]
	v_mfma_f32_16x16x32_f16 v[58:61], v[156:159], v[182:185], v[58:61]
	v_mfma_f32_16x16x32_f16 v[46:49], v[146:149], v[190:193], v[46:49]
	v_mfma_f32_16x16x32_f16 v[42:45], v[156:159], v[190:193], v[42:45]
	v_mfma_f32_16x16x32_f16 v[30:33], v[146:149], v[198:201], v[30:33]
	v_mfma_f32_16x16x32_f16 v[26:29], v[156:159], v[198:201], v[26:29]
	v_mfma_f32_16x16x32_f16 v[14:17], v[146:149], v[206:209], v[14:17]
	v_mfma_f32_16x16x32_f16 v[10:13], v[156:159], v[206:209], v[10:13]
	v_mfma_f32_16x16x32_f16 v[54:57], v[162:165], v[178:181], v[54:57]
	v_mfma_f32_16x16x32_f16 v[50:53], v[170:173], v[178:181], v[50:53]
	v_mfma_f32_16x16x32_f16 v[38:41], v[162:165], v[186:189], v[38:41]
	v_mfma_f32_16x16x32_f16 v[34:37], v[170:173], v[186:189], v[34:37]
	v_mfma_f32_16x16x32_f16 v[22:25], v[162:165], v[194:197], v[22:25]
	v_mfma_f32_16x16x32_f16 v[18:21], v[170:173], v[194:197], v[18:21]
	v_mfma_f32_16x16x32_f16 v[6:9], v[162:165], v[202:205], v[6:9]
	v_mfma_f32_16x16x32_f16 v[2:5], v[170:173], v[202:205], v[2:5]
	v_mfma_f32_16x16x32_f16 v[54:57], v[166:169], v[182:185], v[54:57]
	v_mfma_f32_16x16x32_f16 v[50:53], v[174:177], v[182:185], v[50:53]
	v_mfma_f32_16x16x32_f16 v[38:41], v[166:169], v[190:193], v[38:41]
	v_mfma_f32_16x16x32_f16 v[34:37], v[174:177], v[190:193], v[34:37]
	v_mfma_f32_16x16x32_f16 v[22:25], v[166:169], v[198:201], v[22:25]
	v_mfma_f32_16x16x32_f16 v[18:21], v[174:177], v[198:201], v[18:21]
	v_mfma_f32_16x16x32_f16 v[6:9], v[166:169], v[206:209], v[6:9]
	v_mfma_f32_16x16x32_f16 v[2:5], v[174:177], v[206:209], v[2:5]
	s_setprio 0
	s_barrier
	s_add_u32 s15, s15, 0x100
	s_addc_u32 s22, s22, 0
	s_cmp_ge_i32 s26, s23
	s_mov_b64 s[20:21], s[0:1]
	s_mov_b32 s24, s26
	s_cbranch_scc0 .LBB0_659
	s_branch .LBB0_661

; #define PG8_STAGE(bufoff, gbase, voff) do { _Pragma("unroll") for (int _i = 0; _i < 2; ++_i) \
;         __builtin_amdgcn_global_load_lds((const unsigned*)((const char*)(gbase) + (voff)[_i]), (LAS unsigned*)(lds + (bufoff) + ldsw + _i * 8192), 16, 0, 0); } while (0)
; #define PG8_LDA(dst, b, h) do { _Pragma("unroll") for (int m = 0; m < 4; ++m) _Pragma("unroll") for (int k = 0; k < 2; ++k) dst[m][k] = *(const LAS half8*)(lds + PG8_SA(b, h) + aoff + m * 2048 + k * 1024); } while (0)
; #define PG8_LDB(dst, b, h) do { _Pragma("unroll") for (int n = 0; n < 2; ++n) _Pragma("unroll") for (int k = 0; k < 2; ++k) dst[n][k] = *(const LAS half8*)(lds + PG8_SB(b, h) + boff + n * 2048 + k * 1024); } while (0)
; #define PG8_MMA(ai, bj, At, Bt) do { __builtin_amdgcn_s_setprio(1); _Pragma("unroll") for (int m = 0; m < 4; ++m) _Pragma("unroll") for (int n = 0; n < 2; ++n) _Pragma("unroll") for (int k = 0; k < 2; ++k) \
;         acc[ai][bj][m][n] = __builtin_amdgcn_mfma_f32_16x16x32_f16(Bt[n][k], At[m][k], acc[ai][bj][m][n], 0, 0, 0); __builtin_amdgcn_s_setprio(0); } while (0)
; #define PG8_WAIT_V(n) asm volatile("s_waitcnt vmcnt(" #n ")" ::: "memory")
; #define PG8_WAIT_L(n) asm volatile("s_waitcnt lgkmcnt(" #n ")" ::: "memory")
; #define PG8_BAR __builtin_amdgcn_s_barrier()
; #define PG8_SCHED __builtin_amdgcn_sched_barrier(0)
; template <class Epi>
; __device__ __forceinline__ void gemm_phase(LAS unsigned char* lds, const Gemm g, const StaticOrder& S, const Epi& E) {
;     ...
;         for (int t = 0; t < nt; t += 2) {
;             const bool last = (t == nt - 2);
;             const char* a1 = cA + (size_t)(t + 1) * kstep;
;             const char* a2 = last ? nA : cA + (size_t)(t + 2) * kstep; const char* b2 = last ? nB : cB + (size_t)(t + 2) * kstep;
;             const char* a3 = a2 + kstep; const char* b3 = b2 + kstep;
;             PG8_LDB(B0, 0, 0); PG8_LDB(B1, 0, 1); PG8_SCHED; PG8_LDA(At, 0, 0); PG8_STAGE(PG8_SA(1, 1), a1 + hA, voffA);
;             PG8_WAIT_V(8); PG8_WAIT_L(0); PG8_BAR; PG8_MMA(0, 0, At, B0); PG8_MMA(0, 1, At, B1); PG8_BAR; PG8_SCHED;
;             PG8_LDA(At, 0, 1); PG8_STAGE(PG8_SB(0, 0), b2, voffB); PG8_STAGE(PG8_SB(0, 1), b2 + hB, voffB); PG8_STAGE(PG8_SA(0, 0), a2, voffA);
;             PG8_WAIT_V(8); PG8_WAIT_L(0); PG8_BAR; PG8_MMA(1, 0, At, B0); PG8_MMA(1, 1, At, B1); PG8_BAR; PG8_SCHED;
.LBB0_882:
	s_add_i32 s27, s26, 2
	s_add_u32 s28, s24, 0xfffc0080
	s_addc_u32 s29, s25, -1
	s_add_i32 s30, 0, 0x10000
	s_cmp_eq_u32 s51, s26
	s_cselect_b32 s41, s2, s29
	s_cselect_b32 s40, s3, s28
	v_add_u32_e32 v140, s30, v142
	s_cselect_b32 s35, s11, s22
	s_cselect_b32 s34, s13, s19
	s_add_i32 s26, 0, 0x14000
	ds_read_b128 v[144:147], v140
	ds_read_b128 v[148:151], v140 offset:1024
	ds_read_b128 v[152:155], v140 offset:2048
	ds_read_b128 v[156:159], v140 offset:3072
	v_add_u32_e32 v140, s26, v142
	ds_read_b128 v[162:165], v140
	ds_read_b128 v[166:169], v140 offset:1024
	ds_read_b128 v[170:173], v140 offset:2048
	ds_read_b128 v[174:177], v140 offset:3072
	v_lshl_add_u64 v[140:141], s[24:25], 0, v[138:139]
	s_add_i32 m0, s21, 0xc000
	ds_read_b128 v[178:181], v143
	ds_read_b128 v[182:185], v143 offset:1024
	ds_read_b128 v[186:189], v143 offset:2048
	ds_read_b128 v[190:193], v143 offset:3072
	ds_read_b128 v[194:197], v143 offset:4096
	ds_read_b128 v[198:201], v143 offset:5120
	ds_read_b128 v[202:205], v143 offset:6144
	ds_read_b128 v[206:209], v143 offset:7168
	global_load_lds_dwordx4 v[140:141], off
	v_lshl_add_u64 v[140:141], s[24:25], 0, v[136:137]
	s_add_i32 m0, s21, 0xe000
	s_nop 0
	global_load_lds_dwordx4 v[140:141], off
	s_waitcnt vmcnt(8)
	s_waitcnt lgkmcnt(0)
	s_barrier
	s_setprio 1
	s_waitcnt lgkmcnt(0)
	v_mfma_f32_16x16x32_f16 v[126:129], v[144:147], v[178:181], v[126:129]
	v_mfma_f32_16x16x32_f16 v[122:125], v[152:155], v[178:181], v[122:125]
	v_mfma_f32_16x16x32_f16 v[110:113], v[144:147], v[186:189], v[110:113]
	v_mfma_f32_16x16x32_f16 v[106:109], v[152:155], v[186:189], v[106:109]
	v_mfma_f32_16x16x32_f16 v[94:97], v[144:147], v[194:197], v[94:97]
	v_mfma_f32_16x16x32_f16 v[90:93], v[152:155], v[194:197], v[90:93]
	v_mfma_f32_16x16x32_f16 v[78:81], v[144:147], v[202:205], v[78:81]
	v_mfma_f32_16x16x32_f16 v[74:77], v[152:155], v[202:205], v[74:77]
	v_mfma_f32_16x16x32_f16 v[126:129], v[148:151], v[182:185], v[126:129]
	v_mfma_f32_16x16x32_f16 v[122:125], v[156:159], v[182:185], v[122:125]
	v_mfma_f32_16x16x32_f16 v[110:113], v[148:151], v[190:193], v[110:113]
	v_mfma_f32_16x16x32_f16 v[106:109], v[156:159], v[190:193], v[106:109]
	v_mfma_f32_16x16x32_f16 v[94:97], v[148:151], v[198:201], v[94:97]
	v_mfma_f32_16x16x32_f16 v[90:93], v[156:159], v[198:201], v[90:93]
	v_mfma_f32_16x16x32_f16 v[78:81], v[148:151], v[206:209], v[78:81]
	v_mfma_f32_16x16x32_f16 v[74:77], v[156:159], v[206:209], v[74:77]
	v_mfma_f32_16x16x32_f16 v[118:121], v[162:165], v[178:181], v[118:121]
	v_mfma_f32_16x16x32_f16 v[114:117], v[170:173], v[178:181], v[114:117]
	v_mfma_f32_16x16x32_f16 v[102:105], v[162:165], v[186:189], v[102:105]
	v_mfma_f32_16x16x32_f16 v[98:101], v[170:173], v[186:189], v[98:101]
	v_mfma_f32_16x16x32_f16 v[86:89], v[162:165], v[194:197], v[86:89]
	v_mfma_f32_16x16x32_f16 v[82:85], v[170:173], v[194:197], v[82:85]
	v_mfma_f32_16x16x32_f16 v[70:73], v[162:165], v[202:205], v[70:73]
	v_mfma_f32_16x16x32_f16 v[66:69], v[170:173], v[202:205], v[66:69]
	v_mfma_f32_16x16x32_f16 v[118:121], v[166:169], v[182:185], v[118:121]
	v_mfma_f32_16x16x32_f16 v[114:117], v[174:177], v[182:185], v[114:117]
	v_mfma_f32_16x16x32_f16 v[102:105], v[166:169], v[190:193], v[102:105]
	v_mfma_f32_16x16x32_f16 v[98:101], v[174:177], v[190:193], v[98:101]
	v_mfma_f32_16x16x32_f16 v[86:89], v[166:169], v[198:201], v[86:89]
	v_mfma_f32_16x16x32_f16 v[82:85], v[174:177], v[198:201], v[82:85]
	v_mfma_f32_16x16x32_f16 v[70:73], v[166:169], v[206:209], v[70:73]
	v_mfma_f32_16x16x32_f16 v[66:69], v[174:177], v[206:209], v[66:69]
	s_setprio 0
	s_barrier
	s_add_i32 s28, s30, s42
	v_lshl_add_u64 v[140:141], s[34:35], 0, v[0:1]
	s_mov_b32 m0, s28
	ds_read_b128 v[178:181], v143 offset:16384
	ds_read_b128 v[182:185], v143 offset:17408
	ds_read_b128 v[186:189], v143 offset:18432
	ds_read_b128 v[190:193], v143 offset:19456
	ds_read_b128 v[194:197], v143 offset:20480
	ds_read_b128 v[198:201], v143 offset:21504
	ds_read_b128 v[202:205], v143 offset:22528
	ds_read_b128 v[206:209], v143 offset:23552
	global_load_lds_dwordx4 v[140:141], off
	s_add_i32 m0, s28, 0x2000
	s_add_u32 s28, s34, 0x40000
	v_lshl_add_u64 v[210:211], s[34:35], 0, v[134:135]
	s_addc_u32 s29, s35, 0
	s_add_i32 s26, s26, s42
	global_load_lds_dwordx4 v[210:211], off
	v_lshl_add_u64 v[212:213], s[28:29], 0, v[0:1]
	s_mov_b32 m0, s26
	v_lshl_add_u64 v[214:215], s[40:41], 0, v[132:133]
	global_load_lds_dwordx4 v[212:213], off
	v_lshl_add_u64 v[212:213], s[28:29], 0, v[134:135]
	s_add_i32 m0, s26, 0x2000
	s_nop 0
	global_load_lds_dwordx4 v[212:213], off
	v_lshl_add_u64 v[212:213], s[40:41], 0, v[130:131]
	s_mov_b32 m0, s21
	s_nop 0
	global_load_lds_dwordx4 v[212:213], off
	s_mov_b32 m0, s43
	s_nop 0
	global_load_lds_dwordx4 v[214:215], off
	s_waitcnt vmcnt(8)
	s_waitcnt lgkmcnt(0)
	s_barrier
; #define PG8_STAGE(bufoff, gbase, voff) do { _Pragma("unroll") for (int _i = 0; _i < 2; ++_i) \
;         __builtin_amdgcn_global_load_lds((const unsigned*)((const char*)(gbase) + (voff)[_i]), (LAS unsigned*)(lds + (bufoff) + ldsw + _i * 8192), 16, 0, 0); } while (0)
; #define PG8_LDA(dst, b, h) do { _Pragma("unroll") for (int m = 0; m < 4; ++m) _Pragma("unroll") for (int k = 0; k < 2; ++k) dst[m][k] = *(const LAS half8*)(lds + PG8_SA(b, h) + aoff + m * 2048 + k * 1024); } while (0)
; #define PG8_LDB(dst, b, h) do { _Pragma("unroll") for (int n = 0; n < 2; ++n) _Pragma("unroll") for (int k = 0; k < 2; ++k) dst[n][k] = *(const LAS half8*)(lds + PG8_SB(b, h) + boff + n * 2048 + k * 1024); } while (0)
; #define PG8_MMA(ai, bj, At, Bt) do { __builtin_amdgcn_s_setprio(1); _Pragma("unroll") for (int m = 0; m < 4; ++m) _Pragma("unroll") for (int n = 0; n < 2; ++n) _Pragma("unroll") for (int k = 0; k < 2; ++k) \
;         acc[ai][bj][m][n] = __builtin_amdgcn_mfma_f32_16x16x32_f16(Bt[n][k], At[m][k], acc[ai][bj][m][n], 0, 0, 0); __builtin_amdgcn_s_setprio(0); } while (0)
; #define PG8_WAIT_V(n) asm volatile("s_waitcnt vmcnt(" #n ")" ::: "memory")
; #define PG8_WAIT_L(n) asm volatile("s_waitcnt lgkmcnt(" #n ")" ::: "memory")
; #define PG8_BAR __builtin_amdgcn_s_barrier()
; #define PG8_SCHED __builtin_amdgcn_sched_barrier(0)
; template <class Epi>
; __device__ __forceinline__ void gemm_phase(LAS unsigned char* lds, const Gemm g, const StaticOrder& S, const Epi& E) {
;     ...
;             PG8_WAIT_V(8); PG8_WAIT_L(0); PG8_BAR; PG8_MMA(1, 0, At, B0); PG8_MMA(1, 1, At, B1); PG8_BAR; PG8_SCHED;
;             PG8_LDB(B0, 1, 0); PG8_LDB(B1, 1, 1); PG8_SCHED; PG8_LDA(At, 1, 0); PG8_STAGE(PG8_SA(0, 1), a2 + hA, voffA);
;             PG8_WAIT_V(8); PG8_WAIT_L(0); PG8_BAR; PG8_MMA(0, 0, At, B0); PG8_MMA(0, 1, At, B1); PG8_BAR; PG8_SCHED;
	s_setprio 1
	s_waitcnt lgkmcnt(0)
	v_mfma_f32_16x16x32_f16 v[62:65], v[144:147], v[178:181], v[62:65]
	v_mfma_f32_16x16x32_f16 v[58:61], v[152:155], v[178:181], v[58:61]
	v_mfma_f32_16x16x32_f16 v[46:49], v[144:147], v[186:189], v[46:49]
	v_mfma_f32_16x16x32_f16 v[42:45], v[152:155], v[186:189], v[42:45]
	v_mfma_f32_16x16x32_f16 v[30:33], v[144:147], v[194:197], v[30:33]
	v_mfma_f32_16x16x32_f16 v[26:29], v[152:155], v[194:197], v[26:29]
	v_mfma_f32_16x16x32_f16 v[14:17], v[144:147], v[202:205], v[14:17]
	v_mfma_f32_16x16x32_f16 v[10:13], v[152:155], v[202:205], v[10:13]
	v_mfma_f32_16x16x32_f16 v[62:65], v[148:151], v[182:185], v[62:65]
	v_mfma_f32_16x16x32_f16 v[58:61], v[156:159], v[182:185], v[58:61]
	v_mfma_f32_16x16x32_f16 v[46:49], v[148:151], v[190:193], v[46:49]
	v_mfma_f32_16x16x32_f16 v[42:45], v[156:159], v[190:193], v[42:45]
	v_mfma_f32_16x16x32_f16 v[30:33], v[148:151], v[198:201], v[30:33]
	v_mfma_f32_16x16x32_f16 v[26:29], v[156:159], v[198:201], v[26:29]
	v_mfma_f32_16x16x32_f16 v[14:17], v[148:151], v[206:209], v[14:17]
	v_mfma_f32_16x16x32_f16 v[10:13], v[156:159], v[206:209], v[10:13]
	v_mfma_f32_16x16x32_f16 v[54:57], v[162:165], v[178:181], v[54:57]
	v_mfma_f32_16x16x32_f16 v[50:53], v[170:173], v[178:181], v[50:53]
	v_mfma_f32_16x16x32_f16 v[38:41], v[162:165], v[186:189], v[38:41]
	v_mfma_f32_16x16x32_f16 v[34:37], v[170:173], v[186:189], v[34:37]
	v_mfma_f32_16x16x32_f16 v[22:25], v[162:165], v[194:197], v[22:25]
	v_mfma_f32_16x16x32_f16 v[18:21], v[170:173], v[194:197], v[18:21]
	v_mfma_f32_16x16x32_f16 v[6:9], v[162:165], v[202:205], v[6:9]
	v_mfma_f32_16x16x32_f16 v[2:5], v[170:173], v[202:205], v[2:5]
	v_mfma_f32_16x16x32_f16 v[54:57], v[166:169], v[182:185], v[54:57]
	v_mfma_f32_16x16x32_f16 v[50:53], v[174:177], v[182:185], v[50:53]
	v_mfma_f32_16x16x32_f16 v[38:41], v[166:169], v[190:193], v[38:41]
	v_mfma_f32_16x16x32_f16 v[34:37], v[174:177], v[190:193], v[34:37]
	v_mfma_f32_16x16x32_f16 v[22:25], v[166:169], v[198:201], v[22:25]
	v_mfma_f32_16x16x32_f16 v[18:21], v[174:177], v[198:201], v[18:21]
	v_mfma_f32_16x16x32_f16 v[6:9], v[166:169], v[206:209], v[6:9]
	v_mfma_f32_16x16x32_f16 v[2:5], v[174:177], v[206:209], v[2:5]
	s_setprio 0
	s_barrier
	s_add_i32 s26, 0, 0x18000
	s_add_i32 s30, 0, 0x1c000
	v_add_u32_e32 v156, s26, v142
	v_add_u32_e32 v161, s30, v142
	ds_read_b128 v[144:147], v156
	ds_read_b128 v[148:151], v156 offset:1024
	ds_read_b128 v[152:155], v156 offset:2048
	ds_read_b128 v[156:159], v156 offset:3072
	ds_read_b128 v[162:165], v161
	ds_read_b128 v[166:169], v161 offset:1024
	ds_read_b128 v[170:173], v161 offset:2048
	ds_read_b128 v[174:177], v161 offset:3072
	s_add_u32 s28, s40, 0x40000
	s_addc_u32 s29, s41, 0
	s_mov_b32 m0, s44
	v_lshl_add_u64 v[218:219], s[28:29], 0, v[130:131]
	ds_read_b128 v[178:181], v143 offset:32768
	ds_read_b128 v[182:185], v143 offset:33792
	ds_read_b128 v[186:189], v143 offset:34816
	ds_read_b128 v[190:193], v143 offset:35840
	ds_read_b128 v[194:197], v143 offset:36864
	ds_read_b128 v[198:201], v143 offset:37888
	ds_read_b128 v[202:205], v143 offset:38912
	ds_read_b128 v[206:209], v143 offset:39936
	global_load_lds_dwordx4 v[218:219], off
	v_lshl_add_u64 v[218:219], s[28:29], 0, v[132:133]
	s_mov_b32 m0, s45
	s_nop 0
	global_load_lds_dwordx4 v[218:219], off
	s_waitcnt vmcnt(8)
	s_waitcnt lgkmcnt(0)
	s_barrier
	s_setprio 1
	s_waitcnt lgkmcnt(0)
	v_mfma_f32_16x16x32_f16 v[126:129], v[144:147], v[178:181], v[126:129]
	v_mfma_f32_16x16x32_f16 v[122:125], v[152:155], v[178:181], v[122:125]
	v_mfma_f32_16x16x32_f16 v[110:113], v[144:147], v[186:189], v[110:113]
	v_mfma_f32_16x16x32_f16 v[106:109], v[152:155], v[186:189], v[106:109]
	v_mfma_f32_16x16x32_f16 v[94:97], v[144:147], v[194:197], v[94:97]
	v_mfma_f32_16x16x32_f16 v[90:93], v[152:155], v[194:197], v[90:93]
	v_mfma_f32_16x16x32_f16 v[78:81], v[144:147], v[202:205], v[78:81]
	v_mfma_f32_16x16x32_f16 v[74:77], v[152:155], v[202:205], v[74:77]
	v_mfma_f32_16x16x32_f16 v[126:129], v[148:151], v[182:185], v[126:129]
	v_mfma_f32_16x16x32_f16 v[122:125], v[156:159], v[182:185], v[122:125]
	v_mfma_f32_16x16x32_f16 v[110:113], v[148:151], v[190:193], v[110:113]
	v_mfma_f32_16x16x32_f16 v[106:109], v[156:159], v[190:193], v[106:109]
	v_mfma_f32_16x16x32_f16 v[94:97], v[148:151], v[198:201], v[94:97]
	v_mfma_f32_16x16x32_f16 v[90:93], v[156:159], v[198:201], v[90:93]
	v_mfma_f32_16x16x32_f16 v[78:81], v[148:151], v[206:209], v[78:81]
	v_mfma_f32_16x16x32_f16 v[74:77], v[156:159], v[206:209], v[74:77]
	v_mfma_f32_16x16x32_f16 v[118:121], v[162:165], v[178:181], v[118:121]
	v_mfma_f32_16x16x32_f16 v[114:117], v[170:173], v[178:181], v[114:117]
	v_mfma_f32_16x16x32_f16 v[102:105], v[162:165], v[186:189], v[102:105]
	v_mfma_f32_16x16x32_f16 v[98:101], v[170:173], v[186:189], v[98:101]
	v_mfma_f32_16x16x32_f16 v[86:89], v[162:165], v[194:197], v[86:89]
	v_mfma_f32_16x16x32_f16 v[82:85], v[170:173], v[194:197], v[82:85]
	v_mfma_f32_16x16x32_f16 v[70:73], v[162:165], v[202:205], v[70:73]
	v_mfma_f32_16x16x32_f16 v[66:69], v[170:173], v[202:205], v[66:69]
	v_mfma_f32_16x16x32_f16 v[118:121], v[166:169], v[182:185], v[118:121]
	v_mfma_f32_16x16x32_f16 v[114:117], v[174:177], v[182:185], v[114:117]
	v_mfma_f32_16x16x32_f16 v[102:105], v[166:169], v[190:193], v[102:105]
	v_mfma_f32_16x16x32_f16 v[98:101], v[174:177], v[190:193], v[98:101]
	v_mfma_f32_16x16x32_f16 v[86:89], v[166:169], v[198:201], v[86:89]
	v_mfma_f32_16x16x32_f16 v[82:85], v[174:177], v[198:201], v[82:85]
	v_mfma_f32_16x16x32_f16 v[70:73], v[166:169], v[206:209], v[70:73]
	v_mfma_f32_16x16x32_f16 v[66:69], v[174:177], v[206:209], v[66:69]
	s_setprio 0
	s_barrier
; #define PG8_STAGE(bufoff, gbase, voff) do { _Pragma("unroll") for (int _i = 0; _i < 2; ++_i) \
;         __builtin_amdgcn_global_load_lds((const unsigned*)((const char*)(gbase) + (voff)[_i]), (LAS unsigned*)(lds + (bufoff) + ldsw + _i * 8192), 16, 0, 0); } while (0)
; #define PG8_LDA(dst, b, h) do { _Pragma("unroll") for (int m = 0; m < 4; ++m) _Pragma("unroll") for (int k = 0; k < 2; ++k) dst[m][k] = *(const LAS half8*)(lds + PG8_SA(b, h) + aoff + m * 2048 + k * 1024); } while (0)
; #define PG8_MMA(ai, bj, At, Bt) do { __builtin_amdgcn_s_setprio(1); _Pragma("unroll") for (int m = 0; m < 4; ++m) _Pragma("unroll") for (int n = 0; n < 2; ++n) _Pragma("unroll") for (int k = 0; k < 2; ++k) \
;         acc[ai][bj][m][n] = __builtin_amdgcn_mfma_f32_16x16x32_f16(Bt[n][k], At[m][k], acc[ai][bj][m][n], 0, 0, 0); __builtin_amdgcn_s_setprio(0); } while (0)
; #define PG8_WAIT_V(n) asm volatile("s_waitcnt vmcnt(" #n ")" ::: "memory")
; #define PG8_WAIT_L(n) asm volatile("s_waitcnt lgkmcnt(" #n ")" ::: "memory")
; #define PG8_BAR __builtin_amdgcn_s_barrier()
; #define PG8_SCHED __builtin_amdgcn_sched_barrier(0)
; template <class Epi>
; __device__ __forceinline__ void gemm_phase(LAS unsigned char* lds, const Gemm g, const StaticOrder& S, const Epi& E) {
;     ...
;             PG8_LDA(At, 1, 1); PG8_STAGE(PG8_SB(1, 0), b3, voffB); PG8_STAGE(PG8_SB(1, 1), b3 + hB, voffB); PG8_STAGE(PG8_SA(1, 0), a3, voffA);
;             PG8_WAIT_V(8); PG8_WAIT_L(0); PG8_BAR; PG8_MMA(1, 0, At, B0); PG8_MMA(1, 1, At, B1); PG8_BAR; PG8_SCHED;
;         }
	s_add_i32 s26, s26, s42
	v_lshl_add_u64 v[140:141], v[140:141], 0, s[92:93]
	s_mov_b32 m0, s26
	ds_read_b128 v[178:181], v143 offset:49152
	ds_read_b128 v[182:185], v143 offset:50176
	ds_read_b128 v[186:189], v143 offset:51200
	ds_read_b128 v[190:193], v143 offset:52224
	ds_read_b128 v[194:197], v143 offset:53248
	ds_read_b128 v[198:201], v143 offset:54272
	ds_read_b128 v[202:205], v143 offset:55296
	ds_read_b128 v[206:209], v143 offset:56320
	global_load_lds_dwordx4 v[140:141], off
	s_add_i32 m0, s26, 0x2000
	s_add_u32 s28, s34, 0x40080
	v_lshl_add_u64 v[140:141], v[210:211], 0, s[92:93]
	s_addc_u32 s29, s35, 0
	s_add_i32 s26, s30, s42
	global_load_lds_dwordx4 v[140:141], off
	v_lshl_add_u64 v[140:141], s[28:29], 0, v[0:1]
	s_mov_b32 m0, s26
	s_nop 0
	global_load_lds_dwordx4 v[140:141], off
	v_lshl_add_u64 v[140:141], s[28:29], 0, v[134:135]
	s_add_i32 m0, s26, 0x2000
	s_nop 0
	global_load_lds_dwordx4 v[140:141], off
	v_lshl_add_u64 v[140:141], v[212:213], 0, s[92:93]
	s_mov_b32 m0, s46
	s_nop 0
	global_load_lds_dwordx4 v[140:141], off
	v_lshl_add_u64 v[140:141], v[214:215], 0, s[92:93]
	s_mov_b32 m0, s47
	s_nop 0
	global_load_lds_dwordx4 v[140:141], off
	s_waitcnt vmcnt(8)
	s_waitcnt lgkmcnt(0)
	s_barrier
	s_setprio 1
	s_waitcnt lgkmcnt(0)
	v_mfma_f32_16x16x32_f16 v[62:65], v[144:147], v[178:181], v[62:65]
	v_mfma_f32_16x16x32_f16 v[58:61], v[152:155], v[178:181], v[58:61]
	v_mfma_f32_16x16x32_f16 v[46:49], v[144:147], v[186:189], v[46:49]
	v_mfma_f32_16x16x32_f16 v[42:45], v[152:155], v[186:189], v[42:45]
	v_mfma_f32_16x16x32_f16 v[30:33], v[144:147], v[194:197], v[30:33]
	v_mfma_f32_16x16x32_f16 v[26:29], v[152:155], v[194:197], v[26:29]
	v_mfma_f32_16x16x32_f16 v[14:17], v[144:147], v[202:205], v[14:17]
	v_mfma_f32_16x16x32_f16 v[10:13], v[152:155], v[202:205], v[10:13]
	v_mfma_f32_16x16x32_f16 v[62:65], v[148:151], v[182:185], v[62:65]
	v_mfma_f32_16x16x32_f16 v[58:61], v[156:159], v[182:185], v[58:61]
	v_mfma_f32_16x16x32_f16 v[46:49], v[148:151], v[190:193], v[46:49]
	v_mfma_f32_16x16x32_f16 v[42:45], v[156:159], v[190:193], v[42:45]
	v_mfma_f32_16x16x32_f16 v[30:33], v[148:151], v[198:201], v[30:33]
	v_mfma_f32_16x16x32_f16 v[26:29], v[156:159], v[198:201], v[26:29]
	v_mfma_f32_16x16x32_f16 v[14:17], v[148:151], v[206:209], v[14:17]
	v_mfma_f32_16x16x32_f16 v[10:13], v[156:159], v[206:209], v[10:13]
	v_mfma_f32_16x16x32_f16 v[54:57], v[162:165], v[178:181], v[54:57]
	v_mfma_f32_16x16x32_f16 v[50:53], v[170:173], v[178:181], v[50:53]
	v_mfma_f32_16x16x32_f16 v[38:41], v[162:165], v[186:189], v[38:41]
	v_mfma_f32_16x16x32_f16 v[34:37], v[170:173], v[186:189], v[34:37]
	v_mfma_f32_16x16x32_f16 v[22:25], v[162:165], v[194:197], v[22:25]
	v_mfma_f32_16x16x32_f16 v[18:21], v[170:173], v[194:197], v[18:21]
	v_mfma_f32_16x16x32_f16 v[6:9], v[162:165], v[202:205], v[6:9]
	v_mfma_f32_16x16x32_f16 v[2:5], v[170:173], v[202:205], v[2:5]
	v_mfma_f32_16x16x32_f16 v[54:57], v[166:169], v[182:185], v[54:57]
	v_mfma_f32_16x16x32_f16 v[50:53], v[174:177], v[182:185], v[50:53]
	v_mfma_f32_16x16x32_f16 v[38:41], v[166:169], v[190:193], v[38:41]
	v_mfma_f32_16x16x32_f16 v[34:37], v[174:177], v[190:193], v[34:37]
	v_mfma_f32_16x16x32_f16 v[22:25], v[166:169], v[198:201], v[22:25]
	v_mfma_f32_16x16x32_f16 v[18:21], v[174:177], v[198:201], v[18:21]
	v_mfma_f32_16x16x32_f16 v[6:9], v[166:169], v[206:209], v[6:9]
	v_mfma_f32_16x16x32_f16 v[2:5], v[174:177], v[206:209], v[2:5]
	s_setprio 0
	s_barrier
	s_add_u32 s19, s19, 0x100
	s_addc_u32 s22, s22, 0
	s_add_u32 s24, s24, 0x100
	s_addc_u32 s25, s25, 0
	s_cmp_ge_i32 s27, s23
	s_mov_b32 s26, s27
	s_cbranch_scc0 .LBB0_882
	v_readlane_b32 s26, v255, 0
	v_readlane_b32 s27, v255, 1
	s_and_b64 vcc, exec, s[8:9]
	s_cbranch_vccz .LBB0_885
